# hoist K/V LDS fragment reads in attention tiles; hand-scheduled SwiGLU epilogues (P1,P11, rs loads hoisted); loop-invariant gain reloads + redundant vmcnt(0) removed in residual/norm phases P3,P10,P13
# speedup vs baseline: 1.0630x; 1.0630x over previous
; __device__ __forceinline__ unsigned cvt_pk_bf16(float lo, float hi) { unsigned r; asm volatile("v_cvt_pk_bf16_f32 %0, %1, %2" : "=v"(r) : "v"(lo), "v"(hi)); return r; }
;     __device__ __forceinline__ void operator()(const f32x4 (&acc)[2][2][4][2], const Unit& u, int wr, int wc, int fr, int fq) const {
;         const int row0 = u.pm * BM + wr * 64 + fr, col0 = u.pn * 128 + wc * 32 + 8 * fq;
; #pragma unroll
;         for (int ai = 0; ai < 2; ++ai)
; #pragma unroll
;             for (int m = 0; m < 4; ++m) {
;                 bf16_t* p = O + (size_t)(row0 + ai * HALF + m * 16) * ldc + col0;
;                 float h[8]; const float rsc = rs ? rs[row0 + ai * HALF + m * 16] : 1.0f;
; #pragma unroll
;                 for (int n = 0; n < 2; ++n)
; #pragma unroll
;                     for (int i = 0; i < 4; ++i) { const float g = acc[ai][0][m][n][i] * rsc, uu = acc[ai][1][m][n][i] * rsc; h[4 * n + i] = g * __builtin_amdgcn_rcpf(1.0f + __builtin_amdgcn_exp2f(g)) * uu; }
;                 u32x4 w; w.x = cvt_pk_bf16(h[0], h[1]); w.y = cvt_pk_bf16(h[2], h[3]); w.z = cvt_pk_bf16(h[4], h[5]); w.w = cvt_pk_bf16(h[6], h[7]);
;                 *(u32x4*)p = w;
;             }
.LBB0_296:
	s_mov_b32 s98, 0x16000
	s_mov_b32 s99, 0
	s_mov_b32 s100, 0x6e000
	s_mov_b32 s101, 0
	v_readlane_b32 s24, v253, 47
	v_lshl_or_b32 v146, s45, 7, v150
	v_readlane_b32 s25, v253, 48
	v_lshl_add_u32 v154, s22, 8, v148
	v_ashrrev_i32_e32 v147, 31, v146
	v_mov_b32_e32 v176, 1.0
	v_mov_b64_e32 v[144:145], s[24:25]
	v_mad_i64_i32 v[198:199], s[24:25], v154, s44, v[144:145]
	v_lshlrev_b64 v[146:147], 1, v[146:147]
	v_exp_f32_e32 v160, v124
	v_exp_f32_e32 v161, v125
	v_exp_f32_e32 v162, v126
	v_exp_f32_e32 v163, v127
	v_lshl_add_u64 v[198:199], v[198:199], 0, v[146:147]
	v_exp_f32_e32 v164, v120
	v_exp_f32_e32 v165, v121
	v_exp_f32_e32 v166, v122
	v_exp_f32_e32 v167, v123
	v_exp_f32_e32 v168, v108
	v_exp_f32_e32 v169, v109
	v_exp_f32_e32 v170, v110
	v_exp_f32_e32 v171, v111
	v_exp_f32_e32 v172, v104
	v_exp_f32_e32 v173, v105
	v_exp_f32_e32 v174, v106
	v_exp_f32_e32 v175, v107
	v_pk_add_f32 v[160:161], v[160:161], v[176:177] op_sel_hi:[1,0]
	v_pk_add_f32 v[162:163], v[162:163], v[176:177] op_sel_hi:[1,0]
	v_pk_add_f32 v[164:165], v[164:165], v[176:177] op_sel_hi:[1,0]
	v_pk_add_f32 v[166:167], v[166:167], v[176:177] op_sel_hi:[1,0]
	v_pk_add_f32 v[168:169], v[168:169], v[176:177] op_sel_hi:[1,0]
	v_pk_add_f32 v[170:171], v[170:171], v[176:177] op_sel_hi:[1,0]
	v_pk_add_f32 v[172:173], v[172:173], v[176:177] op_sel_hi:[1,0]
	v_pk_add_f32 v[174:175], v[174:175], v[176:177] op_sel_hi:[1,0]
	v_rcp_f32_e32 v160, v160
	v_lshl_add_u64 v[200:201], v[198:199], 0, s[98:99]
	v_rcp_f32_e32 v161, v161
	v_lshl_add_u64 v[202:203], v[200:201], 0, s[98:99]
	v_rcp_f32_e32 v162, v162
	v_lshl_add_u64 v[204:205], v[202:203], 0, s[98:99]
	v_rcp_f32_e32 v163, v163
	v_lshl_add_u64 v[206:207], v[204:205], 0, s[100:101]
	v_rcp_f32_e32 v164, v164
	v_lshl_add_u64 v[208:209], v[206:207], 0, s[98:99]
	v_rcp_f32_e32 v165, v165
	v_lshl_add_u64 v[210:211], v[208:209], 0, s[98:99]
	v_rcp_f32_e32 v166, v166
	v_lshl_add_u64 v[212:213], v[210:211], 0, s[98:99]
	v_rcp_f32_e32 v167, v167
	v_rcp_f32_e32 v168, v168
	v_rcp_f32_e32 v169, v169
	v_rcp_f32_e32 v170, v170
	v_rcp_f32_e32 v171, v171
	v_rcp_f32_e32 v172, v172
	v_rcp_f32_e32 v173, v173
	v_rcp_f32_e32 v174, v174
	v_rcp_f32_e32 v175, v175
	v_pk_mul_f32 v[124:125], v[124:125], v[160:161]
	v_exp_f32_e32 v160, v92
	v_pk_mul_f32 v[126:127], v[126:127], v[162:163]
	v_exp_f32_e32 v161, v93
	v_pk_mul_f32 v[120:121], v[120:121], v[164:165]
	v_exp_f32_e32 v162, v94
	v_pk_mul_f32 v[122:123], v[122:123], v[166:167]
	v_exp_f32_e32 v163, v95
	v_pk_mul_f32 v[108:109], v[108:109], v[168:169]
	v_exp_f32_e32 v164, v88
	v_pk_mul_f32 v[110:111], v[110:111], v[170:171]
	v_exp_f32_e32 v165, v89
	v_pk_mul_f32 v[104:105], v[104:105], v[172:173]
	v_exp_f32_e32 v166, v90
	v_pk_mul_f32 v[106:107], v[106:107], v[174:175]
	v_exp_f32_e32 v167, v91
	v_pk_mul_f32 v[116:117], v[124:125], v[116:117]
	v_exp_f32_e32 v168, v76
	v_pk_mul_f32 v[118:119], v[126:127], v[118:119]
	v_exp_f32_e32 v169, v77
	v_pk_mul_f32 v[112:113], v[120:121], v[112:113]
	v_exp_f32_e32 v170, v78
	v_pk_mul_f32 v[114:115], v[122:123], v[114:115]
	v_exp_f32_e32 v171, v79
	v_pk_mul_f32 v[100:101], v[108:109], v[100:101]
	v_exp_f32_e32 v172, v72
	v_pk_mul_f32 v[102:103], v[110:111], v[102:103]
	v_exp_f32_e32 v173, v73
	v_pk_mul_f32 v[96:97], v[104:105], v[96:97]
	v_exp_f32_e32 v174, v74
	v_pk_mul_f32 v[98:99], v[106:107], v[98:99]
	v_exp_f32_e32 v175, v75
	v_pk_add_f32 v[160:161], v[160:161], v[176:177] op_sel_hi:[1,0]
	v_pk_add_f32 v[162:163], v[162:163], v[176:177] op_sel_hi:[1,0]
	v_pk_add_f32 v[164:165], v[164:165], v[176:177] op_sel_hi:[1,0]
	v_pk_add_f32 v[166:167], v[166:167], v[176:177] op_sel_hi:[1,0]
	v_pk_add_f32 v[168:169], v[168:169], v[176:177] op_sel_hi:[1,0]
	v_pk_add_f32 v[170:171], v[170:171], v[176:177] op_sel_hi:[1,0]
	v_pk_add_f32 v[172:173], v[172:173], v[176:177] op_sel_hi:[1,0]
	v_pk_add_f32 v[174:175], v[174:175], v[176:177] op_sel_hi:[1,0]
	v_rcp_f32_e32 v160, v160
	v_cvt_pk_bf16_f32 v120, v116, v117
	v_rcp_f32_e32 v161, v161
	v_cvt_pk_bf16_f32 v121, v118, v119
	v_rcp_f32_e32 v162, v162
	v_cvt_pk_bf16_f32 v122, v112, v113
	v_rcp_f32_e32 v163, v163
	v_cvt_pk_bf16_f32 v123, v114, v115
	v_rcp_f32_e32 v164, v164
	v_cvt_pk_bf16_f32 v104, v100, v101
	v_rcp_f32_e32 v165, v165
	v_cvt_pk_bf16_f32 v105, v102, v103
	v_rcp_f32_e32 v166, v166
	v_cvt_pk_bf16_f32 v106, v96, v97
	v_rcp_f32_e32 v167, v167
	v_cvt_pk_bf16_f32 v107, v98, v99
	v_rcp_f32_e32 v168, v168
	global_store_dwordx4 v[198:199], v[120:123], off
	v_rcp_f32_e32 v169, v169
	global_store_dwordx4 v[200:201], v[104:107], off
	v_rcp_f32_e32 v170, v170
	v_rcp_f32_e32 v171, v171
	v_rcp_f32_e32 v172, v172
	v_rcp_f32_e32 v173, v173
	v_rcp_f32_e32 v174, v174
	v_rcp_f32_e32 v175, v175
	v_pk_mul_f32 v[92:93], v[92:93], v[160:161]
	v_exp_f32_e32 v160, v60
	v_pk_mul_f32 v[94:95], v[94:95], v[162:163]
	v_exp_f32_e32 v161, v61
	v_pk_mul_f32 v[88:89], v[88:89], v[164:165]
	v_exp_f32_e32 v162, v62
	v_pk_mul_f32 v[90:91], v[90:91], v[166:167]
	v_exp_f32_e32 v163, v63
	v_pk_mul_f32 v[76:77], v[76:77], v[168:169]
	v_exp_f32_e32 v164, v56
	v_pk_mul_f32 v[78:79], v[78:79], v[170:171]
	v_exp_f32_e32 v165, v57
	v_pk_mul_f32 v[72:73], v[72:73], v[172:173]
	v_exp_f32_e32 v166, v58
	v_pk_mul_f32 v[74:75], v[74:75], v[174:175]
	v_exp_f32_e32 v167, v59
	v_pk_mul_f32 v[84:85], v[92:93], v[84:85]
	v_exp_f32_e32 v168, v44
	v_pk_mul_f32 v[86:87], v[94:95], v[86:87]
; __device__ __forceinline__ unsigned cvt_pk_bf16(float lo, float hi) { unsigned r; asm volatile("v_cvt_pk_bf16_f32 %0, %1, %2" : "=v"(r) : "v"(lo), "v"(hi)); return r; }
;     __device__ __forceinline__ void operator()(const f32x4 (&acc)[2][2][4][2], const Unit& u, int wr, int wc, int fr, int fq) const {
;         const int row0 = u.pm * BM + wr * 64 + fr, col0 = u.pn * 128 + wc * 32 + 8 * fq;
; #pragma unroll
;         for (int ai = 0; ai < 2; ++ai)
; #pragma unroll
;             for (int m = 0; m < 4; ++m) {
;                 bf16_t* p = O + (size_t)(row0 + ai * HALF + m * 16) * ldc + col0;
;                 float h[8]; const float rsc = rs ? rs[row0 + ai * HALF + m * 16] : 1.0f;
; #pragma unroll
;                 for (int n = 0; n < 2; ++n)
; #pragma unroll
;                     for (int i = 0; i < 4; ++i) { const float g = acc[ai][0][m][n][i] * rsc, uu = acc[ai][1][m][n][i] * rsc; h[4 * n + i] = g * __builtin_amdgcn_rcpf(1.0f + __builtin_amdgcn_exp2f(g)) * uu; }
;                 u32x4 w; w.x = cvt_pk_bf16(h[0], h[1]); w.y = cvt_pk_bf16(h[2], h[3]); w.z = cvt_pk_bf16(h[4], h[5]); w.w = cvt_pk_bf16(h[6], h[7]);
;                 *(u32x4*)p = w;
;             }
	v_exp_f32_e32 v169, v45
	v_pk_mul_f32 v[80:81], v[88:89], v[80:81]
	v_exp_f32_e32 v170, v46
	v_pk_mul_f32 v[82:83], v[90:91], v[82:83]
	v_exp_f32_e32 v171, v47
	v_pk_mul_f32 v[68:69], v[76:77], v[68:69]
	v_exp_f32_e32 v172, v40
	v_pk_mul_f32 v[70:71], v[78:79], v[70:71]
	v_exp_f32_e32 v173, v41
	v_pk_mul_f32 v[64:65], v[72:73], v[64:65]
	v_exp_f32_e32 v174, v42
	v_pk_mul_f32 v[66:67], v[74:75], v[66:67]
	v_exp_f32_e32 v175, v43
	v_pk_add_f32 v[160:161], v[160:161], v[176:177] op_sel_hi:[1,0]
	v_pk_add_f32 v[162:163], v[162:163], v[176:177] op_sel_hi:[1,0]
	v_pk_add_f32 v[164:165], v[164:165], v[176:177] op_sel_hi:[1,0]
	v_pk_add_f32 v[166:167], v[166:167], v[176:177] op_sel_hi:[1,0]
	v_pk_add_f32 v[168:169], v[168:169], v[176:177] op_sel_hi:[1,0]
	v_pk_add_f32 v[170:171], v[170:171], v[176:177] op_sel_hi:[1,0]
	v_pk_add_f32 v[172:173], v[172:173], v[176:177] op_sel_hi:[1,0]
	v_pk_add_f32 v[174:175], v[174:175], v[176:177] op_sel_hi:[1,0]
	v_rcp_f32_e32 v160, v160
	v_cvt_pk_bf16_f32 v88, v84, v85
	v_rcp_f32_e32 v161, v161
	v_cvt_pk_bf16_f32 v89, v86, v87
	v_rcp_f32_e32 v162, v162
	v_cvt_pk_bf16_f32 v90, v80, v81
	v_rcp_f32_e32 v163, v163
	v_cvt_pk_bf16_f32 v91, v82, v83
	v_rcp_f32_e32 v164, v164
	v_cvt_pk_bf16_f32 v72, v68, v69
	v_rcp_f32_e32 v165, v165
	v_cvt_pk_bf16_f32 v73, v70, v71
	v_rcp_f32_e32 v166, v166
	v_cvt_pk_bf16_f32 v74, v64, v65
	v_rcp_f32_e32 v167, v167
	v_cvt_pk_bf16_f32 v75, v66, v67
	v_rcp_f32_e32 v168, v168
	global_store_dwordx4 v[202:203], v[88:91], off
	v_rcp_f32_e32 v169, v169
	global_store_dwordx4 v[204:205], v[72:75], off
	v_rcp_f32_e32 v170, v170
	v_rcp_f32_e32 v171, v171
	v_rcp_f32_e32 v172, v172
	v_rcp_f32_e32 v173, v173
	v_rcp_f32_e32 v174, v174
	v_rcp_f32_e32 v175, v175
	v_pk_mul_f32 v[60:61], v[60:61], v[160:161]
	v_exp_f32_e32 v160, v28
	v_pk_mul_f32 v[62:63], v[62:63], v[162:163]
	v_exp_f32_e32 v161, v29
	v_pk_mul_f32 v[56:57], v[56:57], v[164:165]
	v_exp_f32_e32 v162, v30
	v_pk_mul_f32 v[58:59], v[58:59], v[166:167]
	v_exp_f32_e32 v163, v31
	v_pk_mul_f32 v[44:45], v[44:45], v[168:169]
	v_exp_f32_e32 v164, v24
	v_pk_mul_f32 v[46:47], v[46:47], v[170:171]
	v_exp_f32_e32 v165, v25
	v_pk_mul_f32 v[40:41], v[40:41], v[172:173]
	v_exp_f32_e32 v166, v26
	v_pk_mul_f32 v[42:43], v[42:43], v[174:175]
	v_exp_f32_e32 v167, v27
	v_pk_mul_f32 v[52:53], v[60:61], v[52:53]
	v_exp_f32_e32 v168, v12
	v_pk_mul_f32 v[54:55], v[62:63], v[54:55]
	v_exp_f32_e32 v169, v13
	v_pk_mul_f32 v[48:49], v[56:57], v[48:49]
	v_exp_f32_e32 v170, v14
	v_pk_mul_f32 v[50:51], v[58:59], v[50:51]
	v_exp_f32_e32 v171, v15
	v_pk_mul_f32 v[36:37], v[44:45], v[36:37]
	v_exp_f32_e32 v172, v8
	v_pk_mul_f32 v[38:39], v[46:47], v[38:39]
	v_exp_f32_e32 v173, v9
	v_pk_mul_f32 v[32:33], v[40:41], v[32:33]
	v_exp_f32_e32 v174, v10
	v_pk_mul_f32 v[34:35], v[42:43], v[34:35]
	v_exp_f32_e32 v175, v11
	v_pk_add_f32 v[160:161], v[160:161], v[176:177] op_sel_hi:[1,0]
	v_pk_add_f32 v[162:163], v[162:163], v[176:177] op_sel_hi:[1,0]
	v_pk_add_f32 v[164:165], v[164:165], v[176:177] op_sel_hi:[1,0]
	v_pk_add_f32 v[166:167], v[166:167], v[176:177] op_sel_hi:[1,0]
	v_pk_add_f32 v[168:169], v[168:169], v[176:177] op_sel_hi:[1,0]
	v_pk_add_f32 v[170:171], v[170:171], v[176:177] op_sel_hi:[1,0]
	v_pk_add_f32 v[172:173], v[172:173], v[176:177] op_sel_hi:[1,0]
	v_pk_add_f32 v[174:175], v[174:175], v[176:177] op_sel_hi:[1,0]
	v_rcp_f32_e32 v160, v160
	v_cvt_pk_bf16_f32 v56, v52, v53
	v_rcp_f32_e32 v161, v161
	v_cvt_pk_bf16_f32 v57, v54, v55
	v_rcp_f32_e32 v162, v162
	v_cvt_pk_bf16_f32 v58, v48, v49
	v_rcp_f32_e32 v163, v163
	v_cvt_pk_bf16_f32 v59, v50, v51
	v_rcp_f32_e32 v164, v164
	v_cvt_pk_bf16_f32 v40, v36, v37
	v_rcp_f32_e32 v165, v165
	v_cvt_pk_bf16_f32 v41, v38, v39
	v_rcp_f32_e32 v166, v166
	v_cvt_pk_bf16_f32 v42, v32, v33
	v_rcp_f32_e32 v167, v167
	v_cvt_pk_bf16_f32 v43, v34, v35
	v_rcp_f32_e32 v168, v168
	global_store_dwordx4 v[206:207], v[56:59], off
	v_rcp_f32_e32 v169, v169
	global_store_dwordx4 v[208:209], v[40:43], off
	v_rcp_f32_e32 v170, v170
	v_rcp_f32_e32 v171, v171
	v_rcp_f32_e32 v172, v172
	v_rcp_f32_e32 v173, v173
	v_rcp_f32_e32 v174, v174
	v_rcp_f32_e32 v175, v175
	v_pk_mul_f32 v[28:29], v[28:29], v[160:161]
	v_pk_mul_f32 v[30:31], v[30:31], v[162:163]
	v_pk_mul_f32 v[24:25], v[24:25], v[164:165]
	v_pk_mul_f32 v[26:27], v[26:27], v[166:167]
	v_pk_mul_f32 v[12:13], v[12:13], v[168:169]
	v_pk_mul_f32 v[14:15], v[14:15], v[170:171]
	v_pk_mul_f32 v[8:9], v[8:9], v[172:173]
	v_pk_mul_f32 v[10:11], v[10:11], v[174:175]
	v_pk_mul_f32 v[20:21], v[28:29], v[20:21]
	v_pk_mul_f32 v[22:23], v[30:31], v[22:23]
	v_pk_mul_f32 v[16:17], v[24:25], v[16:17]
	v_pk_mul_f32 v[18:19], v[26:27], v[18:19]
	v_pk_mul_f32 v[4:5], v[12:13], v[4:5]
	v_pk_mul_f32 v[6:7], v[14:15], v[6:7]
	v_pk_mul_f32 v[0:1], v[8:9], v[0:1]
	v_pk_mul_f32 v[2:3], v[10:11], v[2:3]
	v_cvt_pk_bf16_f32 v24, v20, v21
	v_cvt_pk_bf16_f32 v25, v22, v23
	v_cvt_pk_bf16_f32 v26, v16, v17
	v_cvt_pk_bf16_f32 v27, v18, v19
	v_cvt_pk_bf16_f32 v8, v4, v5
	v_cvt_pk_bf16_f32 v9, v6, v7
	v_cvt_pk_bf16_f32 v10, v0, v1
	v_cvt_pk_bf16_f32 v11, v2, v3
	global_store_dwordx4 v[210:211], v[24:27], off
	global_store_dwordx4 v[212:213], v[8:11], off
	s_andn2_b64 vcc, exec, s[0:1]
	s_mov_b64 s[0:1], -1
	s_cbranch_vccnz .LBB0_289
	s_andn2_b64 vcc, exec, s[4:5]
	s_cbranch_vccnz .LBB0_288
	s_barrier
	s_branch .LBB0_288

; DI unsigned pk2(float lo, float hi) { f32x2_t v = {lo, hi}; bf16x2_t b = __builtin_convertvector(v, bf16x2_t); return __builtin_bit_cast(unsigned, b); }
; DI float bflo(unsigned u) { return __uint_as_float(u << 16); }
; template <int NR, bool XIN_BF, bool XOUT_BF> DI void resid_rows(const void* xin_, void* xout_, const bf16* d, const float* rsq, float coef, const float* pg, const float* ng, bf16* xn, int m0, int mstride, int lane, float* rs_out = nullptr) {
;     f32x4 xv[NR][4]; u32x2 dv[NR][4]; float ss[NR];
; #pragma unroll
;     for (int r = 0; r < NR; ++r) { const size_t m = (size_t)(m0 + r * mstride);
;         ss[r] = lane < 16 ? rsq[m * 16 + lane] : 0.f;
; #pragma unroll
;         for (int j = 0; j < 4; ++j) { const int c = 4 * lane + 256 * j;
;             if (XIN_BF) { const u32x2 t = __builtin_nontemporal_load((const u32x2*)((const bf16*)xin_ + m * DM + c)); xv[r][j] = (f32x4){bflo(t.x), bfhi(t.x), bflo(t.y), bfhi(t.y)}; }
;             else xv[r][j] = __builtin_nontemporal_load((const f32x4*)((const float*)xin_ + m * DM + c));
;             dv[r][j] = __builtin_nontemporal_load((const u32x2*)(d + m * DM + c)); } }
; #pragma unroll
;     for (int r = 0; r < NR; ++r) { const size_t m = (size_t)(m0 + r * mstride);
;         const float rr = rsqrtf(wave_sum(ss[r]) * (1.f / 1024.f) + EPS) * coef; float s2 = 0.f;
; #pragma unroll
;         for (int j = 0; j < 4; ++j) { const int c = 4 * lane + 256 * j; const f32x4 gg = *(const f32x4*)(pg + c);
;             const f32x4 df = {bflo(dv[r][j].x), bfhi(dv[r][j].x), bflo(dv[r][j].y), bfhi(dv[r][j].y)};
;             xv[r][j] = xv[r][j] + df * rr * gg;
;             if (XOUT_BF) { u32x2 w; w.x = pk2(xv[r][j][0], xv[r][j][1]); w.y = pk2(xv[r][j][2], xv[r][j][3]); *(u32x2*)((bf16*)xout_ + m * DM + c) = w; }
;             else __builtin_nontemporal_store(xv[r][j], (f32x4*)((float*)xout_ + m * DM + c));
;             s2 += (xv[r][j][0] * xv[r][j][0] + xv[r][j][1] * xv[r][j][1]) + (xv[r][j][2] * xv[r][j][2] + xv[r][j][3] * xv[r][j][3]); }
;         if (rs_out) { const float r2 = rsqrtf(wave_sum(s2) * (1.f / 1024.f) + EPS); if (lane == 0) rs_out[m] = r2; }
; __global__ void __launch_bounds__(512, 2) mk_fwd(Args a) {
;     ...
;         for (int m = gw; m < M; m += 4 * NGW) resid_rows<4, false, true>(x, a.out, Q, ROWSQ, 0.5f, (const float*)a.in[6], nullptr, nullptr, m, NGW, lane, RS2);
.LBB0_443:
	s_cmp_lt_i32 s66, 4
	s_cselect_b64 s[2:3], -1, 0
	s_add_u32 s4, s64, 0x2aac000
	s_addc_u32 s5, s65, 0
	s_and_b64 s[8:9], s[2:3], s[0:1]
	s_andn2_b64 vcc, exec, s[8:9]
	s_cbranch_vccnz .LBB0_463
	s_cmpk_gt_i32 s58, 0x7fff
	s_cbranch_scc1 .LBB0_463
	v_mbcnt_lo_u32_b32 v4, -1, 0
	v_mbcnt_hi_u32_b32 v4, -1, v4
	s_waitcnt lgkmcnt(0)
	v_and_b32_e32 v5, 64, v4
	v_add_u32_e32 v5, 64, v5
	v_xor_b32_e32 v6, 1, v4
	v_cmp_lt_i32_e32 vcc, v6, v5
	s_ashr_i32 s59, s58, 31
	s_lshl_b32 s10, s70, 5
	v_cndmask_b32_e32 v6, v4, v6, vcc
	s_lshl_b64 s[12:13], s[58:59], 2
	v_lshlrev_b32_e32 v110, 2, v6
	v_xor_b32_e32 v6, 2, v4
	s_add_u32 s11, s64, s12
	v_cmp_lt_i32_e32 vcc, v6, v5
	s_addc_u32 s13, s65, s13
	s_add_u32 s12, s11, 0x2aac000
	v_cndmask_b32_e32 v6, v4, v6, vcc
	v_lshlrev_b32_e32 v111, 2, v6
	v_xor_b32_e32 v6, 4, v4
	s_addc_u32 s13, s13, 0
	s_ashr_i32 s11, s10, 31
	v_cmp_lt_i32_e32 vcc, v6, v5
	s_lshl_b64 s[14:15], s[10:11], 2
	s_lshl_b64 s[16:17], s[58:59], 6
	v_mov_b32_e32 v65, 0
	v_readlane_b32 s2, v253, 49
	v_cndmask_b32_e32 v6, v4, v6, vcc
	s_add_u32 s16, s64, s16
	v_lshlrev_b32_e32 v0, 2, v196
	v_mov_b32_e32 v1, v65
	v_readlane_b32 s3, v253, 50
	v_lshlrev_b32_e32 v112, 2, v6
	v_xor_b32_e32 v6, 8, v4
	s_addc_u32 s17, s65, s17
	v_lshl_add_u64 v[66:67], s[2:3], 0, v[0:1]
	v_cmp_lt_i32_e32 vcc, v6, v5
	v_lshl_add_u64 v[0:1], s[16:17], 0, v[0:1]
	s_mov_b64 s[16:17], 0x28a0000
	v_cndmask_b32_e32 v6, v4, v6, vcc
	v_lshl_add_u64 v[76:77], v[0:1], 0, s[16:17]
	s_lshl_b64 s[16:17], s[10:11], 6
	s_lshl_b64 s[22:23], s[58:59], 11
	v_lshlrev_b32_e32 v113, 2, v6
	v_xor_b32_e32 v6, 16, v4
	s_add_u32 s18, s62, s22
	v_cmp_lt_i32_e32 vcc, v6, v5
	s_addc_u32 s19, s63, s23
	s_lshl_b64 s[20:21], s[10:11], 11
	v_cndmask_b32_e32 v6, v4, v6, vcc
	s_add_u32 s22, s64, s22
	v_readlane_b32 s36, v253, 3
	v_lshlrev_b32_e32 v114, 2, v6
	v_xor_b32_e32 v6, 32, v4
	s_addc_u32 s23, s65, s23
	s_lshl_b64 s[24:25], s[58:59], 12
	v_readlane_b32 s37, v253, 4
	v_cmp_lt_i32_e32 vcc, v6, v5
	s_add_u32 s24, s36, s24
	v_lshlrev_b32_e32 v2, 4, v196
	v_mov_b32_e32 v3, v65
	v_readlane_b32 s42, v253, 9
	v_readlane_b32 s43, v253, 10
	v_readlane_b32 s48, v253, 15
	v_readlane_b32 s49, v253, 16
	v_cndmask_b32_e32 v4, v4, v6, vcc
	v_lshlrev_b32_e32 v64, 3, v196
	s_addc_u32 s25, s37, s25
	v_cmp_gt_u32_e64 s[0:1], 16, v196
	v_cmp_eq_u32_e64 s[2:3], 0, v196
	v_lshl_add_u64 v[68:69], s[48:49], 0, v[2:3]
	v_lshlrev_b32_e32 v115, 2, v4
	v_lshl_add_u64 v[70:71], s[36:37], 0, v[2:3]
	v_lshl_add_u64 v[72:73], s[84:85], 0, v[64:65]
	v_lshl_add_u64 v[74:75], s[62:63], 0, v[64:65]
	s_mul_i32 s33, s70, 24
	v_lshl_add_u64 v[78:79], s[24:25], 0, v[2:3]
	s_lshl_b64 s[24:25], s[10:11], 12
	s_lshl_b32 s11, s70, 4
	v_mov_b32_e32 v116, 0x358637bd
	s_mov_b32 s42, 0x800000
	s_mov_b32 s43, s58
	v_readlane_b32 s38, v253, 5
	v_readlane_b32 s39, v253, 6
	v_readlane_b32 s40, v253, 7
	v_readlane_b32 s41, v253, 8
	v_readlane_b32 s44, v253, 11
	v_readlane_b32 s45, v253, 12
	v_readlane_b32 s46, v253, 13
	v_readlane_b32 s47, v253, 14
	v_readlane_b32 s50, v253, 17
	v_readlane_b32 s51, v253, 18
	global_load_dwordx4 v[200:203], v[68:69], off
	global_load_dwordx4 v[204:207], v[68:69], off offset:1024
	global_load_dwordx4 v[208:211], v[68:69], off offset:2048
	global_load_dwordx4 v[212:215], v[68:69], off offset:3072
	s_waitcnt vmcnt(0)
	s_branch .LBB0_447

; DI unsigned pk2(float lo, float hi) { f32x2_t v = {lo, hi}; bf16x2_t b = __builtin_convertvector(v, bf16x2_t); return __builtin_bit_cast(unsigned, b); }
; DI float bflo(unsigned u) { return __uint_as_float(u << 16); }
; DI float bfhi(unsigned u) { return __uint_as_float(u & 0xffff0000u); }
; template <int NR, bool XIN_BF, bool XOUT_BF> DI void resid_rows(const void* xin_, void* xout_, const bf16* d, const float* rsq, float coef, const float* pg, const float* ng, bf16* xn, int m0, int mstride, int lane, float* rs_out = nullptr) {
;     ...
;     for (int r = 0; r < NR; ++r) { const size_t m = (size_t)(m0 + r * mstride);
;         const float rr = rsqrtf(wave_sum(ss[r]) * (1.f / 1024.f) + EPS) * coef; float s2 = 0.f;
; #pragma unroll
;         for (int j = 0; j < 4; ++j) { const int c = 4 * lane + 256 * j; const f32x4 gg = *(const f32x4*)(pg + c);
;             const f32x4 df = {bflo(dv[r][j].x), bfhi(dv[r][j].x), bflo(dv[r][j].y), bfhi(dv[r][j].y)};
;             xv[r][j] = xv[r][j] + df * rr * gg;
;             if (XOUT_BF) { u32x2 w; w.x = pk2(xv[r][j][0], xv[r][j][1]); w.y = pk2(xv[r][j][2], xv[r][j][3]); *(u32x2*)((bf16*)xout_ + m * DM + c) = w; }
;             else __builtin_nontemporal_store(xv[r][j], (f32x4*)((float*)xout_ + m * DM + c));
;             s2 += (xv[r][j][0] * xv[r][j][0] + xv[r][j][1] * xv[r][j][1]) + (xv[r][j][2] * xv[r][j][2] + xv[r][j][3] * xv[r][j][3]); }
;         if (rs_out) { const float r2 = rsqrtf(wave_sum(s2) * (1.f / 1024.f) + EPS); if (lane == 0) rs_out[m] = r2; }
.LBB0_455:
	s_or_b64 exec, exec, s[30:31]
	s_nop 1
	v_mov_b64_e32 v[120:121], v[200:201]
	v_mov_b64_e32 v[122:123], v[202:203]
	s_waitcnt vmcnt(0)
	ds_bpermute_b32 v3, v110, v2
	v_lshlrev_b32_e32 v124, 16, v0
	v_and_b32_e32 v125, 0xffff0000, v0
	v_lshlrev_b32_e32 v126, 16, v1
	v_and_b32_e32 v127, 0xffff0000, v1
	s_waitcnt lgkmcnt(0)
	v_add_f32_e32 v2, v2, v3
	ds_bpermute_b32 v3, v111, v2
	s_lshl_b64 s[40:41], s[26:27], 12
	s_lshl_b64 s[30:31], s[26:27], 11
	v_lshl_add_u64 v[128:129], s[18:19], 0, v[64:65]
	v_lshl_add_u64 v[0:1], v[70:71], 0, s[40:41]
	s_waitcnt lgkmcnt(0)
	v_add_f32_e32 v2, v2, v3
	ds_bpermute_b32 v3, v112, v2
	v_lshl_add_u64 v[80:81], v[72:73], 0, s[30:31]
	s_waitcnt lgkmcnt(0)
	v_add_f32_e32 v2, v2, v3
	ds_bpermute_b32 v3, v113, v2
	s_waitcnt lgkmcnt(0)
	v_add_f32_e32 v2, v2, v3
	ds_bpermute_b32 v3, v114, v2
	s_waitcnt lgkmcnt(0)
	v_add_f32_e32 v82, v2, v3
	ds_bpermute_b32 v83, v115, v82
	global_load_dwordx4 v[12:15], v[0:1], off nt
	global_load_dwordx4 v[8:11], v[0:1], off offset:1024 nt
	global_load_dwordx4 v[4:7], v[0:1], off offset:2048 nt
	s_nop 0
	global_load_dwordx4 v[0:3], v[0:1], off offset:3072 nt
	s_waitcnt lgkmcnt(0)
	v_add_f32_e32 v82, v82, v83
	v_fmamk_f32 v82, v82, 0x3a800000, v116
	v_mul_f32_e32 v83, 0x4b800000, v82
	v_cmp_gt_f32_e32 vcc, s42, v82
	s_nop 1
	v_cndmask_b32_e32 v82, v82, v83, vcc
	v_rsq_f32_e32 v130, v82
	global_load_dwordx2 v[86:87], v[80:81], off nt
	global_load_dwordx2 v[84:85], v[80:81], off offset:512 nt
	global_load_dwordx2 v[82:83], v[80:81], off offset:1024 nt
	s_nop 0
	global_load_dwordx2 v[80:81], v[80:81], off offset:1536 nt
	v_mul_f32_e32 v131, 0x45800000, v130
	v_cndmask_b32_e32 v130, v130, v131, vcc
	v_mul_f32_e32 v130, 0.5, v130
	v_pk_mul_f32 v[124:125], v[130:131], v[124:125] op_sel_hi:[0,1]
	v_pk_mul_f32 v[126:127], v[130:131], v[126:127] op_sel_hi:[0,1]
	v_pk_fma_f32 v[122:123], v[122:123], v[126:127], v[62:63]
	v_pk_fma_f32 v[120:121], v[120:121], v[124:125], v[60:61]
	v_cvt_pk_bf16_f32 v61, v122, v123
	v_cvt_pk_bf16_f32 v60, v120, v121
	global_store_dwordx2 v[128:129], v[60:61], off
	s_nop 1
	v_mov_b64_e32 v[60:61], v[204:205]
	v_mov_b64_e32 v[62:63], v[206:207]
	v_lshlrev_b32_e32 v124, 16, v108
	v_and_b32_e32 v125, 0xffff0000, v108
	v_lshlrev_b32_e32 v108, 16, v109
	v_and_b32_e32 v109, 0xffff0000, v109
	v_pk_mul_f32 v[124:125], v[130:131], v[124:125] op_sel_hi:[0,1]
	v_pk_mul_f32 v[108:109], v[130:131], v[108:109] op_sel_hi:[0,1]
	s_nop 1
	v_pk_fma_f32 v[62:63], v[62:63], v[108:109], v[58:59]
	v_pk_fma_f32 v[60:61], v[60:61], v[124:125], v[56:57]
	v_cvt_pk_bf16_f32 v57, v62, v63
	v_cvt_pk_bf16_f32 v56, v60, v61
	global_store_dwordx2 v[128:129], v[56:57], off offset:512
	s_nop 1
	v_mov_b64_e32 v[56:57], v[208:209]
	v_mov_b64_e32 v[58:59], v[210:211]
	v_lshlrev_b32_e32 v108, 16, v106
	v_and_b32_e32 v109, 0xffff0000, v106
	v_lshlrev_b32_e32 v106, 16, v107
	v_and_b32_e32 v107, 0xffff0000, v107
	v_pk_mul_f32 v[108:109], v[130:131], v[108:109] op_sel_hi:[0,1]
	v_pk_mul_f32 v[106:107], v[130:131], v[106:107] op_sel_hi:[0,1]
	v_mul_f32_e32 v61, v61, v61
	v_mul_f32_e32 v63, v63, v63
	v_fmac_f32_e32 v61, v60, v60
	v_fmac_f32_e32 v63, v62, v62
	v_add_f32_e32 v60, v61, v63
	s_nop 1
	v_pk_fma_f32 v[58:59], v[58:59], v[106:107], v[54:55]
	v_pk_fma_f32 v[56:57], v[56:57], v[108:109], v[52:53]
	v_cvt_pk_bf16_f32 v53, v58, v59
	v_cvt_pk_bf16_f32 v52, v56, v57
	global_store_dwordx2 v[128:129], v[52:53], off offset:1024
	s_nop 1
	v_mov_b64_e32 v[52:53], v[212:213]
	v_mov_b64_e32 v[54:55], v[214:215]
	v_lshlrev_b32_e32 v106, 16, v104
	v_and_b32_e32 v107, 0xffff0000, v104
	v_lshlrev_b32_e32 v104, 16, v105
	v_and_b32_e32 v105, 0xffff0000, v105
	v_pk_mul_f32 v[106:107], v[130:131], v[106:107] op_sel_hi:[0,1]
	v_pk_mul_f32 v[104:105], v[130:131], v[104:105] op_sel_hi:[0,1]
	v_mul_f32_e32 v108, v121, v121
	v_mul_f32_e32 v109, v123, v123
	v_fmac_f32_e32 v108, v120, v120
	v_fmac_f32_e32 v109, v122, v122
	v_mul_f32_e32 v57, v57, v57
	v_mul_f32_e32 v59, v59, v59
	v_add_f32_e32 v108, v108, v109
	v_fmac_f32_e32 v57, v56, v56
	v_fmac_f32_e32 v59, v58, v58
	v_add_f32_e32 v60, v108, v60
	v_add_f32_e32 v56, v57, v59
	v_add_f32_e32 v56, v56, v60
	s_nop 1
	v_pk_fma_f32 v[50:51], v[54:55], v[104:105], v[50:51]
	v_pk_fma_f32 v[52:53], v[52:53], v[106:107], v[48:49]
	v_mul_f32_e32 v49, v51, v51
	v_mul_f32_e32 v48, v53, v53
	v_fmac_f32_e32 v48, v52, v52
	v_fmac_f32_e32 v49, v50, v50
	v_add_f32_e32 v48, v48, v49
	v_add_f32_e32 v48, v48, v56
	ds_bpermute_b32 v49, v110, v48
	v_cvt_pk_bf16_f32 v52, v52, v53
	v_cvt_pk_bf16_f32 v53, v50, v51
	global_store_dwordx2 v[128:129], v[52:53], off offset:1536
	s_waitcnt lgkmcnt(0)
	v_add_f32_e32 v48, v48, v49
	ds_bpermute_b32 v49, v111, v48
	s_waitcnt lgkmcnt(0)
	v_add_f32_e32 v48, v48, v49
	ds_bpermute_b32 v49, v112, v48
	s_waitcnt lgkmcnt(0)
	v_add_f32_e32 v48, v48, v49
	ds_bpermute_b32 v49, v113, v48
	s_waitcnt lgkmcnt(0)
	v_add_f32_e32 v48, v48, v49
	ds_bpermute_b32 v49, v114, v48
	s_waitcnt lgkmcnt(0)
	v_add_f32_e32 v48, v48, v49
	ds_bpermute_b32 v49, v115, v48
	s_and_saveexec_b64 s[40:41], s[2:3]
	s_cbranch_execz .LBB0_457
	s_waitcnt lgkmcnt(0)
	v_add_f32_e32 v48, v48, v49
	v_fmamk_f32 v48, v48, 0x3a800000, v116
	v_mul_f32_e32 v49, 0x4b800000, v48
	v_cmp_gt_f32_e32 vcc, s42, v48
	s_nop 1
	v_cndmask_b32_e32 v48, v48, v49, vcc
	v_rsq_f32_e32 v48, v48
	s_nop 0
	v_mul_f32_e32 v49, 0x45800000, v48
	v_cndmask_b32_e32 v48, v48, v49, vcc
	global_store_dword v65, v48, s[12:13]
; DI unsigned pk2(float lo, float hi) { f32x2_t v = {lo, hi}; bf16x2_t b = __builtin_convertvector(v, bf16x2_t); return __builtin_bit_cast(unsigned, b); }
; DI float bflo(unsigned u) { return __uint_as_float(u << 16); }
; DI float bfhi(unsigned u) { return __uint_as_float(u & 0xffff0000u); }
; template <int NR, bool XIN_BF, bool XOUT_BF> DI void resid_rows(const void* xin_, void* xout_, const bf16* d, const float* rsq, float coef, const float* pg, const float* ng, bf16* xn, int m0, int mstride, int lane, float* rs_out = nullptr) {
;     ...
;     for (int r = 0; r < NR; ++r) { const size_t m = (size_t)(m0 + r * mstride);
;         const float rr = rsqrtf(wave_sum(ss[r]) * (1.f / 1024.f) + EPS) * coef; float s2 = 0.f;
; #pragma unroll
;         for (int j = 0; j < 4; ++j) { const int c = 4 * lane + 256 * j; const f32x4 gg = *(const f32x4*)(pg + c);
;             const f32x4 df = {bflo(dv[r][j].x), bfhi(dv[r][j].x), bflo(dv[r][j].y), bfhi(dv[r][j].y)};
;             xv[r][j] = xv[r][j] + df * rr * gg;
;             if (XOUT_BF) { u32x2 w; w.x = pk2(xv[r][j][0], xv[r][j][1]); w.y = pk2(xv[r][j][2], xv[r][j][3]); *(u32x2*)((bf16*)xout_ + m * DM + c) = w; }
;             else __builtin_nontemporal_store(xv[r][j], (f32x4*)((float*)xout_ + m * DM + c));
;             s2 += (xv[r][j][0] * xv[r][j][0] + xv[r][j][1] * xv[r][j][1]) + (xv[r][j][2] * xv[r][j][2] + xv[r][j][3] * xv[r][j][3]); }
;         if (rs_out) { const float r2 = rsqrtf(wave_sum(s2) * (1.f / 1024.f) + EPS); if (lane == 0) rs_out[m] = r2; }
.LBB0_457:
	s_or_b64 exec, exec, s[40:41]
	s_waitcnt lgkmcnt(0)
	s_nop 1
	v_mov_b64_e32 v[48:49], v[200:201]
	v_mov_b64_e32 v[50:51], v[202:203]
	ds_bpermute_b32 v52, v110, v119
	v_lshl_add_u64 v[56:57], v[74:75], 0, s[38:39]
	s_waitcnt lgkmcnt(0)
	v_add_f32_e32 v52, v119, v52
	ds_bpermute_b32 v53, v111, v52
	s_waitcnt lgkmcnt(0)
	v_add_f32_e32 v52, v52, v53
	ds_bpermute_b32 v53, v112, v52
	s_waitcnt lgkmcnt(0)
	v_add_f32_e32 v52, v52, v53
	ds_bpermute_b32 v53, v113, v52
	s_waitcnt lgkmcnt(0)
	v_add_f32_e32 v52, v52, v53
	ds_bpermute_b32 v53, v114, v52
	s_waitcnt lgkmcnt(0)
	v_add_f32_e32 v54, v52, v53
	ds_bpermute_b32 v55, v115, v54
	v_lshlrev_b32_e32 v52, 16, v102
	v_and_b32_e32 v53, 0xffff0000, v102
	s_waitcnt lgkmcnt(0)
	v_add_f32_e32 v54, v54, v55
	v_fmamk_f32 v54, v54, 0x3a800000, v116
	v_mul_f32_e32 v55, 0x4b800000, v54
	v_cmp_gt_f32_e32 vcc, s42, v54
	s_nop 1
	v_cndmask_b32_e32 v54, v54, v55, vcc
	v_rsq_f32_e32 v58, v54
	v_lshlrev_b32_e32 v54, 16, v103
	v_and_b32_e32 v55, 0xffff0000, v103
	v_mul_f32_e32 v59, 0x45800000, v58
	v_cndmask_b32_e32 v58, v58, v59, vcc
	v_mul_f32_e32 v58, 0.5, v58
	v_pk_mul_f32 v[52:53], v[58:59], v[52:53] op_sel_hi:[0,1]
	v_pk_mul_f32 v[54:55], v[58:59], v[54:55] op_sel_hi:[0,1]
	s_nop 1
	v_pk_fma_f32 v[50:51], v[50:51], v[54:55], v[46:47]
	v_pk_fma_f32 v[48:49], v[48:49], v[52:53], v[44:45]
	v_cvt_pk_bf16_f32 v45, v50, v51
	v_cvt_pk_bf16_f32 v44, v48, v49
	global_store_dwordx2 v[56:57], v[44:45], off
	s_nop 1
	v_mov_b64_e32 v[44:45], v[204:205]
	v_mov_b64_e32 v[46:47], v[206:207]
	v_lshlrev_b32_e32 v52, 16, v100
	v_and_b32_e32 v53, 0xffff0000, v100
	v_lshlrev_b32_e32 v54, 16, v101
	v_and_b32_e32 v55, 0xffff0000, v101
	v_pk_mul_f32 v[52:53], v[58:59], v[52:53] op_sel_hi:[0,1]
	v_pk_mul_f32 v[54:55], v[58:59], v[54:55] op_sel_hi:[0,1]
	v_mul_f32_e32 v49, v49, v49
	v_mul_f32_e32 v51, v51, v51
	v_fmac_f32_e32 v49, v48, v48
	v_fmac_f32_e32 v51, v50, v50
	v_add_f32_e32 v48, v49, v51
	s_nop 1
	v_pk_fma_f32 v[46:47], v[46:47], v[54:55], v[42:43]
	v_pk_fma_f32 v[44:45], v[44:45], v[52:53], v[40:41]
	v_cvt_pk_bf16_f32 v41, v46, v47
	v_cvt_pk_bf16_f32 v40, v44, v45
	global_store_dwordx2 v[56:57], v[40:41], off offset:512
	s_nop 1
	v_mov_b64_e32 v[40:41], v[208:209]
	v_mov_b64_e32 v[42:43], v[210:211]
	v_lshlrev_b32_e32 v52, 16, v98
	v_and_b32_e32 v53, 0xffff0000, v98
	v_lshlrev_b32_e32 v54, 16, v99
	v_and_b32_e32 v55, 0xffff0000, v99
	v_pk_mul_f32 v[52:53], v[58:59], v[52:53] op_sel_hi:[0,1]
	v_pk_mul_f32 v[54:55], v[58:59], v[54:55] op_sel_hi:[0,1]
	v_mul_f32_e32 v45, v45, v45
	v_mul_f32_e32 v47, v47, v47
	v_fmac_f32_e32 v45, v44, v44
	v_fmac_f32_e32 v47, v46, v46
	v_add_f32_e32 v44, v45, v47
	v_add_f32_e32 v44, v48, v44
	s_nop 1
	v_pk_fma_f32 v[42:43], v[42:43], v[54:55], v[38:39]
	v_pk_fma_f32 v[40:41], v[40:41], v[52:53], v[36:37]
	v_cvt_pk_bf16_f32 v37, v42, v43
	v_cvt_pk_bf16_f32 v36, v40, v41
	global_store_dwordx2 v[56:57], v[36:37], off offset:1024
	s_nop 1
	v_mov_b64_e32 v[36:37], v[212:213]
	v_mov_b64_e32 v[38:39], v[214:215]
	v_lshlrev_b32_e32 v52, 16, v96
	v_and_b32_e32 v53, 0xffff0000, v96
	v_lshlrev_b32_e32 v54, 16, v97
	v_and_b32_e32 v55, 0xffff0000, v97
	v_pk_mul_f32 v[52:53], v[58:59], v[52:53] op_sel_hi:[0,1]
	v_pk_mul_f32 v[54:55], v[58:59], v[54:55] op_sel_hi:[0,1]
	v_mul_f32_e32 v41, v41, v41
	v_mul_f32_e32 v43, v43, v43
	v_fmac_f32_e32 v41, v40, v40
	v_fmac_f32_e32 v43, v42, v42
	v_add_f32_e32 v40, v41, v43
	v_add_f32_e32 v40, v40, v44
	s_nop 1
	v_pk_fma_f32 v[34:35], v[38:39], v[54:55], v[34:35]
	v_pk_fma_f32 v[36:37], v[36:37], v[52:53], v[32:33]
	v_mul_f32_e32 v33, v35, v35
	v_mul_f32_e32 v32, v37, v37
	v_fmac_f32_e32 v32, v36, v36
	v_fmac_f32_e32 v33, v34, v34
	v_add_f32_e32 v32, v32, v33
	v_add_f32_e32 v32, v32, v40
	ds_bpermute_b32 v33, v110, v32
	v_cvt_pk_bf16_f32 v36, v36, v37
	v_cvt_pk_bf16_f32 v37, v34, v35
	global_store_dwordx2 v[56:57], v[36:37], off offset:1536
	s_waitcnt lgkmcnt(0)
	v_add_f32_e32 v32, v32, v33
	ds_bpermute_b32 v33, v111, v32
	s_waitcnt lgkmcnt(0)
	v_add_f32_e32 v32, v32, v33
	ds_bpermute_b32 v33, v112, v32
	s_waitcnt lgkmcnt(0)
	v_add_f32_e32 v32, v32, v33
	ds_bpermute_b32 v33, v113, v32
	s_waitcnt lgkmcnt(0)
	v_add_f32_e32 v32, v32, v33
	ds_bpermute_b32 v33, v114, v32
	s_waitcnt lgkmcnt(0)
	v_add_f32_e32 v32, v32, v33
	ds_bpermute_b32 v33, v115, v32
	s_and_saveexec_b64 s[38:39], s[2:3]
	s_cbranch_execz .LBB0_459
	s_waitcnt lgkmcnt(0)
	v_add_f32_e32 v32, v32, v33
	v_fmamk_f32 v32, v32, 0x3a800000, v116
	v_mul_f32_e32 v33, 0x4b800000, v32
	v_cmp_gt_f32_e32 vcc, s42, v32
	s_lshl_b64 s[36:37], s[36:37], 2
	s_add_u32 s36, s4, s36
	v_cndmask_b32_e32 v32, v32, v33, vcc
	v_rsq_f32_e32 v32, v32
	s_addc_u32 s37, s5, s37
	v_mul_f32_e32 v33, 0x45800000, v32
	v_cndmask_b32_e32 v32, v32, v33, vcc
	global_store_dword v65, v32, s[36:37]
; DI unsigned pk2(float lo, float hi) { f32x2_t v = {lo, hi}; bf16x2_t b = __builtin_convertvector(v, bf16x2_t); return __builtin_bit_cast(unsigned, b); }
; DI float bflo(unsigned u) { return __uint_as_float(u << 16); }
; DI float bfhi(unsigned u) { return __uint_as_float(u & 0xffff0000u); }
; template <int NR, bool XIN_BF, bool XOUT_BF> DI void resid_rows(const void* xin_, void* xout_, const bf16* d, const float* rsq, float coef, const float* pg, const float* ng, bf16* xn, int m0, int mstride, int lane, float* rs_out = nullptr) {
;     ...
;     for (int r = 0; r < NR; ++r) { const size_t m = (size_t)(m0 + r * mstride);
;         const float rr = rsqrtf(wave_sum(ss[r]) * (1.f / 1024.f) + EPS) * coef; float s2 = 0.f;
; #pragma unroll
;         for (int j = 0; j < 4; ++j) { const int c = 4 * lane + 256 * j; const f32x4 gg = *(const f32x4*)(pg + c);
;             const f32x4 df = {bflo(dv[r][j].x), bfhi(dv[r][j].x), bflo(dv[r][j].y), bfhi(dv[r][j].y)};
;             xv[r][j] = xv[r][j] + df * rr * gg;
;             if (XOUT_BF) { u32x2 w; w.x = pk2(xv[r][j][0], xv[r][j][1]); w.y = pk2(xv[r][j][2], xv[r][j][3]); *(u32x2*)((bf16*)xout_ + m * DM + c) = w; }
;             else __builtin_nontemporal_store(xv[r][j], (f32x4*)((float*)xout_ + m * DM + c));
;             s2 += (xv[r][j][0] * xv[r][j][0] + xv[r][j][1] * xv[r][j][1]) + (xv[r][j][2] * xv[r][j][2] + xv[r][j][3] * xv[r][j][3]); }
;         if (rs_out) { const float r2 = rsqrtf(wave_sum(s2) * (1.f / 1024.f) + EPS); if (lane == 0) rs_out[m] = r2; }
.LBB0_459:
	s_or_b64 exec, exec, s[38:39]
	s_waitcnt lgkmcnt(0)
	s_nop 1
	v_mov_b64_e32 v[32:33], v[200:201]
	v_mov_b64_e32 v[34:35], v[202:203]
	ds_bpermute_b32 v36, v110, v118
	v_lshl_add_u64 v[40:41], v[74:75], 0, s[34:35]
	s_waitcnt lgkmcnt(0)
	v_add_f32_e32 v36, v118, v36
	ds_bpermute_b32 v37, v111, v36
	s_waitcnt lgkmcnt(0)
	v_add_f32_e32 v36, v36, v37
	ds_bpermute_b32 v37, v112, v36
	s_waitcnt lgkmcnt(0)
	v_add_f32_e32 v36, v36, v37
	ds_bpermute_b32 v37, v113, v36
	s_waitcnt lgkmcnt(0)
	v_add_f32_e32 v36, v36, v37
	ds_bpermute_b32 v37, v114, v36
	s_waitcnt lgkmcnt(0)
	v_add_f32_e32 v38, v36, v37
	ds_bpermute_b32 v39, v115, v38
	v_lshlrev_b32_e32 v36, 16, v94
	v_and_b32_e32 v37, 0xffff0000, v94
	s_waitcnt lgkmcnt(0)
	v_add_f32_e32 v38, v38, v39
	v_fmamk_f32 v38, v38, 0x3a800000, v116
	v_mul_f32_e32 v39, 0x4b800000, v38
	v_cmp_gt_f32_e32 vcc, s42, v38
	s_nop 1
	v_cndmask_b32_e32 v38, v38, v39, vcc
	v_rsq_f32_e32 v42, v38
	v_lshlrev_b32_e32 v38, 16, v95
	v_and_b32_e32 v39, 0xffff0000, v95
	v_mul_f32_e32 v43, 0x45800000, v42
	v_cndmask_b32_e32 v42, v42, v43, vcc
	v_mul_f32_e32 v42, 0.5, v42
	v_pk_mul_f32 v[36:37], v[42:43], v[36:37] op_sel_hi:[0,1]
	v_pk_mul_f32 v[38:39], v[42:43], v[38:39] op_sel_hi:[0,1]
	s_nop 1
	v_pk_fma_f32 v[34:35], v[34:35], v[38:39], v[30:31]
	v_pk_fma_f32 v[32:33], v[32:33], v[36:37], v[28:29]
	v_cvt_pk_bf16_f32 v29, v34, v35
	v_cvt_pk_bf16_f32 v28, v32, v33
	global_store_dwordx2 v[40:41], v[28:29], off
	s_nop 1
	v_mov_b64_e32 v[28:29], v[204:205]
	v_mov_b64_e32 v[30:31], v[206:207]
	v_lshlrev_b32_e32 v36, 16, v92
	v_and_b32_e32 v37, 0xffff0000, v92
	v_lshlrev_b32_e32 v38, 16, v93
	v_and_b32_e32 v39, 0xffff0000, v93
	v_pk_mul_f32 v[36:37], v[42:43], v[36:37] op_sel_hi:[0,1]
	v_pk_mul_f32 v[38:39], v[42:43], v[38:39] op_sel_hi:[0,1]
	v_mul_f32_e32 v33, v33, v33
	v_mul_f32_e32 v35, v35, v35
	v_fmac_f32_e32 v33, v32, v32
	v_fmac_f32_e32 v35, v34, v34
	v_add_f32_e32 v32, v33, v35
	s_nop 1
	v_pk_fma_f32 v[30:31], v[30:31], v[38:39], v[26:27]
	v_pk_fma_f32 v[28:29], v[28:29], v[36:37], v[24:25]
	v_cvt_pk_bf16_f32 v25, v30, v31
	v_cvt_pk_bf16_f32 v24, v28, v29
	global_store_dwordx2 v[40:41], v[24:25], off offset:512
	s_nop 1
	v_mov_b64_e32 v[24:25], v[208:209]
	v_mov_b64_e32 v[26:27], v[210:211]
	v_lshlrev_b32_e32 v36, 16, v90
	v_and_b32_e32 v37, 0xffff0000, v90
	v_lshlrev_b32_e32 v38, 16, v91
	v_and_b32_e32 v39, 0xffff0000, v91
	v_pk_mul_f32 v[36:37], v[42:43], v[36:37] op_sel_hi:[0,1]
	v_pk_mul_f32 v[38:39], v[42:43], v[38:39] op_sel_hi:[0,1]
	v_mul_f32_e32 v29, v29, v29
	v_mul_f32_e32 v31, v31, v31
	v_fmac_f32_e32 v29, v28, v28
	v_fmac_f32_e32 v31, v30, v30
	v_add_f32_e32 v28, v29, v31
	v_add_f32_e32 v28, v32, v28
	s_nop 1
	v_pk_fma_f32 v[26:27], v[26:27], v[38:39], v[22:23]
	v_pk_fma_f32 v[24:25], v[24:25], v[36:37], v[20:21]
	v_cvt_pk_bf16_f32 v21, v26, v27
	v_cvt_pk_bf16_f32 v20, v24, v25
	global_store_dwordx2 v[40:41], v[20:21], off offset:1024
	s_nop 1
	v_mov_b64_e32 v[20:21], v[212:213]
	v_mov_b64_e32 v[22:23], v[214:215]
	v_lshlrev_b32_e32 v36, 16, v88
	v_and_b32_e32 v37, 0xffff0000, v88
	v_lshlrev_b32_e32 v38, 16, v89
	v_and_b32_e32 v39, 0xffff0000, v89
	v_pk_mul_f32 v[36:37], v[42:43], v[36:37] op_sel_hi:[0,1]
	v_pk_mul_f32 v[38:39], v[42:43], v[38:39] op_sel_hi:[0,1]
	v_mul_f32_e32 v25, v25, v25
	v_mul_f32_e32 v27, v27, v27
	v_fmac_f32_e32 v25, v24, v24
	v_fmac_f32_e32 v27, v26, v26
	v_add_f32_e32 v24, v25, v27
	v_add_f32_e32 v24, v24, v28
	s_waitcnt vmcnt(0)
	v_pk_fma_f32 v[18:19], v[22:23], v[38:39], v[18:19]
	v_pk_fma_f32 v[20:21], v[20:21], v[36:37], v[16:17]
	v_mul_f32_e32 v17, v19, v19
	v_mul_f32_e32 v16, v21, v21
	v_fmac_f32_e32 v16, v20, v20
	v_fmac_f32_e32 v17, v18, v18
	v_add_f32_e32 v16, v16, v17
	v_add_f32_e32 v16, v16, v24
	ds_bpermute_b32 v17, v110, v16
	v_cvt_pk_bf16_f32 v20, v20, v21
	v_cvt_pk_bf16_f32 v21, v18, v19
	global_store_dwordx2 v[40:41], v[20:21], off offset:1536
	s_waitcnt lgkmcnt(0)
	v_add_f32_e32 v16, v16, v17
	ds_bpermute_b32 v17, v111, v16
	s_waitcnt lgkmcnt(0)
	v_add_f32_e32 v16, v16, v17
	ds_bpermute_b32 v17, v112, v16
	s_waitcnt lgkmcnt(0)
	v_add_f32_e32 v16, v16, v17
	ds_bpermute_b32 v17, v113, v16
	s_waitcnt lgkmcnt(0)
	v_add_f32_e32 v16, v16, v17
	ds_bpermute_b32 v17, v114, v16
	s_waitcnt lgkmcnt(0)
	v_add_f32_e32 v16, v16, v17
	ds_bpermute_b32 v17, v115, v16
	s_and_saveexec_b64 s[34:35], s[2:3]
	s_cbranch_execz .LBB0_461
	s_waitcnt lgkmcnt(0)
	v_add_f32_e32 v16, v16, v17
	v_fmamk_f32 v16, v16, 0x3a800000, v116
	v_mul_f32_e32 v17, 0x4b800000, v16
	v_cmp_gt_f32_e32 vcc, s42, v16
	s_lshl_b64 s[28:29], s[28:29], 2
	s_add_u32 s28, s4, s28
	v_cndmask_b32_e32 v16, v16, v17, vcc
	v_rsq_f32_e32 v16, v16
	s_addc_u32 s29, s5, s29
	v_mul_f32_e32 v17, 0x45800000, v16
	v_cndmask_b32_e32 v16, v16, v17, vcc
	global_store_dword v65, v16, s[28:29]
; DI unsigned pk2(float lo, float hi) { f32x2_t v = {lo, hi}; bf16x2_t b = __builtin_convertvector(v, bf16x2_t); return __builtin_bit_cast(unsigned, b); }
; DI float bflo(unsigned u) { return __uint_as_float(u << 16); }
; DI float bfhi(unsigned u) { return __uint_as_float(u & 0xffff0000u); }
; template <int NR, bool XIN_BF, bool XOUT_BF> DI void resid_rows(const void* xin_, void* xout_, const bf16* d, const float* rsq, float coef, const float* pg, const float* ng, bf16* xn, int m0, int mstride, int lane, float* rs_out = nullptr) {
;     ...
;     for (int r = 0; r < NR; ++r) { const size_t m = (size_t)(m0 + r * mstride);
;         const float rr = rsqrtf(wave_sum(ss[r]) * (1.f / 1024.f) + EPS) * coef; float s2 = 0.f;
; #pragma unroll
;         for (int j = 0; j < 4; ++j) { const int c = 4 * lane + 256 * j; const f32x4 gg = *(const f32x4*)(pg + c);
;             const f32x4 df = {bflo(dv[r][j].x), bfhi(dv[r][j].x), bflo(dv[r][j].y), bfhi(dv[r][j].y)};
;             xv[r][j] = xv[r][j] + df * rr * gg;
;             if (XOUT_BF) { u32x2 w; w.x = pk2(xv[r][j][0], xv[r][j][1]); w.y = pk2(xv[r][j][2], xv[r][j][3]); *(u32x2*)((bf16*)xout_ + m * DM + c) = w; }
;             else __builtin_nontemporal_store(xv[r][j], (f32x4*)((float*)xout_ + m * DM + c));
;             s2 += (xv[r][j][0] * xv[r][j][0] + xv[r][j][1] * xv[r][j][1]) + (xv[r][j][2] * xv[r][j][2] + xv[r][j][3] * xv[r][j][3]); }
;         if (rs_out) { const float r2 = rsqrtf(wave_sum(s2) * (1.f / 1024.f) + EPS); if (lane == 0) rs_out[m] = r2; }
.LBB0_461:
	s_or_b64 exec, exec, s[34:35]
	s_waitcnt lgkmcnt(0)
	s_nop 1
	v_mov_b64_e32 v[16:17], v[200:201]
	v_mov_b64_e32 v[18:19], v[202:203]
	ds_bpermute_b32 v20, v110, v117
	v_lshl_add_u64 v[24:25], v[74:75], 0, s[30:31]
	s_waitcnt lgkmcnt(0)
	v_add_f32_e32 v20, v117, v20
	ds_bpermute_b32 v21, v111, v20
	s_waitcnt lgkmcnt(0)
	v_add_f32_e32 v20, v20, v21
	ds_bpermute_b32 v21, v112, v20
	s_waitcnt lgkmcnt(0)
	v_add_f32_e32 v20, v20, v21
	ds_bpermute_b32 v21, v113, v20
	s_waitcnt lgkmcnt(0)
	v_add_f32_e32 v20, v20, v21
	ds_bpermute_b32 v21, v114, v20
	s_waitcnt lgkmcnt(0)
	v_add_f32_e32 v22, v20, v21
	ds_bpermute_b32 v23, v115, v22
	v_lshlrev_b32_e32 v20, 16, v86
	v_and_b32_e32 v21, 0xffff0000, v86
	s_waitcnt lgkmcnt(0)
	v_add_f32_e32 v22, v22, v23
	v_fmamk_f32 v22, v22, 0x3a800000, v116
	v_mul_f32_e32 v23, 0x4b800000, v22
	v_cmp_gt_f32_e32 vcc, s42, v22
	s_nop 1
	v_cndmask_b32_e32 v22, v22, v23, vcc
	v_rsq_f32_e32 v26, v22
	v_lshlrev_b32_e32 v22, 16, v87
	v_and_b32_e32 v23, 0xffff0000, v87
	v_mul_f32_e32 v27, 0x45800000, v26
	v_cndmask_b32_e32 v26, v26, v27, vcc
	v_mul_f32_e32 v26, 0.5, v26
	v_pk_mul_f32 v[20:21], v[26:27], v[20:21] op_sel_hi:[0,1]
	v_pk_mul_f32 v[22:23], v[26:27], v[22:23] op_sel_hi:[0,1]
	s_nop 1
	v_pk_fma_f32 v[18:19], v[18:19], v[22:23], v[14:15]
	v_pk_fma_f32 v[16:17], v[16:17], v[20:21], v[12:13]
	v_cvt_pk_bf16_f32 v13, v18, v19
	v_cvt_pk_bf16_f32 v12, v16, v17
	global_store_dwordx2 v[24:25], v[12:13], off
	s_nop 1
	v_mov_b64_e32 v[12:13], v[204:205]
	v_mov_b64_e32 v[14:15], v[206:207]
	v_lshlrev_b32_e32 v20, 16, v84
	v_and_b32_e32 v21, 0xffff0000, v84
	v_lshlrev_b32_e32 v22, 16, v85
	v_and_b32_e32 v23, 0xffff0000, v85
	v_pk_mul_f32 v[20:21], v[26:27], v[20:21] op_sel_hi:[0,1]
	v_pk_mul_f32 v[22:23], v[26:27], v[22:23] op_sel_hi:[0,1]
	v_mul_f32_e32 v17, v17, v17
	v_mul_f32_e32 v19, v19, v19
	v_fmac_f32_e32 v17, v16, v16
	v_fmac_f32_e32 v19, v18, v18
	v_add_f32_e32 v16, v17, v19
	s_nop 1
	v_pk_fma_f32 v[14:15], v[14:15], v[22:23], v[10:11]
	v_pk_fma_f32 v[12:13], v[12:13], v[20:21], v[8:9]
	v_cvt_pk_bf16_f32 v9, v14, v15
	v_cvt_pk_bf16_f32 v8, v12, v13
	global_store_dwordx2 v[24:25], v[8:9], off offset:512
	s_nop 1
	v_mov_b64_e32 v[8:9], v[208:209]
	v_mov_b64_e32 v[10:11], v[210:211]
	v_lshlrev_b32_e32 v20, 16, v82
	v_and_b32_e32 v21, 0xffff0000, v82
	v_lshlrev_b32_e32 v22, 16, v83
	v_and_b32_e32 v23, 0xffff0000, v83
	v_pk_mul_f32 v[20:21], v[26:27], v[20:21] op_sel_hi:[0,1]
	v_pk_mul_f32 v[22:23], v[26:27], v[22:23] op_sel_hi:[0,1]
	v_mul_f32_e32 v13, v13, v13
	v_mul_f32_e32 v15, v15, v15
	v_fmac_f32_e32 v13, v12, v12
	v_fmac_f32_e32 v15, v14, v14
	v_add_f32_e32 v12, v13, v15
	v_add_f32_e32 v12, v16, v12
	s_nop 1
	v_pk_fma_f32 v[10:11], v[10:11], v[22:23], v[6:7]
	v_pk_fma_f32 v[8:9], v[8:9], v[20:21], v[4:5]
	v_cvt_pk_bf16_f32 v5, v10, v11
	v_cvt_pk_bf16_f32 v4, v8, v9
	global_store_dwordx2 v[24:25], v[4:5], off offset:1024
	s_nop 1
	v_mov_b64_e32 v[4:5], v[212:213]
	v_mov_b64_e32 v[6:7], v[214:215]
	v_lshlrev_b32_e32 v20, 16, v80
	v_and_b32_e32 v21, 0xffff0000, v80
	v_lshlrev_b32_e32 v22, 16, v81
	v_and_b32_e32 v23, 0xffff0000, v81
	v_pk_mul_f32 v[20:21], v[26:27], v[20:21] op_sel_hi:[0,1]
	v_pk_mul_f32 v[22:23], v[26:27], v[22:23] op_sel_hi:[0,1]
	v_mul_f32_e32 v9, v9, v9
	v_mul_f32_e32 v11, v11, v11
	v_fmac_f32_e32 v9, v8, v8
	v_fmac_f32_e32 v11, v10, v10
	v_add_f32_e32 v8, v9, v11
	v_add_f32_e32 v8, v8, v12
	s_nop 1
	v_pk_fma_f32 v[2:3], v[6:7], v[22:23], v[2:3]
	v_pk_fma_f32 v[4:5], v[4:5], v[20:21], v[0:1]
	v_mul_f32_e32 v1, v3, v3
	v_mul_f32_e32 v0, v5, v5
	v_fmac_f32_e32 v0, v4, v4
	v_fmac_f32_e32 v1, v2, v2
	v_add_f32_e32 v0, v0, v1
	v_add_f32_e32 v0, v0, v8
	ds_bpermute_b32 v1, v110, v0
	v_cvt_pk_bf16_f32 v4, v4, v5
	v_cvt_pk_bf16_f32 v5, v2, v3
	global_store_dwordx2 v[24:25], v[4:5], off offset:1536
	s_waitcnt lgkmcnt(0)
	v_add_f32_e32 v0, v0, v1
	ds_bpermute_b32 v1, v111, v0
	s_waitcnt lgkmcnt(0)
	v_add_f32_e32 v0, v0, v1
	ds_bpermute_b32 v1, v112, v0
	s_waitcnt lgkmcnt(0)
	v_add_f32_e32 v0, v0, v1
	ds_bpermute_b32 v1, v113, v0
	s_waitcnt lgkmcnt(0)
	v_add_f32_e32 v0, v0, v1
	ds_bpermute_b32 v1, v114, v0
	s_waitcnt lgkmcnt(0)
	v_add_f32_e32 v0, v0, v1
	ds_bpermute_b32 v1, v115, v0
	s_and_saveexec_b64 s[28:29], s[2:3]
	s_cbranch_execz .LBB0_446
	s_waitcnt lgkmcnt(0)
	v_add_f32_e32 v0, v0, v1
	v_fmamk_f32 v0, v0, 0x3a800000, v116
	v_mul_f32_e32 v1, 0x4b800000, v0
	v_cmp_gt_f32_e32 vcc, s42, v0
	s_lshl_b64 s[26:27], s[26:27], 2
	s_add_u32 s26, s4, s26
	v_cndmask_b32_e32 v0, v0, v1, vcc
	v_rsq_f32_e32 v0, v0
	s_addc_u32 s27, s5, s27
	v_mul_f32_e32 v1, 0x45800000, v0
	v_cndmask_b32_e32 v0, v0, v1, vcc
	global_store_dword v65, v0, s[26:27]
	s_branch .LBB0_446

; #define LAS __attribute__((address_space(3)))
; #define MFMA32(a, b, c) __builtin_amdgcn_mfma_f32_32x32x16_bf16((a), (b), (c), 0, 0, 0)
; DI unsigned pk2(float lo, float hi) { f32x2_t v = {lo, hi}; bf16x2_t b = __builtin_convertvector(v, bf16x2_t); return __builtin_bit_cast(unsigned, b); }
; DI void attn_tile(bool MASK, const LAS unsigned char* Ks, const LAS unsigned char* Vs, const bf16x8 (&qr)[6], f32x16& negm, float& mrun, float& lrun, f32x16& o0, f32x16& o1,
;                                        int kv0, int qrow, int r32, int hi) {
;     ...
;     float ls = 0.f;
; #pragma unroll
;     for (int r = 0; r < 16; ++r) { p0[r] = __builtin_amdgcn_exp2f(p0[r]); p1[r] = __builtin_amdgcn_exp2f(p1[r]); ls += p0[r] + p1[r]; }
;     lrun += ls;
; #pragma unroll
;     for (int ks = 0; ks < 4; ++ks) {
;         u32x4 pp;
;         if (ks == 0) { pp.x = pk2(p0[0], p0[1]); pp.y = pk2(p0[2], p0[3]); pp.z = pk2(p0[4], p0[5]); pp.w = pk2(p0[6], p0[7]); }
;         else if (ks == 1) { pp.x = pk2(p0[8], p0[9]); pp.y = pk2(p0[10], p0[11]); pp.z = pk2(p0[12], p0[13]); pp.w = pk2(p0[14], p0[15]); }
;         else if (ks == 2) { pp.x = pk2(p1[0], p1[1]); pp.y = pk2(p1[2], p1[3]); pp.z = pk2(p1[4], p1[5]); pp.w = pk2(p1[6], p1[7]); }
;         else { pp.x = pk2(p1[8], p1[9]); pp.y = pk2(p1[10], p1[11]); pp.z = pk2(p1[12], p1[13]); pp.w = pk2(p1[14], p1[15]); }
;         const bf16x8 pa = __builtin_bit_cast(bf16x8, pp);
;         const LAS unsigned char* vp = Vs + r32 * 136 + (16 * ks + 4 * hi) * 2;
;         const u32x2 l0 = *(const LAS u32x2*)vp, h0 = *(const LAS u32x2*)(vp + 16);
;         const u32x2 l1 = *(const LAS u32x2*)(vp + 32 * 136), h1 = *(const LAS u32x2*)(vp + 32 * 136 + 16);
;         u32x4 v0 = {l0.x, l0.y, h0.x, h0.y}, v1 = {l1.x, l1.y, h1.x, h1.y};
;         o0 = MFMA32(__builtin_bit_cast(bf16x8, v0), pa, o0);
;         o1 = MFMA32(__builtin_bit_cast(bf16x8, v1), pa, o1);
;     }
.LBB0_847:
	v_exp_f32_e32 v3, v82
	v_exp_f32_e32 v159, v66
	v_exp_f32_e32 v0, v83
	v_exp_f32_e32 v66, v67
	v_exp_f32_e32 v9, v84
	v_add_f32_e32 v67, v159, v3
	v_cvt_pk_bf16_f32 v8, v3, v0
	v_pk_add_f32 v[4:5], v[66:67], v[0:1]
	v_exp_f32_e32 v67, v68
	v_pk_add_f32 v[10:11], v[4:5], v[4:5] op_sel_hi:[0,1]
	v_exp_f32_e32 v10, v85
	v_exp_f32_e32 v68, v69
	v_add_f32_e32 v69, v67, v9
	v_exp_f32_e32 v3, v96
	v_cvt_pk_bf16_f32 v9, v9, v10
	v_pk_add_f32 v[4:5], v[68:69], v[10:11]
	v_exp_f32_e32 v11, v86
	v_pk_add_f32 v[12:13], v[4:5], v[4:5] op_sel_hi:[0,1]
	v_exp_f32_e32 v69, v70
	v_exp_f32_e32 v12, v87
	v_exp_f32_e32 v70, v71
	v_add_f32_e32 v71, v69, v11
	v_cvt_pk_bf16_f32 v10, v11, v12
	v_pk_add_f32 v[4:5], v[70:71], v[12:13]
	v_exp_f32_e32 v13, v88
	v_pk_add_f32 v[14:15], v[4:5], v[4:5] op_sel_hi:[0,1]
	v_exp_f32_e32 v71, v72
	v_exp_f32_e32 v14, v89
	v_exp_f32_e32 v72, v73
	v_add_f32_e32 v73, v71, v13
	v_cvt_pk_bf16_f32 v11, v13, v14
	v_pk_add_f32 v[4:5], v[72:73], v[14:15]
	v_exp_f32_e32 v73, v90
	v_pk_add_f32 v[82:83], v[4:5], v[4:5] op_sel_hi:[0,1]
	v_exp_f32_e32 v90, v74
	v_exp_f32_e32 v82, v91
	v_exp_f32_e32 v74, v75
	v_add_u32_e32 v15, v205, v208
	v_add_f32_e32 v75, v90, v73
	v_add_u32_e32 v0, 0xf000, v15
	v_pk_add_f32 v[4:5], v[74:75], v[82:83]
	v_exp_f32_e32 v75, v92
	v_pk_add_f32 v[84:85], v[4:5], v[4:5] op_sel_hi:[0,1]
	v_exp_f32_e32 v83, v76
	v_exp_f32_e32 v84, v93
	v_exp_f32_e32 v76, v77
	v_exp_f32_e32 v91, v78
	v_add_f32_e32 v77, v83, v75
	v_exp_f32_e32 v78, v79
	v_pk_add_f32 v[4:5], v[76:77], v[84:85]
	v_add_u32_e32 v77, 0xe000, v15
	v_pk_add_f32 v[86:87], v[4:5], v[4:5] op_sel_hi:[0,1]
	v_exp_f32_e32 v85, v94
	v_exp_f32_e32 v86, v95
	s_waitcnt lgkmcnt(0)
	v_mfma_f32_32x32x16_bf16 v[32:47], v[214:217], v[8:11], v[32:47]
	v_add_f32_e32 v79, v91, v85
	v_add_f32_e64 v88, v78, v86
	v_add_f32_e64 v89, v79, v87
	s_nop 0
	v_mfma_f32_32x32x16_bf16 v[16:31], v[218:221], v[8:11], v[16:31]
	v_add_f32_e64 v12, v88, v88
	v_add_f32_e64 v13, v88, v89
	v_exp_f32_e32 v12, v97
	v_cvt_pk_bf16_f32 v8, v73, v82
	v_cvt_pk_bf16_f32 v9, v75, v84
	v_cvt_pk_bf16_f32 v10, v85, v86
	v_cvt_pk_bf16_f32 v11, v3, v12
	v_exp_f32_e32 v15, v80
	v_exp_f32_e32 v14, v81
	s_nop 0
	v_mfma_f32_32x32x16_bf16 v[32:47], v[222:225], v[8:11], v[32:47]
	s_nop 0
	v_mfma_f32_32x32x16_bf16 v[16:31], v[226:229], v[8:11], v[16:31]
	v_cvt_pk_bf16_f32 v8, v159, v66
	v_cvt_pk_bf16_f32 v9, v67, v68
	v_cvt_pk_bf16_f32 v10, v69, v70
	v_cvt_pk_bf16_f32 v11, v71, v72
	s_nop 0
	s_nop 0
	v_mfma_f32_32x32x16_bf16 v[32:47], v[230:233], v[8:11], v[32:47]
	s_nop 0
	v_mfma_f32_32x32x16_bf16 v[16:31], v[234:237], v[8:11], v[16:31]
	v_cvt_pk_bf16_f32 v8, v90, v74
	v_cvt_pk_bf16_f32 v9, v83, v76
	v_cvt_pk_bf16_f32 v10, v91, v78
	v_cvt_pk_bf16_f32 v11, v15, v14
	v_add_f32_e32 v15, v15, v3
	v_pk_add_f32 v[12:13], v[14:15], v[12:13]
	s_nop 0
	v_mfma_f32_32x32x16_bf16 v[32:47], v[238:241], v[8:11], v[32:47]
	v_add_f32_e32 v0, v12, v13
	v_add_f32_e32 v48, v48, v0
	s_nop 0
	v_mfma_f32_32x32x16_bf16 v[16:31], v[242:245], v[8:11], v[16:31]

; #define LAS __attribute__((address_space(3)))
; #define MFMA32(a, b, c) __builtin_amdgcn_mfma_f32_32x32x16_bf16((a), (b), (c), 0, 0, 0)
; DI int crow(int r, int hi) { return (r & 3) + 8 * (r >> 2) + 4 * hi; }
; DI void attn_tile(bool MASK, const LAS unsigned char* Ks, const LAS unsigned char* Vs, const bf16x8 (&qr)[6], f32x16& negm, float& mrun, float& lrun, f32x16& o0, f32x16& o1,
;                                        int kv0, int qrow, int r32, int hi) {
;     f32x16 p0, p1;
;     __builtin_amdgcn_s_setprio(1);
;     {
;         const bf16x8 a0 = *(const LAS bf16x8*)(Ks + r32 * 208 + hi * 16);
;         const bf16x8 a1 = *(const LAS bf16x8*)(Ks + (32 + r32) * 208 + hi * 16);
;         p0 = MFMA32(a0, qr[0], negm); p1 = MFMA32(a1, qr[0], negm);
;     }
; #pragma unroll
;     for (int d0 = 1; d0 < 6; ++d0) {
;         const bf16x8 a0 = *(const LAS bf16x8*)(Ks + r32 * 208 + (2 * d0 + hi) * 16);
;         const bf16x8 a1 = *(const LAS bf16x8*)(Ks + (32 + r32) * 208 + (2 * d0 + hi) * 16);
;         p0 = MFMA32(a0, qr[d0], p0); p1 = MFMA32(a1, qr[d0], p1);
;     }
;     __builtin_amdgcn_s_setprio(0);
;     if (MASK) {
;         asm volatile("" ::: "memory");
; #pragma unroll
;         for (int r = 0; r < 16; ++r) { const int kv = kv0 + crow(r, hi); if (kv > qrow) p0[r] = -INFINITY; if (kv + 32 > qrow) p1[r] = -INFINITY; }
.LBB0_849:
	s_add_i32 s33, s23, 4
	s_min_i32 s33, s33, s20
	v_mad_i64_i32 v[4:5], s[34:35], s33, v161, v[190:191]
	v_mad_i64_i32 v[6:7], s[34:35], s33, v161, v[194:195]
	v_add3_u32 v0, v204, v199, s29
	s_lshl_b32 s34, s33, 6
	s_waitcnt lgkmcnt(0)
	s_barrier
	s_waitcnt vmcnt(3)
	ds_write_b128 v209, v[130:133] offset:22016
	ds_write_b128 v210, v[106:109] offset:22016
	ds_write2_b64 v0, v[110:111], v[112:113] offset1:1
	s_ashr_i32 s35, s34, 31
	global_load_dwordx4 v[130:133], v[4:5], off
	global_load_dwordx4 v[106:109], v[6:7], off
	v_lshl_add_u64 v[4:5], s[34:35], 1, v[192:193]
	global_load_dwordx4 v[110:113], v[4:5], off
	s_cmp_gt_i32 s21, s22
	s_cbranch_scc1 .LBB0_855
	s_cmp_lt_i32 s23, s12
	s_setprio 1
	v_add_u32_e32 v0, v206, v160
	ds_read_b128 v[4:7], v0
	ds_read_b128 v[8:11], v0 offset:6656
	ds_read_b128 v[12:15], v0 offset:32
	ds_read_b128 v[214:217], v0 offset:6688
	ds_read_b128 v[218:221], v0 offset:64
	ds_read_b128 v[222:225], v0 offset:6720
	ds_read_b128 v[226:229], v0 offset:96
	ds_read_b128 v[230:233], v0 offset:6752
	s_waitcnt lgkmcnt(7)
	v_mfma_f32_32x32x16_bf16 v[82:97], v[4:7], v[154:157], v[50:65]
	ds_read_b128 v[234:237], v0 offset:128
	s_waitcnt lgkmcnt(7)
	v_mfma_f32_32x32x16_bf16 v[66:81], v[8:11], v[154:157], v[50:65]
	ds_read_b128 v[238:241], v0 offset:6784
	s_waitcnt lgkmcnt(7)
	v_mfma_f32_32x32x16_bf16 v[82:97], v[12:15], v[150:153], v[82:97]
	ds_read_b128 v[242:245], v0 offset:160
	s_waitcnt lgkmcnt(7)
	v_mfma_f32_32x32x16_bf16 v[66:81], v[214:217], v[150:153], v[66:81]
	ds_read_b128 v[246:249], v0 offset:6816
	s_waitcnt lgkmcnt(7)
	v_mfma_f32_32x32x16_bf16 v[82:97], v[218:221], v[146:149], v[82:97]
	s_waitcnt lgkmcnt(6)
	v_mfma_f32_32x32x16_bf16 v[66:81], v[222:225], v[146:149], v[66:81]
	s_waitcnt lgkmcnt(5)
	v_mfma_f32_32x32x16_bf16 v[82:97], v[226:229], v[126:129], v[82:97]
	s_waitcnt lgkmcnt(4)
	v_mfma_f32_32x32x16_bf16 v[66:81], v[230:233], v[126:129], v[66:81]
	s_waitcnt lgkmcnt(3)
	v_mfma_f32_32x32x16_bf16 v[82:97], v[234:237], v[122:125], v[82:97]
	s_waitcnt lgkmcnt(2)
	v_mfma_f32_32x32x16_bf16 v[66:81], v[238:241], v[122:125], v[66:81]
	s_waitcnt lgkmcnt(1)
	v_mfma_f32_32x32x16_bf16 v[82:97], v[242:245], v[118:121], v[82:97]
	s_waitcnt lgkmcnt(0)
	v_mfma_f32_32x32x16_bf16 v[66:81], v[246:249], v[118:121], v[66:81]
	s_setprio 0
	v_add_u32_e32 v3, v205, v208
	v_add_u32_e32 v0, 0x4000, v3
	v_add_u32_e32 v3, 0x3000, v3
	ds_read2_b64 v[214:217], v3 offset0:128 offset1:130
	ds_read2_b64 v[218:221], v0 offset0:160 offset1:162
	ds_read2_b64 v[222:225], v3 offset0:132 offset1:134
	ds_read2_b64 v[226:229], v0 offset0:164 offset1:166
	ds_read2_b64 v[230:233], v3 offset0:136 offset1:138
	ds_read2_b64 v[234:237], v0 offset0:168 offset1:170
	ds_read2_b64 v[238:241], v3 offset0:140 offset1:142
	ds_read2_b64 v[242:245], v0 offset0:172 offset1:174
	s_cbranch_scc1 .LBB0_852
	v_add_u32_e32 v0, s21, v207
	v_add_u32_e32 v3, 32, v0
	v_cmp_le_i32_e32 vcc, v3, v49
	v_add_u32_e32 v3, 33, v0
	s_nop 5
	v_cndmask_b32_e32 v66, v212, v66, vcc
	v_cmp_lt_i32_e32 vcc, v0, v49
	s_nop 1
	v_cndmask_b32_e32 v83, v212, v83, vcc
	v_cmp_le_i32_e32 vcc, v0, v49
	s_nop 1
	v_cndmask_b32_e32 v82, v212, v82, vcc
	v_cmp_le_i32_e32 vcc, v3, v49
	v_add_u32_e32 v3, 2, v0
	s_nop 0
	v_cndmask_b32_e32 v67, v212, v67, vcc
	v_cmp_le_i32_e32 vcc, v3, v49
	v_add_u32_e32 v3, 34, v0
	s_nop 0
	v_cndmask_b32_e32 v84, v212, v84, vcc
	v_cmp_le_i32_e32 vcc, v3, v49
	v_add_u32_e32 v3, 3, v0
	s_nop 0
	v_cndmask_b32_e32 v68, v212, v68, vcc
	v_cmp_le_i32_e32 vcc, v3, v49
	v_add_u32_e32 v3, 35, v0
	s_nop 0
	v_cndmask_b32_e32 v85, v212, v85, vcc
	v_cmp_le_i32_e32 vcc, v3, v49
	v_add_u32_e32 v3, 8, v0
	s_nop 0
	v_cndmask_b32_e32 v69, v212, v69, vcc
	v_cmp_le_i32_e32 vcc, v3, v49
	v_add_u32_e32 v3, 40, v0
	s_nop 0
	v_cndmask_b32_e32 v86, v212, v86, vcc
	v_cmp_le_i32_e32 vcc, v3, v49
	v_add_u32_e32 v3, 9, v0
	s_nop 0
	v_cndmask_b32_e32 v70, v212, v70, vcc
	v_cmp_le_i32_e32 vcc, v3, v49
	v_add_u32_e32 v3, 41, v0
	s_nop 0
	v_cndmask_b32_e32 v87, v212, v87, vcc
	v_cmp_le_i32_e32 vcc, v3, v49
	v_add_u32_e32 v3, 10, v0
	s_nop 0
	v_cndmask_b32_e32 v71, v212, v71, vcc
	v_cmp_le_i32_e32 vcc, v3, v49
	v_add_u32_e32 v3, 42, v0
	s_nop 0
	v_cndmask_b32_e32 v88, v212, v88, vcc
	v_cmp_le_i32_e32 vcc, v3, v49
	v_add_u32_e32 v3, 11, v0
	s_nop 0
	v_cndmask_b32_e32 v72, v212, v72, vcc
	v_cmp_le_i32_e32 vcc, v3, v49
	v_add_u32_e32 v3, 43, v0
	s_nop 0
	v_cndmask_b32_e32 v89, v212, v89, vcc
	v_cmp_le_i32_e32 vcc, v3, v49
	v_add_u32_e32 v3, 16, v0
	s_nop 0
	v_cndmask_b32_e32 v73, v212, v73, vcc
	v_cmp_le_i32_e32 vcc, v3, v49
	v_add_u32_e32 v3, 48, v0
	s_nop 0
	v_cndmask_b32_e32 v90, v212, v90, vcc
	v_cmp_le_i32_e32 vcc, v3, v49
	v_add_u32_e32 v3, 17, v0
	s_nop 0
	v_cndmask_b32_e32 v74, v212, v74, vcc
	v_cmp_le_i32_e32 vcc, v3, v49
	v_add_u32_e32 v3, 49, v0
	s_nop 0
	v_cndmask_b32_e32 v91, v212, v91, vcc
	v_cmp_le_i32_e32 vcc, v3, v49
	v_add_u32_e32 v3, 18, v0
	s_nop 0
	v_cndmask_b32_e32 v75, v212, v75, vcc
	v_cmp_le_i32_e32 vcc, v3, v49
	v_add_u32_e32 v3, 50, v0
	s_nop 0
	v_cndmask_b32_e32 v92, v212, v92, vcc
	v_cmp_le_i32_e32 vcc, v3, v49
	v_add_u32_e32 v3, 19, v0
	s_nop 0
	v_cndmask_b32_e32 v76, v212, v76, vcc
	v_cmp_le_i32_e32 vcc, v3, v49
	v_add_u32_e32 v3, 51, v0
	s_nop 0
	v_cndmask_b32_e32 v93, v212, v93, vcc
	v_cmp_le_i32_e32 vcc, v3, v49
	v_add_u32_e32 v3, 24, v0
	s_nop 0
	v_cndmask_b32_e32 v77, v212, v77, vcc
	v_cmp_le_i32_e32 vcc, v3, v49
	v_add_u32_e32 v3, 56, v0
	s_nop 0
	v_cndmask_b32_e32 v94, v212, v94, vcc
	v_cmp_le_i32_e32 vcc, v3, v49
	v_add_u32_e32 v3, 25, v0
	s_nop 0
	v_cndmask_b32_e32 v78, v212, v78, vcc
	v_cmp_le_i32_e32 vcc, v3, v49
	v_add_u32_e32 v3, 57, v0
	s_nop 0
	v_cndmask_b32_e32 v95, v212, v95, vcc
	v_cmp_le_i32_e32 vcc, v3, v49
	v_add_u32_e32 v3, 26, v0
	s_nop 0
	v_cndmask_b32_e32 v79, v212, v79, vcc
	v_cmp_le_i32_e32 vcc, v3, v49
	v_add_u32_e32 v3, 58, v0
	s_nop 0
	v_cndmask_b32_e32 v96, v212, v96, vcc
	v_cmp_le_i32_e32 vcc, v3, v49
	v_add_u32_e32 v3, 27, v0
	v_add_u32_e32 v0, 59, v0
	v_cndmask_b32_e32 v80, v212, v80, vcc
	v_cmp_le_i32_e32 vcc, v3, v49
	s_nop 1
	v_cndmask_b32_e32 v97, v212, v97, vcc
	v_cmp_le_i32_e32 vcc, v0, v49
	s_nop 1
	v_cndmask_b32_e32 v81, v212, v81, vcc

; #define LAS __attribute__((address_space(3)))
; #define MFMA32(a, b, c) __builtin_amdgcn_mfma_f32_32x32x16_bf16((a), (b), (c), 0, 0, 0)
; DI unsigned pk2(float lo, float hi) { f32x2_t v = {lo, hi}; bf16x2_t b = __builtin_convertvector(v, bf16x2_t); return __builtin_bit_cast(unsigned, b); }
; DI void attn_tile(bool MASK, const LAS unsigned char* Ks, const LAS unsigned char* Vs, const bf16x8 (&qr)[6], f32x16& negm, float& mrun, float& lrun, f32x16& o0, f32x16& o1,
;                                        int kv0, int qrow, int r32, int hi) {
;     ...
;     float ls = 0.f;
; #pragma unroll
;     for (int r = 0; r < 16; ++r) { p0[r] = __builtin_amdgcn_exp2f(p0[r]); p1[r] = __builtin_amdgcn_exp2f(p1[r]); ls += p0[r] + p1[r]; }
;     lrun += ls;
; #pragma unroll
;     for (int ks = 0; ks < 4; ++ks) {
;         u32x4 pp;
;         if (ks == 0) { pp.x = pk2(p0[0], p0[1]); pp.y = pk2(p0[2], p0[3]); pp.z = pk2(p0[4], p0[5]); pp.w = pk2(p0[6], p0[7]); }
;         else if (ks == 1) { pp.x = pk2(p0[8], p0[9]); pp.y = pk2(p0[10], p0[11]); pp.z = pk2(p0[12], p0[13]); pp.w = pk2(p0[14], p0[15]); }
;         else if (ks == 2) { pp.x = pk2(p1[0], p1[1]); pp.y = pk2(p1[2], p1[3]); pp.z = pk2(p1[4], p1[5]); pp.w = pk2(p1[6], p1[7]); }
;         else { pp.x = pk2(p1[8], p1[9]); pp.y = pk2(p1[10], p1[11]); pp.z = pk2(p1[12], p1[13]); pp.w = pk2(p1[14], p1[15]); }
;         const bf16x8 pa = __builtin_bit_cast(bf16x8, pp);
;         const LAS unsigned char* vp = Vs + r32 * 136 + (16 * ks + 4 * hi) * 2;
;         const u32x2 l0 = *(const LAS u32x2*)vp, h0 = *(const LAS u32x2*)(vp + 16);
;         const u32x2 l1 = *(const LAS u32x2*)(vp + 32 * 136), h1 = *(const LAS u32x2*)(vp + 32 * 136 + 16);
;         u32x4 v0 = {l0.x, l0.y, h0.x, h0.y}, v1 = {l1.x, l1.y, h1.x, h1.y};
;         o0 = MFMA32(__builtin_bit_cast(bf16x8, v0), pa, o0);
;         o1 = MFMA32(__builtin_bit_cast(bf16x8, v1), pa, o1);
;     }
.LBB0_854:
	v_exp_f32_e32 v3, v82
	v_exp_f32_e32 v159, v66
	v_exp_f32_e32 v0, v83
	v_exp_f32_e32 v66, v67
	v_exp_f32_e32 v9, v84
	v_add_f32_e32 v67, v159, v3
	v_cvt_pk_bf16_f32 v8, v3, v0
	v_pk_add_f32 v[4:5], v[66:67], v[0:1]
	v_exp_f32_e32 v67, v68
	v_pk_add_f32 v[10:11], v[4:5], v[4:5] op_sel_hi:[0,1]
	v_exp_f32_e32 v10, v85
	v_exp_f32_e32 v68, v69
	v_add_f32_e32 v69, v67, v9
	v_exp_f32_e32 v3, v96
	v_cvt_pk_bf16_f32 v9, v9, v10
	v_pk_add_f32 v[4:5], v[68:69], v[10:11]
	v_exp_f32_e32 v11, v86
	v_pk_add_f32 v[12:13], v[4:5], v[4:5] op_sel_hi:[0,1]
	v_exp_f32_e32 v69, v70
	v_exp_f32_e32 v12, v87
	v_exp_f32_e32 v70, v71
	v_add_f32_e32 v71, v69, v11
	v_cvt_pk_bf16_f32 v10, v11, v12
	v_pk_add_f32 v[4:5], v[70:71], v[12:13]
	v_exp_f32_e32 v13, v88
	v_pk_add_f32 v[14:15], v[4:5], v[4:5] op_sel_hi:[0,1]
	v_exp_f32_e32 v71, v72
	v_exp_f32_e32 v14, v89
	v_exp_f32_e32 v72, v73
	v_add_f32_e32 v73, v71, v13
	v_cvt_pk_bf16_f32 v11, v13, v14
	v_pk_add_f32 v[4:5], v[72:73], v[14:15]
	v_exp_f32_e32 v73, v90
	v_pk_add_f32 v[82:83], v[4:5], v[4:5] op_sel_hi:[0,1]
	v_exp_f32_e32 v90, v74
	v_exp_f32_e32 v82, v91
	v_exp_f32_e32 v74, v75
	v_add_u32_e32 v15, v205, v208
	v_add_f32_e32 v75, v90, v73
	v_add_u32_e32 v0, 0x4000, v15
	v_pk_add_f32 v[4:5], v[74:75], v[82:83]
	v_exp_f32_e32 v75, v92
	v_pk_add_f32 v[84:85], v[4:5], v[4:5] op_sel_hi:[0,1]
	v_exp_f32_e32 v83, v76
	v_exp_f32_e32 v84, v93
	v_exp_f32_e32 v76, v77
	v_exp_f32_e32 v91, v78
	v_add_f32_e32 v77, v83, v75
	v_exp_f32_e32 v78, v79
	v_pk_add_f32 v[4:5], v[76:77], v[84:85]
	v_add_u32_e32 v77, 0x3000, v15
	v_pk_add_f32 v[86:87], v[4:5], v[4:5] op_sel_hi:[0,1]
	v_exp_f32_e32 v85, v94
	v_exp_f32_e32 v86, v95
	s_waitcnt lgkmcnt(0)
	v_mfma_f32_32x32x16_bf16 v[32:47], v[214:217], v[8:11], v[32:47]
	v_add_f32_e32 v79, v91, v85
	v_add_f32_e64 v88, v78, v86
	v_add_f32_e64 v89, v79, v87
	s_nop 0
	v_mfma_f32_32x32x16_bf16 v[16:31], v[218:221], v[8:11], v[16:31]
	v_add_f32_e64 v12, v88, v88
	v_add_f32_e64 v13, v88, v89
	v_exp_f32_e32 v12, v97
	v_cvt_pk_bf16_f32 v8, v73, v82
	v_cvt_pk_bf16_f32 v9, v75, v84
	v_cvt_pk_bf16_f32 v10, v85, v86
	v_cvt_pk_bf16_f32 v11, v3, v12
	v_exp_f32_e32 v15, v80
	v_exp_f32_e32 v14, v81
	s_nop 0
	v_mfma_f32_32x32x16_bf16 v[32:47], v[222:225], v[8:11], v[32:47]
	s_nop 0
	v_mfma_f32_32x32x16_bf16 v[16:31], v[226:229], v[8:11], v[16:31]
	v_cvt_pk_bf16_f32 v8, v159, v66
	v_cvt_pk_bf16_f32 v9, v67, v68
	v_cvt_pk_bf16_f32 v10, v69, v70
	v_cvt_pk_bf16_f32 v11, v71, v72
	s_nop 0
	s_nop 0
	v_mfma_f32_32x32x16_bf16 v[32:47], v[230:233], v[8:11], v[32:47]
	s_nop 0
	v_mfma_f32_32x32x16_bf16 v[16:31], v[234:237], v[8:11], v[16:31]
	v_cvt_pk_bf16_f32 v8, v90, v74
	v_cvt_pk_bf16_f32 v9, v83, v76
	v_cvt_pk_bf16_f32 v10, v91, v78
	v_cvt_pk_bf16_f32 v11, v15, v14
	v_add_f32_e32 v15, v15, v3
	v_pk_add_f32 v[12:13], v[14:15], v[12:13]
	s_nop 0
	v_mfma_f32_32x32x16_bf16 v[32:47], v[238:241], v[8:11], v[32:47]
	v_add_f32_e32 v0, v12, v13
	v_add_f32_e32 v48, v48, v0
	s_nop 0
	v_mfma_f32_32x32x16_bf16 v[16:31], v[242:245], v[8:11], v[16:31]
; #define LAS __attribute__((address_space(3)))
; #define MFMA32(a, b, c) __builtin_amdgcn_mfma_f32_32x32x16_bf16((a), (b), (c), 0, 0, 0)
; DI int crow(int r, int hi) { return (r & 3) + 8 * (r >> 2) + 4 * hi; }
; DI void attn_tile(bool MASK, const LAS unsigned char* Ks, const LAS unsigned char* Vs, const bf16x8 (&qr)[6], f32x16& negm, float& mrun, float& lrun, f32x16& o0, f32x16& o1,
;                                        int kv0, int qrow, int r32, int hi) {
;     f32x16 p0, p1;
;     __builtin_amdgcn_s_setprio(1);
;     {
;         const bf16x8 a0 = *(const LAS bf16x8*)(Ks + r32 * 208 + hi * 16);
;         const bf16x8 a1 = *(const LAS bf16x8*)(Ks + (32 + r32) * 208 + hi * 16);
;         p0 = MFMA32(a0, qr[0], negm); p1 = MFMA32(a1, qr[0], negm);
;     }
; #pragma unroll
;     for (int d0 = 1; d0 < 6; ++d0) {
;         const bf16x8 a0 = *(const LAS bf16x8*)(Ks + r32 * 208 + (2 * d0 + hi) * 16);
;         const bf16x8 a1 = *(const LAS bf16x8*)(Ks + (32 + r32) * 208 + (2 * d0 + hi) * 16);
;         p0 = MFMA32(a0, qr[d0], p0); p1 = MFMA32(a1, qr[d0], p1);
;     }
;     __builtin_amdgcn_s_setprio(0);
;     if (MASK) {
;         asm volatile("" ::: "memory");
; #pragma unroll
;         for (int r = 0; r < 16; ++r) { const int kv = kv0 + crow(r, hi); if (kv > qrow) p0[r] = -INFINITY; if (kv + 32 > qrow) p1[r] = -INFINITY; }
.LBB0_855:
	s_add_i32 s33, s23, 5
	s_min_i32 s33, s33, s20
	v_mad_i64_i32 v[4:5], s[34:35], s33, v161, v[190:191]
	v_mad_i64_i32 v[6:7], s[34:35], s33, v161, v[194:195]
	v_add3_u32 v0, v204, v199, s31
	s_lshl_b32 s34, s33, 6
	s_waitcnt lgkmcnt(0)
	s_barrier
	ds_write_b128 v209, v[98:101] offset:44032
	ds_write_b128 v210, v[102:105] offset:44032
	ds_write2_b64 v0, v[114:115], v[116:117] offset1:1
	s_ashr_i32 s35, s34, 31
	global_load_dwordx4 v[98:101], v[4:5], off
	global_load_dwordx4 v[102:105], v[6:7], off
	v_lshl_add_u64 v[4:5], s[34:35], 1, v[192:193]
	global_load_dwordx4 v[114:117], v[4:5], off
	s_add_i32 s33, s23, 1
	s_cmp_ge_i32 s33, s19
	s_cbranch_scc1 .LBB0_862
	s_add_i32 s34, s21, 64
	s_cmp_gt_i32 s34, s22
	s_cbranch_scc1 .LBB0_862
	s_cmp_lt_i32 s33, s12
	s_setprio 1
	v_add_u32_e32 v0, v206, v160
	ds_read_b128 v[4:7], v0 offset:22016
	ds_read_b128 v[8:11], v0 offset:28672
	ds_read_b128 v[12:15], v0 offset:22048
	ds_read_b128 v[214:217], v0 offset:28704
	ds_read_b128 v[218:221], v0 offset:22080
	ds_read_b128 v[222:225], v0 offset:28736
	ds_read_b128 v[226:229], v0 offset:22112
	ds_read_b128 v[230:233], v0 offset:28768
	s_waitcnt lgkmcnt(7)
	v_mfma_f32_32x32x16_bf16 v[82:97], v[4:7], v[154:157], v[50:65]
	ds_read_b128 v[234:237], v0 offset:22144
	s_waitcnt lgkmcnt(7)
	v_mfma_f32_32x32x16_bf16 v[66:81], v[8:11], v[154:157], v[50:65]
	ds_read_b128 v[238:241], v0 offset:28800
	s_waitcnt lgkmcnt(7)
	v_mfma_f32_32x32x16_bf16 v[82:97], v[12:15], v[150:153], v[82:97]
	ds_read_b128 v[242:245], v0 offset:22176
	s_waitcnt lgkmcnt(7)
	v_mfma_f32_32x32x16_bf16 v[66:81], v[214:217], v[150:153], v[66:81]
	ds_read_b128 v[246:249], v0 offset:28832
	s_waitcnt lgkmcnt(7)
	v_mfma_f32_32x32x16_bf16 v[82:97], v[218:221], v[146:149], v[82:97]
	s_waitcnt lgkmcnt(6)
	v_mfma_f32_32x32x16_bf16 v[66:81], v[222:225], v[146:149], v[66:81]
	s_waitcnt lgkmcnt(5)
	v_mfma_f32_32x32x16_bf16 v[82:97], v[226:229], v[126:129], v[82:97]
	s_waitcnt lgkmcnt(4)
	v_mfma_f32_32x32x16_bf16 v[66:81], v[230:233], v[126:129], v[66:81]
	s_waitcnt lgkmcnt(3)
	v_mfma_f32_32x32x16_bf16 v[82:97], v[234:237], v[122:125], v[82:97]
	s_waitcnt lgkmcnt(2)
	v_mfma_f32_32x32x16_bf16 v[66:81], v[238:241], v[122:125], v[66:81]
	s_waitcnt lgkmcnt(1)
	v_mfma_f32_32x32x16_bf16 v[82:97], v[242:245], v[118:121], v[82:97]
	s_waitcnt lgkmcnt(0)
	v_mfma_f32_32x32x16_bf16 v[66:81], v[246:249], v[118:121], v[66:81]
	s_setprio 0
	v_add_u32_e32 v3, v205, v208
	v_add_u32_e32 v0, 0x9800, v3
	v_add_u32_e32 v3, 0x8800, v3
	ds_read2_b64 v[214:217], v3 offset0:64 offset1:66
	ds_read2_b64 v[218:221], v0 offset0:96 offset1:98
	ds_read2_b64 v[222:225], v3 offset0:68 offset1:70
	ds_read2_b64 v[226:229], v0 offset0:100 offset1:102
	ds_read2_b64 v[230:233], v3 offset0:72 offset1:74
	ds_read2_b64 v[234:237], v0 offset0:104 offset1:106
	ds_read2_b64 v[238:241], v3 offset0:76 offset1:78
	ds_read2_b64 v[242:245], v0 offset0:108 offset1:110
	s_cbranch_scc1 .LBB0_859
	v_add_u32_e32 v0, s21, v207
	v_add_u32_e32 v4, 0x60, v0
	v_add_u32_e32 v3, 64, v0
	v_cmp_le_i32_e32 vcc, v4, v49
	s_nop 5
	v_cndmask_b32_e32 v66, v212, v66, vcc
	v_cmp_lt_i32_e32 vcc, v3, v49
	s_nop 1
	v_cndmask_b32_e32 v83, v212, v83, vcc
	v_cmp_le_i32_e32 vcc, v3, v49
	v_add_u32_e32 v3, 0x61, v0
	s_nop 0
	v_cndmask_b32_e32 v82, v212, v82, vcc
	v_cmp_le_i32_e32 vcc, v3, v49
	v_add_u32_e32 v3, 0x42, v0
	s_nop 0
	v_cndmask_b32_e32 v67, v212, v67, vcc
	v_cmp_le_i32_e32 vcc, v3, v49
	v_add_u32_e32 v3, 0x62, v0
	s_nop 0
	v_cndmask_b32_e32 v84, v212, v84, vcc
	v_cmp_le_i32_e32 vcc, v3, v49
	v_add_u32_e32 v3, 0x43, v0
	s_nop 0
	v_cndmask_b32_e32 v68, v212, v68, vcc
	v_cmp_le_i32_e32 vcc, v3, v49
	v_add_u32_e32 v3, 0x63, v0
	s_nop 0
	v_cndmask_b32_e32 v85, v212, v85, vcc
	v_cmp_le_i32_e32 vcc, v3, v49
	v_add_u32_e32 v3, 0x48, v0
	s_nop 0
	v_cndmask_b32_e32 v69, v212, v69, vcc
	v_cmp_le_i32_e32 vcc, v3, v49
	v_add_u32_e32 v3, 0x68, v0
	s_nop 0
	v_cndmask_b32_e32 v86, v212, v86, vcc
	v_cmp_le_i32_e32 vcc, v3, v49
	v_add_u32_e32 v3, 0x49, v0
	s_nop 0
	v_cndmask_b32_e32 v70, v212, v70, vcc
	v_cmp_le_i32_e32 vcc, v3, v49
	v_add_u32_e32 v3, 0x69, v0
	s_nop 0
	v_cndmask_b32_e32 v87, v212, v87, vcc
	v_cmp_le_i32_e32 vcc, v3, v49
	v_add_u32_e32 v3, 0x4a, v0
	s_nop 0
	v_cndmask_b32_e32 v71, v212, v71, vcc
	v_cmp_le_i32_e32 vcc, v3, v49
	v_add_u32_e32 v3, 0x6a, v0
	s_nop 0
	v_cndmask_b32_e32 v88, v212, v88, vcc
	v_cmp_le_i32_e32 vcc, v3, v49
	v_add_u32_e32 v3, 0x4b, v0
	s_nop 0
	v_cndmask_b32_e32 v72, v212, v72, vcc
	v_cmp_le_i32_e32 vcc, v3, v49
	v_add_u32_e32 v3, 0x6b, v0
	s_nop 0
	v_cndmask_b32_e32 v89, v212, v89, vcc
	v_cmp_le_i32_e32 vcc, v3, v49
	v_add_u32_e32 v3, 0x50, v0
	s_nop 0
	v_cndmask_b32_e32 v73, v212, v73, vcc
	v_cmp_le_i32_e32 vcc, v3, v49
	v_add_u32_e32 v3, 0x70, v0
	s_nop 0
	v_cndmask_b32_e32 v90, v212, v90, vcc
	v_cmp_le_i32_e32 vcc, v3, v49
	v_add_u32_e32 v3, 0x51, v0
	s_nop 0
	v_cndmask_b32_e32 v74, v212, v74, vcc
	v_cmp_le_i32_e32 vcc, v3, v49
	v_add_u32_e32 v3, 0x71, v0
	s_nop 0
	v_cndmask_b32_e32 v91, v212, v91, vcc
	v_cmp_le_i32_e32 vcc, v3, v49
	v_add_u32_e32 v3, 0x52, v0
	s_nop 0
	v_cndmask_b32_e32 v75, v212, v75, vcc
	v_cmp_le_i32_e32 vcc, v3, v49
	v_add_u32_e32 v3, 0x72, v0
	s_nop 0
	v_cndmask_b32_e32 v92, v212, v92, vcc
	v_cmp_le_i32_e32 vcc, v3, v49
	v_add_u32_e32 v3, 0x53, v0
	s_nop 0
	v_cndmask_b32_e32 v76, v212, v76, vcc
	v_cmp_le_i32_e32 vcc, v3, v49
	v_add_u32_e32 v3, 0x73, v0
	s_nop 0
	v_cndmask_b32_e32 v93, v212, v93, vcc
	v_cmp_le_i32_e32 vcc, v3, v49
	v_add_u32_e32 v3, 0x58, v0
	s_nop 0
	v_cndmask_b32_e32 v77, v212, v77, vcc
	v_cmp_le_i32_e32 vcc, v3, v49
	v_add_u32_e32 v3, 0x78, v0
	s_nop 0
	v_cndmask_b32_e32 v94, v212, v94, vcc
	v_cmp_le_i32_e32 vcc, v3, v49
	v_add_u32_e32 v3, 0x59, v0
	s_nop 0
	v_cndmask_b32_e32 v78, v212, v78, vcc
	v_cmp_le_i32_e32 vcc, v3, v49
	v_add_u32_e32 v3, 0x79, v0
	s_nop 0
	v_cndmask_b32_e32 v95, v212, v95, vcc
	v_cmp_le_i32_e32 vcc, v3, v49
	v_add_u32_e32 v3, 0x5a, v0
	s_nop 0
	v_cndmask_b32_e32 v79, v212, v79, vcc
	v_cmp_le_i32_e32 vcc, v3, v49
	v_add_u32_e32 v3, 0x7a, v0
	s_nop 0
	v_cndmask_b32_e32 v96, v212, v96, vcc
	v_cmp_le_i32_e32 vcc, v3, v49
	v_add_u32_e32 v3, 0x5b, v0
	v_add_u32_e32 v0, 0x7b, v0
	v_cndmask_b32_e32 v80, v212, v80, vcc
	v_cmp_le_i32_e32 vcc, v3, v49
	s_nop 1
	v_cndmask_b32_e32 v97, v212, v97, vcc
	v_cmp_le_i32_e32 vcc, v0, v49
	s_nop 1
	v_cndmask_b32_e32 v81, v212, v81, vcc

; #define LAS __attribute__((address_space(3)))
; #define MFMA32(a, b, c) __builtin_amdgcn_mfma_f32_32x32x16_bf16((a), (b), (c), 0, 0, 0)
; DI unsigned pk2(float lo, float hi) { f32x2_t v = {lo, hi}; bf16x2_t b = __builtin_convertvector(v, bf16x2_t); return __builtin_bit_cast(unsigned, b); }
; DI void attn_tile(bool MASK, const LAS unsigned char* Ks, const LAS unsigned char* Vs, const bf16x8 (&qr)[6], f32x16& negm, float& mrun, float& lrun, f32x16& o0, f32x16& o1,
;                                        int kv0, int qrow, int r32, int hi) {
;     ...
;     float ls = 0.f;
; #pragma unroll
;     for (int r = 0; r < 16; ++r) { p0[r] = __builtin_amdgcn_exp2f(p0[r]); p1[r] = __builtin_amdgcn_exp2f(p1[r]); ls += p0[r] + p1[r]; }
;     lrun += ls;
; #pragma unroll
;     for (int ks = 0; ks < 4; ++ks) {
;         u32x4 pp;
;         if (ks == 0) { pp.x = pk2(p0[0], p0[1]); pp.y = pk2(p0[2], p0[3]); pp.z = pk2(p0[4], p0[5]); pp.w = pk2(p0[6], p0[7]); }
;         else if (ks == 1) { pp.x = pk2(p0[8], p0[9]); pp.y = pk2(p0[10], p0[11]); pp.z = pk2(p0[12], p0[13]); pp.w = pk2(p0[14], p0[15]); }
;         else if (ks == 2) { pp.x = pk2(p1[0], p1[1]); pp.y = pk2(p1[2], p1[3]); pp.z = pk2(p1[4], p1[5]); pp.w = pk2(p1[6], p1[7]); }
;         else { pp.x = pk2(p1[8], p1[9]); pp.y = pk2(p1[10], p1[11]); pp.z = pk2(p1[12], p1[13]); pp.w = pk2(p1[14], p1[15]); }
;         const bf16x8 pa = __builtin_bit_cast(bf16x8, pp);
;         const LAS unsigned char* vp = Vs + r32 * 136 + (16 * ks + 4 * hi) * 2;
;         const u32x2 l0 = *(const LAS u32x2*)vp, h0 = *(const LAS u32x2*)(vp + 16);
;         const u32x2 l1 = *(const LAS u32x2*)(vp + 32 * 136), h1 = *(const LAS u32x2*)(vp + 32 * 136 + 16);
;         u32x4 v0 = {l0.x, l0.y, h0.x, h0.y}, v1 = {l1.x, l1.y, h1.x, h1.y};
;         o0 = MFMA32(__builtin_bit_cast(bf16x8, v0), pa, o0);
;         o1 = MFMA32(__builtin_bit_cast(bf16x8, v1), pa, o1);
;     }
.LBB0_861:
	v_exp_f32_e32 v3, v82
	v_exp_f32_e32 v159, v66
	v_exp_f32_e32 v0, v83
	v_exp_f32_e32 v66, v67
	v_exp_f32_e32 v9, v84
	v_add_f32_e32 v67, v159, v3
	v_cvt_pk_bf16_f32 v8, v3, v0
	v_pk_add_f32 v[4:5], v[66:67], v[0:1]
	v_exp_f32_e32 v67, v68
	v_pk_add_f32 v[10:11], v[4:5], v[4:5] op_sel_hi:[0,1]
	v_exp_f32_e32 v10, v85
	v_exp_f32_e32 v68, v69
	v_add_f32_e32 v69, v67, v9
	v_exp_f32_e32 v3, v96
	v_cvt_pk_bf16_f32 v9, v9, v10
	v_pk_add_f32 v[4:5], v[68:69], v[10:11]
	v_exp_f32_e32 v11, v86
	v_pk_add_f32 v[12:13], v[4:5], v[4:5] op_sel_hi:[0,1]
	v_exp_f32_e32 v69, v70
	v_exp_f32_e32 v12, v87
	v_exp_f32_e32 v70, v71
	v_add_f32_e32 v71, v69, v11
	v_cvt_pk_bf16_f32 v10, v11, v12
	v_pk_add_f32 v[4:5], v[70:71], v[12:13]
	v_exp_f32_e32 v13, v88
	v_pk_add_f32 v[14:15], v[4:5], v[4:5] op_sel_hi:[0,1]
	v_exp_f32_e32 v71, v72
	v_exp_f32_e32 v14, v89
	v_exp_f32_e32 v72, v73
	v_add_f32_e32 v73, v71, v13
	v_cvt_pk_bf16_f32 v11, v13, v14
	v_pk_add_f32 v[4:5], v[72:73], v[14:15]
	v_exp_f32_e32 v73, v90
	v_pk_add_f32 v[82:83], v[4:5], v[4:5] op_sel_hi:[0,1]
	v_exp_f32_e32 v90, v74
	v_exp_f32_e32 v82, v91
	v_exp_f32_e32 v74, v75
	v_add_u32_e32 v15, v205, v208
	v_add_f32_e32 v75, v90, v73
	v_add_u32_e32 v0, 0x9800, v15
	v_pk_add_f32 v[4:5], v[74:75], v[82:83]
	v_exp_f32_e32 v75, v92
	v_pk_add_f32 v[84:85], v[4:5], v[4:5] op_sel_hi:[0,1]
	v_exp_f32_e32 v83, v76
	v_exp_f32_e32 v84, v93
	v_exp_f32_e32 v76, v77
	v_exp_f32_e32 v91, v78
	v_add_f32_e32 v77, v83, v75
	v_exp_f32_e32 v78, v79
	v_pk_add_f32 v[4:5], v[76:77], v[84:85]
	v_add_u32_e32 v77, 0x8800, v15
	v_pk_add_f32 v[86:87], v[4:5], v[4:5] op_sel_hi:[0,1]
	v_exp_f32_e32 v85, v94
	v_exp_f32_e32 v86, v95
	s_waitcnt lgkmcnt(0)
	v_mfma_f32_32x32x16_bf16 v[32:47], v[214:217], v[8:11], v[32:47]
	v_add_f32_e32 v79, v91, v85
	v_add_f32_e64 v88, v78, v86
	v_add_f32_e64 v89, v79, v87
	s_nop 0
	v_mfma_f32_32x32x16_bf16 v[16:31], v[218:221], v[8:11], v[16:31]
	v_add_f32_e64 v12, v88, v88
	v_add_f32_e64 v13, v88, v89
	v_exp_f32_e32 v12, v97
	v_cvt_pk_bf16_f32 v8, v73, v82
	v_cvt_pk_bf16_f32 v9, v75, v84
	v_cvt_pk_bf16_f32 v10, v85, v86
	v_cvt_pk_bf16_f32 v11, v3, v12
	v_exp_f32_e32 v15, v80
	v_exp_f32_e32 v14, v81
	s_nop 0
	v_mfma_f32_32x32x16_bf16 v[32:47], v[222:225], v[8:11], v[32:47]
	s_nop 0
	v_mfma_f32_32x32x16_bf16 v[16:31], v[226:229], v[8:11], v[16:31]
	v_cvt_pk_bf16_f32 v8, v159, v66
	v_cvt_pk_bf16_f32 v9, v67, v68
	v_cvt_pk_bf16_f32 v10, v69, v70
	v_cvt_pk_bf16_f32 v11, v71, v72
	s_nop 0
	s_nop 0
	v_mfma_f32_32x32x16_bf16 v[32:47], v[230:233], v[8:11], v[32:47]
	s_nop 0
	v_mfma_f32_32x32x16_bf16 v[16:31], v[234:237], v[8:11], v[16:31]
	v_cvt_pk_bf16_f32 v8, v90, v74
	v_cvt_pk_bf16_f32 v9, v83, v76
	v_cvt_pk_bf16_f32 v10, v91, v78
	v_cvt_pk_bf16_f32 v11, v15, v14
	v_add_f32_e32 v15, v15, v3
	v_pk_add_f32 v[12:13], v[14:15], v[12:13]
	s_nop 0
	v_mfma_f32_32x32x16_bf16 v[32:47], v[238:241], v[8:11], v[32:47]
	v_add_f32_e32 v0, v12, v13
	v_add_f32_e32 v48, v48, v0
	s_nop 0
	v_mfma_f32_32x32x16_bf16 v[16:31], v[242:245], v[8:11], v[16:31]
; #define LAS __attribute__((address_space(3)))
; #define MFMA32(a, b, c) __builtin_amdgcn_mfma_f32_32x32x16_bf16((a), (b), (c), 0, 0, 0)
; DI int crow(int r, int hi) { return (r & 3) + 8 * (r >> 2) + 4 * hi; }
; DI void attn_tile(bool MASK, const LAS unsigned char* Ks, const LAS unsigned char* Vs, const bf16x8 (&qr)[6], f32x16& negm, float& mrun, float& lrun, f32x16& o0, f32x16& o1,
;                                        int kv0, int qrow, int r32, int hi) {
;     f32x16 p0, p1;
;     __builtin_amdgcn_s_setprio(1);
;     {
;         const bf16x8 a0 = *(const LAS bf16x8*)(Ks + r32 * 208 + hi * 16);
;         const bf16x8 a1 = *(const LAS bf16x8*)(Ks + (32 + r32) * 208 + hi * 16);
;         p0 = MFMA32(a0, qr[0], negm); p1 = MFMA32(a1, qr[0], negm);
;     }
; #pragma unroll
;     for (int d0 = 1; d0 < 6; ++d0) {
;         const bf16x8 a0 = *(const LAS bf16x8*)(Ks + r32 * 208 + (2 * d0 + hi) * 16);
;         const bf16x8 a1 = *(const LAS bf16x8*)(Ks + (32 + r32) * 208 + (2 * d0 + hi) * 16);
;         p0 = MFMA32(a0, qr[d0], p0); p1 = MFMA32(a1, qr[d0], p1);
;     }
;     __builtin_amdgcn_s_setprio(0);
;     if (MASK) {
;         asm volatile("" ::: "memory");
; #pragma unroll
;         for (int r = 0; r < 16; ++r) { const int kv = kv0 + crow(r, hi); if (kv > qrow) p0[r] = -INFINITY; if (kv + 32 > qrow) p1[r] = -INFINITY; }
.LBB0_862:
	s_add_i32 s33, s23, 6
	s_min_i32 s33, s33, s20
	v_mad_i64_i32 v[4:5], s[34:35], s33, v161, v[190:191]
	v_mad_i64_i32 v[6:7], s[34:35], s33, v161, v[194:195]
	s_lshl_b32 s34, s33, 6
	s_waitcnt lgkmcnt(0)
	s_barrier
	s_waitcnt vmcnt(6)
	ds_write_b128 v209, v[142:145]
	ds_write_b128 v210, v[138:141]
	ds_write2_b64 v211, v[134:135], v[136:137] offset1:1
	s_ashr_i32 s35, s34, 31
	global_load_dwordx4 v[142:145], v[4:5], off
	global_load_dwordx4 v[138:141], v[6:7], off
	v_lshl_add_u64 v[4:5], s[34:35], 1, v[192:193]
	global_load_dwordx4 v[134:137], v[4:5], off
	s_add_i32 s33, s23, 2
	s_cmp_ge_i32 s33, s19
	s_cbranch_scc1 .LBB0_848
	s_add_i32 s34, s21, 0x80
	s_cmp_gt_i32 s34, s22
	s_cbranch_scc1 .LBB0_848
	s_cmp_lt_i32 s33, s12
	s_setprio 1
	v_add_u32_e32 v0, v206, v160
	ds_read_b128 v[4:7], v0 offset:44032
	ds_read_b128 v[8:11], v0 offset:50688
	ds_read_b128 v[12:15], v0 offset:44064
	ds_read_b128 v[214:217], v0 offset:50720
	ds_read_b128 v[218:221], v0 offset:44096
	ds_read_b128 v[222:225], v0 offset:50752
	ds_read_b128 v[226:229], v0 offset:44128
	ds_read_b128 v[230:233], v0 offset:50784
	s_waitcnt lgkmcnt(7)
	v_mfma_f32_32x32x16_bf16 v[82:97], v[4:7], v[154:157], v[50:65]
	ds_read_b128 v[234:237], v0 offset:44160
	s_waitcnt lgkmcnt(7)
	v_mfma_f32_32x32x16_bf16 v[66:81], v[8:11], v[154:157], v[50:65]
	ds_read_b128 v[238:241], v0 offset:50816
	s_waitcnt lgkmcnt(7)
	v_mfma_f32_32x32x16_bf16 v[82:97], v[12:15], v[150:153], v[82:97]
	ds_read_b128 v[242:245], v0 offset:44192
	s_waitcnt lgkmcnt(7)
	v_mfma_f32_32x32x16_bf16 v[66:81], v[214:217], v[150:153], v[66:81]
	ds_read_b128 v[246:249], v0 offset:50848
	s_waitcnt lgkmcnt(7)
	v_mfma_f32_32x32x16_bf16 v[82:97], v[218:221], v[146:149], v[82:97]
	s_waitcnt lgkmcnt(6)
	v_mfma_f32_32x32x16_bf16 v[66:81], v[222:225], v[146:149], v[66:81]
	s_waitcnt lgkmcnt(5)
	v_mfma_f32_32x32x16_bf16 v[82:97], v[226:229], v[126:129], v[82:97]
	s_waitcnt lgkmcnt(4)
	v_mfma_f32_32x32x16_bf16 v[66:81], v[230:233], v[126:129], v[66:81]
	s_waitcnt lgkmcnt(3)
	v_mfma_f32_32x32x16_bf16 v[82:97], v[234:237], v[122:125], v[82:97]
	s_waitcnt lgkmcnt(2)
	v_mfma_f32_32x32x16_bf16 v[66:81], v[238:241], v[122:125], v[66:81]
	s_waitcnt lgkmcnt(1)
	v_mfma_f32_32x32x16_bf16 v[82:97], v[242:245], v[118:121], v[82:97]
	s_waitcnt lgkmcnt(0)
	v_mfma_f32_32x32x16_bf16 v[66:81], v[246:249], v[118:121], v[66:81]
	s_setprio 0
	v_add_u32_e32 v3, v205, v208
	v_add_u32_e32 v0, 0xf000, v3
	v_add_u32_e32 v3, 0xe000, v3
	ds_read2_b64 v[214:217], v3 offset0:0 offset1:2
	ds_read2_b64 v[218:221], v0 offset0:32 offset1:34
	ds_read2_b64 v[222:225], v3 offset0:4 offset1:6
	ds_read2_b64 v[226:229], v0 offset0:36 offset1:38
	ds_read2_b64 v[230:233], v3 offset0:8 offset1:10
	ds_read2_b64 v[234:237], v0 offset0:40 offset1:42
	ds_read2_b64 v[238:241], v3 offset0:12 offset1:14
	ds_read2_b64 v[242:245], v0 offset0:44 offset1:46
	s_cbranch_scc1 .LBB0_866
	v_add_u32_e32 v0, s21, v207
	v_add_u32_e32 v4, 0xa0, v0
	v_add_u32_e32 v3, 0x80, v0
	v_cmp_le_i32_e32 vcc, v4, v49
	s_nop 5
	v_cndmask_b32_e32 v66, v212, v66, vcc
	v_cmp_lt_i32_e32 vcc, v3, v49
	s_nop 1
	v_cndmask_b32_e32 v83, v212, v83, vcc
	v_cmp_le_i32_e32 vcc, v3, v49
	v_add_u32_e32 v3, 0xa1, v0
	s_nop 0
	v_cndmask_b32_e32 v82, v212, v82, vcc
	v_cmp_le_i32_e32 vcc, v3, v49
	v_add_u32_e32 v3, 0x82, v0
	s_nop 0
	v_cndmask_b32_e32 v67, v212, v67, vcc
	v_cmp_le_i32_e32 vcc, v3, v49
	v_add_u32_e32 v3, 0xa2, v0
	s_nop 0
	v_cndmask_b32_e32 v84, v212, v84, vcc
	v_cmp_le_i32_e32 vcc, v3, v49
	v_add_u32_e32 v3, 0x83, v0
	s_nop 0
	v_cndmask_b32_e32 v68, v212, v68, vcc
	v_cmp_le_i32_e32 vcc, v3, v49
	v_add_u32_e32 v3, 0xa3, v0
	s_nop 0
	v_cndmask_b32_e32 v85, v212, v85, vcc
	v_cmp_le_i32_e32 vcc, v3, v49
	v_add_u32_e32 v3, 0x88, v0
	s_nop 0
	v_cndmask_b32_e32 v69, v212, v69, vcc
	v_cmp_le_i32_e32 vcc, v3, v49
	v_add_u32_e32 v3, 0xa8, v0
	s_nop 0
	v_cndmask_b32_e32 v86, v212, v86, vcc
	v_cmp_le_i32_e32 vcc, v3, v49
	v_add_u32_e32 v3, 0x89, v0
	s_nop 0
	v_cndmask_b32_e32 v70, v212, v70, vcc
	v_cmp_le_i32_e32 vcc, v3, v49
	v_add_u32_e32 v3, 0xa9, v0
	s_nop 0
	v_cndmask_b32_e32 v87, v212, v87, vcc
	v_cmp_le_i32_e32 vcc, v3, v49
	v_add_u32_e32 v3, 0x8a, v0
	s_nop 0
	v_cndmask_b32_e32 v71, v212, v71, vcc
	v_cmp_le_i32_e32 vcc, v3, v49
	v_add_u32_e32 v3, 0xaa, v0
	s_nop 0
	v_cndmask_b32_e32 v88, v212, v88, vcc
	v_cmp_le_i32_e32 vcc, v3, v49
	v_add_u32_e32 v3, 0x8b, v0
	s_nop 0
	v_cndmask_b32_e32 v72, v212, v72, vcc
	v_cmp_le_i32_e32 vcc, v3, v49
	v_add_u32_e32 v3, 0xab, v0
	s_nop 0
	v_cndmask_b32_e32 v89, v212, v89, vcc
	v_cmp_le_i32_e32 vcc, v3, v49
	v_add_u32_e32 v3, 0x90, v0
	s_nop 0
	v_cndmask_b32_e32 v73, v212, v73, vcc
	v_cmp_le_i32_e32 vcc, v3, v49
	v_add_u32_e32 v3, 0xb0, v0
	s_nop 0
	v_cndmask_b32_e32 v90, v212, v90, vcc
	v_cmp_le_i32_e32 vcc, v3, v49
	v_add_u32_e32 v3, 0x91, v0
	s_nop 0
	v_cndmask_b32_e32 v74, v212, v74, vcc
	v_cmp_le_i32_e32 vcc, v3, v49
	v_add_u32_e32 v3, 0xb1, v0
	s_nop 0
	v_cndmask_b32_e32 v91, v212, v91, vcc
	v_cmp_le_i32_e32 vcc, v3, v49
	v_add_u32_e32 v3, 0x92, v0
	s_nop 0
	v_cndmask_b32_e32 v75, v212, v75, vcc
	v_cmp_le_i32_e32 vcc, v3, v49
	v_add_u32_e32 v3, 0xb2, v0
	s_nop 0
	v_cndmask_b32_e32 v92, v212, v92, vcc
	v_cmp_le_i32_e32 vcc, v3, v49
	v_add_u32_e32 v3, 0x93, v0
	s_nop 0
	v_cndmask_b32_e32 v76, v212, v76, vcc
	v_cmp_le_i32_e32 vcc, v3, v49
	v_add_u32_e32 v3, 0xb3, v0
	s_nop 0
	v_cndmask_b32_e32 v93, v212, v93, vcc
	v_cmp_le_i32_e32 vcc, v3, v49
	v_add_u32_e32 v3, 0x98, v0
	s_nop 0
	v_cndmask_b32_e32 v77, v212, v77, vcc
	v_cmp_le_i32_e32 vcc, v3, v49
	v_add_u32_e32 v3, 0xb8, v0
	s_nop 0
	v_cndmask_b32_e32 v94, v212, v94, vcc
	v_cmp_le_i32_e32 vcc, v3, v49
	v_add_u32_e32 v3, 0x99, v0
	s_nop 0
	v_cndmask_b32_e32 v78, v212, v78, vcc
	v_cmp_le_i32_e32 vcc, v3, v49
	v_add_u32_e32 v3, 0xb9, v0
	s_nop 0
	v_cndmask_b32_e32 v95, v212, v95, vcc
	v_cmp_le_i32_e32 vcc, v3, v49
	v_add_u32_e32 v3, 0x9a, v0
	s_nop 0
	v_cndmask_b32_e32 v79, v212, v79, vcc
	v_cmp_le_i32_e32 vcc, v3, v49
	v_add_u32_e32 v3, 0xba, v0
	s_nop 0
	v_cndmask_b32_e32 v96, v212, v96, vcc
	v_cmp_le_i32_e32 vcc, v3, v49
	v_add_u32_e32 v3, 0x9b, v0
	v_add_u32_e32 v0, 0xbb, v0
	v_cndmask_b32_e32 v80, v212, v80, vcc
	v_cmp_le_i32_e32 vcc, v3, v49
	s_nop 1
	v_cndmask_b32_e32 v97, v212, v97, vcc
	v_cmp_le_i32_e32 vcc, v0, v49
	s_nop 1
	v_cndmask_b32_e32 v81, v212, v81, vcc

; DI unsigned pk2(float lo, float hi) { f32x2_t v = {lo, hi}; bf16x2_t b = __builtin_convertvector(v, bf16x2_t); return __builtin_bit_cast(unsigned, b); }
; DI float bflo(unsigned u) { return __uint_as_float(u << 16); }
; template <int NR, bool XIN_BF, bool XOUT_BF> DI void resid_rows(const void* xin_, void* xout_, const bf16* d, const float* rsq, float coef, const float* pg, const float* ng, bf16* xn, int m0, int mstride, int lane, float* rs_out = nullptr) {
;     f32x4 xv[NR][4]; u32x2 dv[NR][4]; float ss[NR];
; #pragma unroll
;     for (int r = 0; r < NR; ++r) { const size_t m = (size_t)(m0 + r * mstride);
;         ss[r] = lane < 16 ? rsq[m * 16 + lane] : 0.f;
; #pragma unroll
;         for (int j = 0; j < 4; ++j) { const int c = 4 * lane + 256 * j;
;             if (XIN_BF) { const u32x2 t = __builtin_nontemporal_load((const u32x2*)((const bf16*)xin_ + m * DM + c)); xv[r][j] = (f32x4){bflo(t.x), bfhi(t.x), bflo(t.y), bfhi(t.y)}; }
;             else xv[r][j] = __builtin_nontemporal_load((const f32x4*)((const float*)xin_ + m * DM + c));
;             dv[r][j] = __builtin_nontemporal_load((const u32x2*)(d + m * DM + c)); } }
; #pragma unroll
;     for (int r = 0; r < NR; ++r) { const size_t m = (size_t)(m0 + r * mstride);
;         const float rr = rsqrtf(wave_sum(ss[r]) * (1.f / 1024.f) + EPS) * coef; float s2 = 0.f;
; #pragma unroll
;         for (int j = 0; j < 4; ++j) { const int c = 4 * lane + 256 * j; const f32x4 gg = *(const f32x4*)(pg + c);
;             const f32x4 df = {bflo(dv[r][j].x), bfhi(dv[r][j].x), bflo(dv[r][j].y), bfhi(dv[r][j].y)};
;             xv[r][j] = xv[r][j] + df * rr * gg;
;             if (XOUT_BF) { u32x2 w; w.x = pk2(xv[r][j][0], xv[r][j][1]); w.y = pk2(xv[r][j][2], xv[r][j][3]); *(u32x2*)((bf16*)xout_ + m * DM + c) = w; }
;             else __builtin_nontemporal_store(xv[r][j], (f32x4*)((float*)xout_ + m * DM + c));
;             s2 += (xv[r][j][0] * xv[r][j][0] + xv[r][j][1] * xv[r][j][1]) + (xv[r][j][2] * xv[r][j][2] + xv[r][j][3] * xv[r][j][3]); }
;         if (rs_out) { const float r2 = rsqrtf(wave_sum(s2) * (1.f / 1024.f) + EPS); if (lane == 0) rs_out[m] = r2; }
; __global__ void __launch_bounds__(512, 2) mk_fwd(Args a) {
;     ...
;         for (int m = gw; m < M; m += 4 * NGW) resid_rows<4, true, true>(a.out, GB, Q, ROWSQ, 1.0f, (const float*)a.in[19], nullptr, nullptr, m, NGW, lane, RS3);
.LBB0_1064:
	s_cmp_lt_i32 s66, 11
	s_cselect_b64 s[2:3], -1, 0
	s_add_u32 s4, s64, 0x2acc000
	s_addc_u32 s5, s65, 0
	s_and_b64 s[6:7], s[2:3], s[0:1]
	s_andn2_b64 vcc, exec, s[6:7]
	s_cbranch_vccnz .LBB0_1084
	s_cmpk_gt_i32 s58, 0x7fff
	s_cbranch_scc1 .LBB0_1084
	v_readlane_b32 s8, v253, 21
	s_waitcnt lgkmcnt(0)
	v_mov_b32_e32 v1, 0
	v_lshlrev_b32_e32 v0, 4, v196
	v_readlane_b32 s14, v253, 27
	v_readlane_b32 s15, v253, 28
	v_readlane_b32 s10, v253, 23
	v_readlane_b32 s11, v253, 24
	v_lshl_add_u64 v[4:5], s[14:15], 0, v[0:1]
	v_mbcnt_lo_u32_b32 v0, -1, 0
	v_mbcnt_hi_u32_b32 v0, -1, v0
	v_and_b32_e32 v6, 64, v0
	v_add_u32_e32 v6, 64, v6
	v_xor_b32_e32 v7, 1, v0
	v_cmp_lt_i32_e32 vcc, v7, v6
	s_ashr_i32 s59, s58, 31
	v_readlane_b32 s9, v253, 22
	v_cndmask_b32_e32 v7, v0, v7, vcc
	v_lshlrev_b32_e32 v74, 2, v7
	v_xor_b32_e32 v7, 2, v0
	v_cmp_lt_i32_e32 vcc, v7, v6
	s_lshl_b32 s8, s70, 5
	s_lshl_b64 s[10:11], s[58:59], 2
	v_cndmask_b32_e32 v7, v0, v7, vcc
	v_lshlrev_b32_e32 v75, 2, v7
	v_xor_b32_e32 v7, 4, v0
	v_cmp_lt_i32_e32 vcc, v7, v6
	s_add_u32 s9, s64, s10
	s_addc_u32 s11, s65, s11
	v_cndmask_b32_e32 v7, v0, v7, vcc
	v_lshlrev_b32_e32 v76, 2, v7
	v_xor_b32_e32 v7, 8, v0
	s_add_u32 s10, s9, 0x2acc000
	v_readlane_b32 s12, v253, 25
	v_readlane_b32 s13, v253, 26
	v_cmp_lt_i32_e32 vcc, v7, v6
	s_addc_u32 s11, s11, 0
	s_ashr_i32 s9, s8, 31
	v_cndmask_b32_e32 v7, v0, v7, vcc
	s_lshl_b64 s[12:13], s[8:9], 2
	s_lshl_b64 s[14:15], s[58:59], 6
	v_lshlrev_b32_e32 v77, 2, v7
	v_xor_b32_e32 v7, 16, v0
	s_add_u32 s14, s64, s14
	v_lshlrev_b32_e32 v12, 2, v196
	v_mov_b32_e32 v13, v1
	v_cmp_lt_i32_e32 vcc, v7, v6
	s_addc_u32 s15, s65, s15
	v_lshl_add_u64 v[2:3], s[78:79], 0, v[12:13]
	v_readlane_b32 s20, v253, 33
	v_readlane_b32 s21, v253, 34
	v_cndmask_b32_e32 v7, v0, v7, vcc
	v_lshl_add_u64 v[12:13], s[14:15], 0, v[12:13]
	s_mov_b64 s[14:15], 0x28a0000
	v_readlane_b32 s16, v253, 29
	v_lshlrev_b32_e32 v78, 2, v7
	v_xor_b32_e32 v7, 32, v0
	v_lshl_add_u64 v[12:13], v[12:13], 0, s[14:15]
	s_lshl_b64 s[14:15], s[8:9], 6
	s_lshl_b64 s[20:21], s[58:59], 11
	v_readlane_b32 s17, v253, 30
	v_readlane_b32 s18, v253, 31
	v_readlane_b32 s19, v253, 32
	v_cmp_lt_i32_e32 vcc, v7, v6
	s_add_u32 s16, s64, s20
	s_addc_u32 s17, s65, s21
	v_cndmask_b32_e32 v0, v0, v7, vcc
	s_lshl_b64 s[18:19], s[8:9], 11
	v_lshlrev_b32_e32 v79, 2, v0
	v_lshlrev_b32_e32 v0, 3, v196
	s_add_u32 s20, s62, s20
	v_cmp_gt_u32_e64 s[0:1], 16, v196
	v_cmp_eq_u32_e64 s[2:3], 0, v196
	v_lshl_add_u64 v[6:7], s[62:63], 0, v[0:1]
	v_lshl_add_u64 v[8:9], s[84:85], 0, v[0:1]
	v_lshl_add_u64 v[10:11], s[80:81], 0, v[0:1]
	s_addc_u32 s21, s63, s21
	s_lshl_b32 s9, s70, 4
	s_mul_i32 s33, s70, 24
	v_mov_b32_e32 v80, 0x358637bd
	s_mov_b32 s38, 0x800000
	s_mov_b32 s39, 0x15bec000
	s_mov_b32 s40, s58
	v_readlane_b32 s22, v253, 35
	v_readlane_b32 s23, v253, 36
	global_load_dwordx4 v[200:203], v[4:5], off
	global_load_dwordx4 v[204:207], v[4:5], off offset:1024
	global_load_dwordx4 v[208:211], v[4:5], off offset:2048
	global_load_dwordx4 v[212:215], v[4:5], off offset:3072
	s_waitcnt vmcnt(0)
	s_branch .LBB0_1068

; DI unsigned pk2(float lo, float hi) { f32x2_t v = {lo, hi}; bf16x2_t b = __builtin_convertvector(v, bf16x2_t); return __builtin_bit_cast(unsigned, b); }
; DI float bflo(unsigned u) { return __uint_as_float(u << 16); }
; DI float bfhi(unsigned u) { return __uint_as_float(u & 0xffff0000u); }
; template <int NR, bool XIN_BF, bool XOUT_BF> DI void resid_rows(const void* xin_, void* xout_, const bf16* d, const float* rsq, float coef, const float* pg, const float* ng, bf16* xn, int m0, int mstride, int lane, float* rs_out = nullptr) {
;     ...
;     for (int r = 0; r < NR; ++r) { const size_t m = (size_t)(m0 + r * mstride);
;         const float rr = rsqrtf(wave_sum(ss[r]) * (1.f / 1024.f) + EPS) * coef; float s2 = 0.f;
; #pragma unroll
;         for (int j = 0; j < 4; ++j) { const int c = 4 * lane + 256 * j; const f32x4 gg = *(const f32x4*)(pg + c);
;             const f32x4 df = {bflo(dv[r][j].x), bfhi(dv[r][j].x), bflo(dv[r][j].y), bfhi(dv[r][j].y)};
;             xv[r][j] = xv[r][j] + df * rr * gg;
;             if (XOUT_BF) { u32x2 w; w.x = pk2(xv[r][j][0], xv[r][j][1]); w.y = pk2(xv[r][j][2], xv[r][j][3]); *(u32x2*)((bf16*)xout_ + m * DM + c) = w; }
;             else __builtin_nontemporal_store(xv[r][j], (f32x4*)((float*)xout_ + m * DM + c));
;             s2 += (xv[r][j][0] * xv[r][j][0] + xv[r][j][1] * xv[r][j][1]) + (xv[r][j][2] * xv[r][j][2] + xv[r][j][3] * xv[r][j][3]); }
;         if (rs_out) { const float r2 = rsqrtf(wave_sum(s2) * (1.f / 1024.f) + EPS); if (lane == 0) rs_out[m] = r2; }
.LBB0_1076:
	s_or_b64 exec, exec, s[26:27]
	s_nop 1
	v_mov_b64_e32 v[84:85], v[200:201]
	v_mov_b64_e32 v[86:87], v[202:203]
	s_waitcnt vmcnt(0)
	ds_bpermute_b32 v21, v74, v20
	v_lshlrev_b32_e32 v88, 16, v16
	v_and_b32_e32 v89, 0xffff0000, v16
	v_lshlrev_b32_e32 v90, 16, v17
	v_and_b32_e32 v91, 0xffff0000, v17
	s_waitcnt lgkmcnt(0)
	v_add_f32_e32 v20, v20, v21
	ds_bpermute_b32 v21, v75, v20
	v_lshlrev_b32_e32 v92, 16, v18
	v_and_b32_e32 v93, 0xffff0000, v18
	v_lshlrev_b32_e32 v94, 16, v19
	v_and_b32_e32 v95, 0xffff0000, v19
	s_waitcnt lgkmcnt(0)
	v_add_f32_e32 v20, v20, v21
	ds_bpermute_b32 v21, v76, v20
	v_add_co_u32_e32 v96, vcc, s39, v14
	s_lshl_b64 s[26:27], s[22:23], 11
	s_nop 0
	v_addc_co_u32_e32 v97, vcc, 0, v15, vcc
	s_waitcnt lgkmcnt(0)
	v_add_f32_e32 v16, v20, v21
	ds_bpermute_b32 v17, v77, v16
	v_lshl_add_u64 v[14:15], v[6:7], 0, s[26:27]
	s_waitcnt lgkmcnt(0)
	v_add_f32_e32 v18, v16, v17
	ds_bpermute_b32 v19, v78, v18
	v_lshl_add_u64 v[16:17], v[8:9], 0, s[26:27]
	s_waitcnt lgkmcnt(0)
	v_add_f32_e32 v20, v18, v19
	ds_bpermute_b32 v21, v79, v20
	global_load_dwordx2 v[26:27], v[14:15], off nt
	global_load_dwordx2 v[22:23], v[14:15], off offset:512 nt
	global_load_dwordx2 v[18:19], v[14:15], off offset:1024 nt
	s_nop 0
	global_load_dwordx2 v[14:15], v[14:15], off offset:1536 nt
	s_waitcnt lgkmcnt(0)
	v_add_f32_e32 v20, v20, v21
	v_fmamk_f32 v20, v20, 0x3a800000, v80
	v_mul_f32_e32 v21, 0x4b800000, v20
	v_cmp_gt_f32_e32 vcc, s38, v20
	s_nop 1
	v_cndmask_b32_e32 v20, v20, v21, vcc
	v_rsq_f32_e32 v98, v20
	global_load_dwordx2 v[28:29], v[16:17], off nt
	global_load_dwordx2 v[24:25], v[16:17], off offset:512 nt
	global_load_dwordx2 v[20:21], v[16:17], off offset:1024 nt
	s_nop 0
	global_load_dwordx2 v[16:17], v[16:17], off offset:1536 nt
	v_mul_f32_e32 v99, 0x45800000, v98
	v_cndmask_b32_e32 v98, v98, v99, vcc
	v_pk_mul_f32 v[92:93], v[98:99], v[92:93] op_sel_hi:[0,1]
	v_pk_mul_f32 v[94:95], v[98:99], v[94:95] op_sel_hi:[0,1]
	v_pk_fma_f32 v[90:91], v[86:87], v[94:95], v[90:91]
	v_pk_fma_f32 v[88:89], v[84:85], v[92:93], v[88:89]
	v_cvt_pk_bf16_f32 v85, v90, v91
	v_cvt_pk_bf16_f32 v84, v88, v89
	global_store_dwordx2 v[96:97], v[84:85], off
	s_nop 1
	v_mov_b64_e32 v[84:85], v[204:205]
	v_mov_b64_e32 v[86:87], v[206:207]
	v_lshlrev_b32_e32 v94, 16, v72
	v_and_b32_e32 v95, 0xffff0000, v72
	v_lshlrev_b32_e32 v72, 16, v73
	v_and_b32_e32 v73, 0xffff0000, v73
	v_lshlrev_b32_e32 v92, 16, v70
	v_and_b32_e32 v93, 0xffff0000, v70
	v_lshlrev_b32_e32 v70, 16, v71
	v_and_b32_e32 v71, 0xffff0000, v71
	v_pk_mul_f32 v[94:95], v[98:99], v[94:95] op_sel_hi:[0,1]
	v_pk_mul_f32 v[72:73], v[98:99], v[72:73] op_sel_hi:[0,1]
	v_mul_f32_e32 v89, v89, v89
	v_mul_f32_e32 v91, v91, v91
	v_fmac_f32_e32 v89, v88, v88
	v_fmac_f32_e32 v91, v90, v90
	v_add_f32_e32 v88, v89, v91
	s_nop 1
	v_pk_fma_f32 v[86:87], v[86:87], v[72:73], v[70:71]
	v_pk_fma_f32 v[84:85], v[84:85], v[94:95], v[92:93]
	v_cvt_pk_bf16_f32 v71, v86, v87
	v_cvt_pk_bf16_f32 v70, v84, v85
	global_store_dwordx2 v[96:97], v[70:71], off offset:512
	s_nop 1
	v_mov_b64_e32 v[70:71], v[208:209]
	v_mov_b64_e32 v[72:73], v[210:211]
	v_lshlrev_b32_e32 v94, 16, v68
	v_and_b32_e32 v95, 0xffff0000, v68
	v_lshlrev_b32_e32 v68, 16, v69
	v_and_b32_e32 v69, 0xffff0000, v69
	v_lshlrev_b32_e32 v92, 16, v66
	v_and_b32_e32 v93, 0xffff0000, v66
	v_lshlrev_b32_e32 v66, 16, v67
	v_and_b32_e32 v67, 0xffff0000, v67
	v_pk_mul_f32 v[94:95], v[98:99], v[94:95] op_sel_hi:[0,1]
	v_pk_mul_f32 v[68:69], v[98:99], v[68:69] op_sel_hi:[0,1]
	v_mul_f32_e32 v85, v85, v85
	v_mul_f32_e32 v87, v87, v87
	v_fmac_f32_e32 v85, v84, v84
	v_fmac_f32_e32 v87, v86, v86
	v_add_f32_e32 v84, v85, v87
	v_add_f32_e32 v84, v88, v84
	s_nop 1
	v_pk_fma_f32 v[72:73], v[72:73], v[68:69], v[66:67]
	v_pk_fma_f32 v[70:71], v[70:71], v[94:95], v[92:93]
	v_cvt_pk_bf16_f32 v67, v72, v73
	v_cvt_pk_bf16_f32 v66, v70, v71
	global_store_dwordx2 v[96:97], v[66:67], off offset:1024
	s_nop 1
	v_mov_b64_e32 v[66:67], v[212:213]
	v_mov_b64_e32 v[68:69], v[214:215]
	v_lshlrev_b32_e32 v94, 16, v64
	v_and_b32_e32 v95, 0xffff0000, v64
	v_lshlrev_b32_e32 v64, 16, v65
	v_and_b32_e32 v65, 0xffff0000, v65
	v_lshlrev_b32_e32 v92, 16, v62
	v_and_b32_e32 v93, 0xffff0000, v62
	v_lshlrev_b32_e32 v62, 16, v63
	v_and_b32_e32 v63, 0xffff0000, v63
	v_pk_mul_f32 v[94:95], v[98:99], v[94:95] op_sel_hi:[0,1]
	v_pk_mul_f32 v[64:65], v[98:99], v[64:65] op_sel_hi:[0,1]
	v_mul_f32_e32 v71, v71, v71
	v_mul_f32_e32 v73, v73, v73
	v_fmac_f32_e32 v71, v70, v70
	v_fmac_f32_e32 v73, v72, v72
	v_add_f32_e32 v70, v71, v73
	v_add_f32_e32 v70, v70, v84
	s_nop 1
	v_pk_fma_f32 v[64:65], v[68:69], v[64:65], v[62:63]
	v_pk_fma_f32 v[66:67], v[66:67], v[94:95], v[92:93]
	v_mul_f32_e32 v63, v65, v65
	v_mul_f32_e32 v62, v67, v67
	v_fmac_f32_e32 v62, v66, v66
	v_fmac_f32_e32 v63, v64, v64
	v_add_f32_e32 v62, v62, v63
	v_add_f32_e32 v62, v62, v70
	ds_bpermute_b32 v63, v74, v62
	v_cvt_pk_bf16_f32 v66, v66, v67
	v_cvt_pk_bf16_f32 v67, v64, v65
	global_store_dwordx2 v[96:97], v[66:67], off offset:1536
	s_waitcnt lgkmcnt(0)
	v_add_f32_e32 v62, v62, v63
	ds_bpermute_b32 v63, v75, v62
	s_waitcnt lgkmcnt(0)
	v_add_f32_e32 v62, v62, v63
	ds_bpermute_b32 v63, v76, v62
	s_waitcnt lgkmcnt(0)
	v_add_f32_e32 v62, v62, v63
	ds_bpermute_b32 v63, v77, v62
	s_waitcnt lgkmcnt(0)
	v_add_f32_e32 v62, v62, v63
	ds_bpermute_b32 v63, v78, v62
	s_waitcnt lgkmcnt(0)
	v_add_f32_e32 v62, v62, v63
	ds_bpermute_b32 v63, v79, v62
	s_and_saveexec_b64 s[36:37], s[2:3]
	s_cbranch_execz .LBB0_1078
	s_waitcnt lgkmcnt(0)
	v_add_f32_e32 v62, v62, v63
	v_fmamk_f32 v62, v62, 0x3a800000, v80
	v_mul_f32_e32 v63, 0x4b800000, v62
	v_cmp_gt_f32_e32 vcc, s38, v62
	s_nop 1
	v_cndmask_b32_e32 v62, v62, v63, vcc
	v_rsq_f32_e32 v62, v62
	s_nop 0
	v_mul_f32_e32 v63, 0x45800000, v62
	v_cndmask_b32_e32 v62, v62, v63, vcc
	global_store_dword v1, v62, s[10:11]
; DI unsigned pk2(float lo, float hi) { f32x2_t v = {lo, hi}; bf16x2_t b = __builtin_convertvector(v, bf16x2_t); return __builtin_bit_cast(unsigned, b); }
; DI float bflo(unsigned u) { return __uint_as_float(u << 16); }
; DI float bfhi(unsigned u) { return __uint_as_float(u & 0xffff0000u); }
; template <int NR, bool XIN_BF, bool XOUT_BF> DI void resid_rows(const void* xin_, void* xout_, const bf16* d, const float* rsq, float coef, const float* pg, const float* ng, bf16* xn, int m0, int mstride, int lane, float* rs_out = nullptr) {
;     ...
;     for (int r = 0; r < NR; ++r) { const size_t m = (size_t)(m0 + r * mstride);
;         const float rr = rsqrtf(wave_sum(ss[r]) * (1.f / 1024.f) + EPS) * coef; float s2 = 0.f;
; #pragma unroll
;         for (int j = 0; j < 4; ++j) { const int c = 4 * lane + 256 * j; const f32x4 gg = *(const f32x4*)(pg + c);
;             const f32x4 df = {bflo(dv[r][j].x), bfhi(dv[r][j].x), bflo(dv[r][j].y), bfhi(dv[r][j].y)};
;             xv[r][j] = xv[r][j] + df * rr * gg;
;             if (XOUT_BF) { u32x2 w; w.x = pk2(xv[r][j][0], xv[r][j][1]); w.y = pk2(xv[r][j][2], xv[r][j][3]); *(u32x2*)((bf16*)xout_ + m * DM + c) = w; }
;             else __builtin_nontemporal_store(xv[r][j], (f32x4*)((float*)xout_ + m * DM + c));
;             s2 += (xv[r][j][0] * xv[r][j][0] + xv[r][j][1] * xv[r][j][1]) + (xv[r][j][2] * xv[r][j][2] + xv[r][j][3] * xv[r][j][3]); }
;         if (rs_out) { const float r2 = rsqrtf(wave_sum(s2) * (1.f / 1024.f) + EPS); if (lane == 0) rs_out[m] = r2; }
.LBB0_1078:
	s_or_b64 exec, exec, s[36:37]
	s_waitcnt lgkmcnt(0)
	s_nop 1
	v_mov_b64_e32 v[62:63], v[200:201]
	v_mov_b64_e32 v[64:65], v[202:203]
	ds_bpermute_b32 v66, v74, v83
	s_waitcnt lgkmcnt(0)
	v_add_f32_e32 v66, v83, v66
	ds_bpermute_b32 v67, v75, v66
	s_waitcnt lgkmcnt(0)
	v_add_f32_e32 v66, v66, v67
	ds_bpermute_b32 v67, v76, v66
	s_waitcnt lgkmcnt(0)
	v_add_f32_e32 v66, v66, v67
	ds_bpermute_b32 v67, v77, v66
	s_waitcnt lgkmcnt(0)
	v_add_f32_e32 v68, v66, v67
	ds_bpermute_b32 v69, v78, v68
	v_lshlrev_b32_e32 v66, 16, v60
	v_and_b32_e32 v67, 0xffff0000, v60
	v_lshlrev_b32_e32 v60, 16, v61
	v_and_b32_e32 v61, 0xffff0000, v61
	s_waitcnt lgkmcnt(0)
	v_add_f32_e32 v70, v68, v69
	ds_bpermute_b32 v71, v79, v70
	v_lshlrev_b32_e32 v68, 16, v58
	v_and_b32_e32 v69, 0xffff0000, v58
	s_waitcnt lgkmcnt(0)
	v_add_f32_e32 v58, v70, v71
	v_fmamk_f32 v58, v58, 0x3a800000, v80
	v_mul_f32_e32 v70, 0x4b800000, v58
	v_cmp_gt_f32_e32 vcc, s38, v58
	s_nop 1
	v_cndmask_b32_e32 v58, v58, v70, vcc
	v_rsq_f32_e32 v72, v58
	v_lshlrev_b32_e32 v58, 16, v59
	v_and_b32_e32 v59, 0xffff0000, v59
	v_lshl_add_u64 v[70:71], v[10:11], 0, s[34:35]
	v_mul_f32_e32 v73, 0x45800000, v72
	v_cndmask_b32_e32 v72, v72, v73, vcc
	v_pk_mul_f32 v[68:69], v[72:73], v[68:69] op_sel_hi:[0,1]
	v_pk_mul_f32 v[58:59], v[72:73], v[58:59] op_sel_hi:[0,1]
	s_nop 1
	v_pk_fma_f32 v[64:65], v[64:65], v[58:59], v[60:61]
	v_pk_fma_f32 v[62:63], v[62:63], v[68:69], v[66:67]
	v_cvt_pk_bf16_f32 v59, v64, v65
	v_cvt_pk_bf16_f32 v58, v62, v63
	global_store_dwordx2 v[70:71], v[58:59], off
	s_nop 1
	v_mov_b64_e32 v[58:59], v[204:205]
	v_mov_b64_e32 v[60:61], v[206:207]
	v_lshlrev_b32_e32 v68, 16, v56
	v_and_b32_e32 v69, 0xffff0000, v56
	v_lshlrev_b32_e32 v56, 16, v57
	v_and_b32_e32 v57, 0xffff0000, v57
	v_lshlrev_b32_e32 v66, 16, v54
	v_and_b32_e32 v67, 0xffff0000, v54
	v_lshlrev_b32_e32 v54, 16, v55
	v_and_b32_e32 v55, 0xffff0000, v55
	v_pk_mul_f32 v[68:69], v[72:73], v[68:69] op_sel_hi:[0,1]
	v_pk_mul_f32 v[56:57], v[72:73], v[56:57] op_sel_hi:[0,1]
	v_mul_f32_e32 v63, v63, v63
	v_mul_f32_e32 v65, v65, v65
	v_fmac_f32_e32 v63, v62, v62
	v_fmac_f32_e32 v65, v64, v64
	v_add_f32_e32 v62, v63, v65
	s_nop 1
	v_pk_fma_f32 v[60:61], v[60:61], v[56:57], v[54:55]
	v_pk_fma_f32 v[58:59], v[58:59], v[68:69], v[66:67]
	v_cvt_pk_bf16_f32 v55, v60, v61
	v_cvt_pk_bf16_f32 v54, v58, v59
	global_store_dwordx2 v[70:71], v[54:55], off offset:512
	s_nop 1
	v_mov_b64_e32 v[54:55], v[208:209]
	v_mov_b64_e32 v[56:57], v[210:211]
	v_lshlrev_b32_e32 v68, 16, v52
	v_and_b32_e32 v69, 0xffff0000, v52
	v_lshlrev_b32_e32 v52, 16, v53
	v_and_b32_e32 v53, 0xffff0000, v53
	v_lshlrev_b32_e32 v66, 16, v50
	v_and_b32_e32 v67, 0xffff0000, v50
	v_lshlrev_b32_e32 v50, 16, v51
	v_and_b32_e32 v51, 0xffff0000, v51
	v_pk_mul_f32 v[68:69], v[72:73], v[68:69] op_sel_hi:[0,1]
	v_pk_mul_f32 v[52:53], v[72:73], v[52:53] op_sel_hi:[0,1]
	v_mul_f32_e32 v59, v59, v59
	v_mul_f32_e32 v61, v61, v61
	v_fmac_f32_e32 v59, v58, v58
	v_fmac_f32_e32 v61, v60, v60
	v_add_f32_e32 v58, v59, v61
	v_add_f32_e32 v58, v62, v58
	s_nop 1
	v_pk_fma_f32 v[56:57], v[56:57], v[52:53], v[50:51]
	v_pk_fma_f32 v[54:55], v[54:55], v[68:69], v[66:67]
	v_cvt_pk_bf16_f32 v51, v56, v57
	v_cvt_pk_bf16_f32 v50, v54, v55
	global_store_dwordx2 v[70:71], v[50:51], off offset:1024
	s_nop 1
	v_mov_b64_e32 v[50:51], v[212:213]
	v_mov_b64_e32 v[52:53], v[214:215]
	v_lshlrev_b32_e32 v68, 16, v48
	v_and_b32_e32 v69, 0xffff0000, v48
	v_lshlrev_b32_e32 v48, 16, v49
	v_and_b32_e32 v49, 0xffff0000, v49
	v_lshlrev_b32_e32 v66, 16, v46
	v_and_b32_e32 v67, 0xffff0000, v46
	v_lshlrev_b32_e32 v46, 16, v47
	v_and_b32_e32 v47, 0xffff0000, v47
	v_pk_mul_f32 v[68:69], v[72:73], v[68:69] op_sel_hi:[0,1]
	v_pk_mul_f32 v[48:49], v[72:73], v[48:49] op_sel_hi:[0,1]
	v_mul_f32_e32 v55, v55, v55
	v_mul_f32_e32 v57, v57, v57
	v_fmac_f32_e32 v55, v54, v54
	v_fmac_f32_e32 v57, v56, v56
	v_add_f32_e32 v54, v55, v57
	v_add_f32_e32 v54, v54, v58
	s_nop 1
	v_pk_fma_f32 v[48:49], v[52:53], v[48:49], v[46:47]
	v_pk_fma_f32 v[50:51], v[50:51], v[68:69], v[66:67]
	v_mul_f32_e32 v47, v49, v49
	v_mul_f32_e32 v46, v51, v51
	v_fmac_f32_e32 v46, v50, v50
	v_fmac_f32_e32 v47, v48, v48
	v_add_f32_e32 v46, v46, v47
	v_add_f32_e32 v46, v46, v54
	ds_bpermute_b32 v47, v74, v46
	v_cvt_pk_bf16_f32 v50, v50, v51
	v_cvt_pk_bf16_f32 v51, v48, v49
	global_store_dwordx2 v[70:71], v[50:51], off offset:1536
	s_waitcnt lgkmcnt(0)
	v_add_f32_e32 v46, v46, v47
	ds_bpermute_b32 v47, v75, v46
	s_waitcnt lgkmcnt(0)
	v_add_f32_e32 v46, v46, v47
	ds_bpermute_b32 v47, v76, v46
	s_waitcnt lgkmcnt(0)
	v_add_f32_e32 v46, v46, v47
	ds_bpermute_b32 v47, v77, v46
	s_waitcnt lgkmcnt(0)
	v_add_f32_e32 v46, v46, v47
	ds_bpermute_b32 v47, v78, v46
	s_waitcnt lgkmcnt(0)
	v_add_f32_e32 v46, v46, v47
	ds_bpermute_b32 v47, v79, v46
	s_and_saveexec_b64 s[34:35], s[2:3]
	s_cbranch_execz .LBB0_1080
	s_waitcnt lgkmcnt(0)
	v_add_f32_e32 v46, v46, v47
	v_fmamk_f32 v46, v46, 0x3a800000, v80
	v_mul_f32_e32 v47, 0x4b800000, v46
	v_cmp_gt_f32_e32 vcc, s38, v46
	s_lshl_b64 s[30:31], s[30:31], 2
	s_add_u32 s30, s4, s30
	v_cndmask_b32_e32 v46, v46, v47, vcc
	v_rsq_f32_e32 v46, v46
	s_addc_u32 s31, s5, s31
	v_mul_f32_e32 v47, 0x45800000, v46
	v_cndmask_b32_e32 v46, v46, v47, vcc
	global_store_dword v1, v46, s[30:31]
; DI unsigned pk2(float lo, float hi) { f32x2_t v = {lo, hi}; bf16x2_t b = __builtin_convertvector(v, bf16x2_t); return __builtin_bit_cast(unsigned, b); }
; DI float bflo(unsigned u) { return __uint_as_float(u << 16); }
; DI float bfhi(unsigned u) { return __uint_as_float(u & 0xffff0000u); }
; template <int NR, bool XIN_BF, bool XOUT_BF> DI void resid_rows(const void* xin_, void* xout_, const bf16* d, const float* rsq, float coef, const float* pg, const float* ng, bf16* xn, int m0, int mstride, int lane, float* rs_out = nullptr) {
;     ...
;     for (int r = 0; r < NR; ++r) { const size_t m = (size_t)(m0 + r * mstride);
;         const float rr = rsqrtf(wave_sum(ss[r]) * (1.f / 1024.f) + EPS) * coef; float s2 = 0.f;
; #pragma unroll
;         for (int j = 0; j < 4; ++j) { const int c = 4 * lane + 256 * j; const f32x4 gg = *(const f32x4*)(pg + c);
;             const f32x4 df = {bflo(dv[r][j].x), bfhi(dv[r][j].x), bflo(dv[r][j].y), bfhi(dv[r][j].y)};
;             xv[r][j] = xv[r][j] + df * rr * gg;
;             if (XOUT_BF) { u32x2 w; w.x = pk2(xv[r][j][0], xv[r][j][1]); w.y = pk2(xv[r][j][2], xv[r][j][3]); *(u32x2*)((bf16*)xout_ + m * DM + c) = w; }
;             else __builtin_nontemporal_store(xv[r][j], (f32x4*)((float*)xout_ + m * DM + c));
;             s2 += (xv[r][j][0] * xv[r][j][0] + xv[r][j][1] * xv[r][j][1]) + (xv[r][j][2] * xv[r][j][2] + xv[r][j][3] * xv[r][j][3]); }
;         if (rs_out) { const float r2 = rsqrtf(wave_sum(s2) * (1.f / 1024.f) + EPS); if (lane == 0) rs_out[m] = r2; }
.LBB0_1080:
	s_or_b64 exec, exec, s[34:35]
	s_waitcnt lgkmcnt(0)
	s_nop 1
	v_mov_b64_e32 v[46:47], v[200:201]
	v_mov_b64_e32 v[48:49], v[202:203]
	ds_bpermute_b32 v50, v74, v82
	s_waitcnt lgkmcnt(0)
	v_add_f32_e32 v50, v82, v50
	ds_bpermute_b32 v51, v75, v50
	s_waitcnt lgkmcnt(0)
	v_add_f32_e32 v50, v50, v51
	ds_bpermute_b32 v51, v76, v50
	s_waitcnt lgkmcnt(0)
	v_add_f32_e32 v50, v50, v51
	ds_bpermute_b32 v51, v77, v50
	s_waitcnt lgkmcnt(0)
	v_add_f32_e32 v52, v50, v51
	ds_bpermute_b32 v53, v78, v52
	v_lshlrev_b32_e32 v50, 16, v44
	v_and_b32_e32 v51, 0xffff0000, v44
	v_lshlrev_b32_e32 v44, 16, v45
	v_and_b32_e32 v45, 0xffff0000, v45
	s_waitcnt lgkmcnt(0)
	v_add_f32_e32 v54, v52, v53
	ds_bpermute_b32 v55, v79, v54
	v_lshlrev_b32_e32 v52, 16, v42
	v_and_b32_e32 v53, 0xffff0000, v42
	s_waitcnt lgkmcnt(0)
	v_add_f32_e32 v42, v54, v55
	v_fmamk_f32 v42, v42, 0x3a800000, v80
	v_mul_f32_e32 v54, 0x4b800000, v42
	v_cmp_gt_f32_e32 vcc, s38, v42
	s_nop 1
	v_cndmask_b32_e32 v42, v42, v54, vcc
	v_rsq_f32_e32 v56, v42
	v_lshlrev_b32_e32 v42, 16, v43
	v_and_b32_e32 v43, 0xffff0000, v43
	v_lshl_add_u64 v[54:55], v[10:11], 0, s[28:29]
	v_mul_f32_e32 v57, 0x45800000, v56
	v_cndmask_b32_e32 v56, v56, v57, vcc
	v_pk_mul_f32 v[52:53], v[56:57], v[52:53] op_sel_hi:[0,1]
	v_pk_mul_f32 v[42:43], v[56:57], v[42:43] op_sel_hi:[0,1]
	s_nop 1
	v_pk_fma_f32 v[48:49], v[48:49], v[42:43], v[44:45]
	v_pk_fma_f32 v[46:47], v[46:47], v[52:53], v[50:51]
	v_cvt_pk_bf16_f32 v43, v48, v49
	v_cvt_pk_bf16_f32 v42, v46, v47
	global_store_dwordx2 v[54:55], v[42:43], off
	s_nop 1
	v_mov_b64_e32 v[42:43], v[204:205]
	v_mov_b64_e32 v[44:45], v[206:207]
	v_lshlrev_b32_e32 v52, 16, v40
	v_and_b32_e32 v53, 0xffff0000, v40
	v_lshlrev_b32_e32 v40, 16, v41
	v_and_b32_e32 v41, 0xffff0000, v41
	v_lshlrev_b32_e32 v50, 16, v38
	v_and_b32_e32 v51, 0xffff0000, v38
	v_lshlrev_b32_e32 v38, 16, v39
	v_and_b32_e32 v39, 0xffff0000, v39
	v_pk_mul_f32 v[52:53], v[56:57], v[52:53] op_sel_hi:[0,1]
	v_pk_mul_f32 v[40:41], v[56:57], v[40:41] op_sel_hi:[0,1]
	v_mul_f32_e32 v47, v47, v47
	v_mul_f32_e32 v49, v49, v49
	v_fmac_f32_e32 v47, v46, v46
	v_fmac_f32_e32 v49, v48, v48
	v_add_f32_e32 v46, v47, v49
	s_nop 1
	v_pk_fma_f32 v[44:45], v[44:45], v[40:41], v[38:39]
	v_pk_fma_f32 v[42:43], v[42:43], v[52:53], v[50:51]
	v_cvt_pk_bf16_f32 v39, v44, v45
	v_cvt_pk_bf16_f32 v38, v42, v43
	global_store_dwordx2 v[54:55], v[38:39], off offset:512
	s_nop 1
	v_mov_b64_e32 v[38:39], v[208:209]
	v_mov_b64_e32 v[40:41], v[210:211]
	v_lshlrev_b32_e32 v52, 16, v36
	v_and_b32_e32 v53, 0xffff0000, v36
	v_lshlrev_b32_e32 v36, 16, v37
	v_and_b32_e32 v37, 0xffff0000, v37
	v_lshlrev_b32_e32 v50, 16, v34
	v_and_b32_e32 v51, 0xffff0000, v34
	v_lshlrev_b32_e32 v34, 16, v35
	v_and_b32_e32 v35, 0xffff0000, v35
	v_pk_mul_f32 v[52:53], v[56:57], v[52:53] op_sel_hi:[0,1]
	v_pk_mul_f32 v[36:37], v[56:57], v[36:37] op_sel_hi:[0,1]
	v_mul_f32_e32 v43, v43, v43
	v_mul_f32_e32 v45, v45, v45
	v_fmac_f32_e32 v43, v42, v42
	v_fmac_f32_e32 v45, v44, v44
	v_add_f32_e32 v42, v43, v45
	v_add_f32_e32 v42, v46, v42
	s_nop 1
	v_pk_fma_f32 v[40:41], v[40:41], v[36:37], v[34:35]
	v_pk_fma_f32 v[38:39], v[38:39], v[52:53], v[50:51]
	v_cvt_pk_bf16_f32 v35, v40, v41
	v_cvt_pk_bf16_f32 v34, v38, v39
	global_store_dwordx2 v[54:55], v[34:35], off offset:1024
	s_nop 1
	v_mov_b64_e32 v[34:35], v[212:213]
	v_mov_b64_e32 v[36:37], v[214:215]
	v_lshlrev_b32_e32 v52, 16, v32
	v_and_b32_e32 v53, 0xffff0000, v32
	v_lshlrev_b32_e32 v32, 16, v33
	v_and_b32_e32 v33, 0xffff0000, v33
	v_lshlrev_b32_e32 v50, 16, v30
	v_and_b32_e32 v51, 0xffff0000, v30
	v_lshlrev_b32_e32 v30, 16, v31
	v_and_b32_e32 v31, 0xffff0000, v31
	v_pk_mul_f32 v[52:53], v[56:57], v[52:53] op_sel_hi:[0,1]
	v_pk_mul_f32 v[32:33], v[56:57], v[32:33] op_sel_hi:[0,1]
	v_mul_f32_e32 v39, v39, v39
	v_mul_f32_e32 v41, v41, v41
	v_fmac_f32_e32 v39, v38, v38
	v_fmac_f32_e32 v41, v40, v40
	v_add_f32_e32 v38, v39, v41
	v_add_f32_e32 v38, v38, v42
	s_waitcnt vmcnt(0)
	v_pk_fma_f32 v[32:33], v[36:37], v[32:33], v[30:31]
	v_pk_fma_f32 v[34:35], v[34:35], v[52:53], v[50:51]
	v_mul_f32_e32 v31, v33, v33
	v_mul_f32_e32 v30, v35, v35
	v_fmac_f32_e32 v30, v34, v34
	v_fmac_f32_e32 v31, v32, v32
	v_add_f32_e32 v30, v30, v31
	v_add_f32_e32 v30, v30, v38
	ds_bpermute_b32 v31, v74, v30
	v_cvt_pk_bf16_f32 v34, v34, v35
	v_cvt_pk_bf16_f32 v35, v32, v33
	global_store_dwordx2 v[54:55], v[34:35], off offset:1536
	s_waitcnt lgkmcnt(0)
	v_add_f32_e32 v30, v30, v31
	ds_bpermute_b32 v31, v75, v30
	s_waitcnt lgkmcnt(0)
	v_add_f32_e32 v30, v30, v31
	ds_bpermute_b32 v31, v76, v30
	s_waitcnt lgkmcnt(0)
	v_add_f32_e32 v30, v30, v31
	ds_bpermute_b32 v31, v77, v30
	s_waitcnt lgkmcnt(0)
	v_add_f32_e32 v30, v30, v31
	ds_bpermute_b32 v31, v78, v30
	s_waitcnt lgkmcnt(0)
	v_add_f32_e32 v30, v30, v31
	ds_bpermute_b32 v31, v79, v30
	s_and_saveexec_b64 s[28:29], s[2:3]
	s_cbranch_execz .LBB0_1082
	s_waitcnt lgkmcnt(0)
	v_add_f32_e32 v30, v30, v31
	v_fmamk_f32 v30, v30, 0x3a800000, v80
	v_mul_f32_e32 v31, 0x4b800000, v30
	v_cmp_gt_f32_e32 vcc, s38, v30
	s_lshl_b64 s[24:25], s[24:25], 2
	s_add_u32 s24, s4, s24
	v_cndmask_b32_e32 v30, v30, v31, vcc
	v_rsq_f32_e32 v30, v30
	s_addc_u32 s25, s5, s25
	v_mul_f32_e32 v31, 0x45800000, v30
	v_cndmask_b32_e32 v30, v30, v31, vcc
	global_store_dword v1, v30, s[24:25]
; DI unsigned pk2(float lo, float hi) { f32x2_t v = {lo, hi}; bf16x2_t b = __builtin_convertvector(v, bf16x2_t); return __builtin_bit_cast(unsigned, b); }
; DI float bflo(unsigned u) { return __uint_as_float(u << 16); }
; DI float bfhi(unsigned u) { return __uint_as_float(u & 0xffff0000u); }
; template <int NR, bool XIN_BF, bool XOUT_BF> DI void resid_rows(const void* xin_, void* xout_, const bf16* d, const float* rsq, float coef, const float* pg, const float* ng, bf16* xn, int m0, int mstride, int lane, float* rs_out = nullptr) {
;     ...
;     for (int r = 0; r < NR; ++r) { const size_t m = (size_t)(m0 + r * mstride);
;         const float rr = rsqrtf(wave_sum(ss[r]) * (1.f / 1024.f) + EPS) * coef; float s2 = 0.f;
; #pragma unroll
;         for (int j = 0; j < 4; ++j) { const int c = 4 * lane + 256 * j; const f32x4 gg = *(const f32x4*)(pg + c);
;             const f32x4 df = {bflo(dv[r][j].x), bfhi(dv[r][j].x), bflo(dv[r][j].y), bfhi(dv[r][j].y)};
;             xv[r][j] = xv[r][j] + df * rr * gg;
;             if (XOUT_BF) { u32x2 w; w.x = pk2(xv[r][j][0], xv[r][j][1]); w.y = pk2(xv[r][j][2], xv[r][j][3]); *(u32x2*)((bf16*)xout_ + m * DM + c) = w; }
;             else __builtin_nontemporal_store(xv[r][j], (f32x4*)((float*)xout_ + m * DM + c));
;             s2 += (xv[r][j][0] * xv[r][j][0] + xv[r][j][1] * xv[r][j][1]) + (xv[r][j][2] * xv[r][j][2] + xv[r][j][3] * xv[r][j][3]); }
;         if (rs_out) { const float r2 = rsqrtf(wave_sum(s2) * (1.f / 1024.f) + EPS); if (lane == 0) rs_out[m] = r2; }
.LBB0_1082:
	s_or_b64 exec, exec, s[28:29]
	s_waitcnt lgkmcnt(0)
	s_nop 1
	v_mov_b64_e32 v[30:31], v[200:201]
	v_mov_b64_e32 v[32:33], v[202:203]
	ds_bpermute_b32 v34, v74, v81
	s_waitcnt lgkmcnt(0)
	v_add_f32_e32 v34, v81, v34
	ds_bpermute_b32 v35, v75, v34
	s_waitcnt lgkmcnt(0)
	v_add_f32_e32 v34, v34, v35
	ds_bpermute_b32 v35, v76, v34
	s_waitcnt lgkmcnt(0)
	v_add_f32_e32 v34, v34, v35
	ds_bpermute_b32 v35, v77, v34
	s_waitcnt lgkmcnt(0)
	v_add_f32_e32 v36, v34, v35
	ds_bpermute_b32 v37, v78, v36
	v_lshlrev_b32_e32 v34, 16, v26
	v_and_b32_e32 v35, 0xffff0000, v26
	v_lshlrev_b32_e32 v26, 16, v27
	v_and_b32_e32 v27, 0xffff0000, v27
	s_waitcnt lgkmcnt(0)
	v_add_f32_e32 v38, v36, v37
	ds_bpermute_b32 v39, v79, v38
	v_lshlrev_b32_e32 v36, 16, v28
	v_and_b32_e32 v37, 0xffff0000, v28
	s_waitcnt lgkmcnt(0)
	v_add_f32_e32 v28, v38, v39
	v_fmamk_f32 v28, v28, 0x3a800000, v80
	v_mul_f32_e32 v38, 0x4b800000, v28
	v_cmp_gt_f32_e32 vcc, s38, v28
	s_nop 1
	v_cndmask_b32_e32 v28, v28, v38, vcc
	v_rsq_f32_e32 v40, v28
	v_lshlrev_b32_e32 v28, 16, v29
	v_and_b32_e32 v29, 0xffff0000, v29
	v_lshl_add_u64 v[38:39], v[10:11], 0, s[26:27]
	v_mul_f32_e32 v41, 0x45800000, v40
	v_cndmask_b32_e32 v40, v40, v41, vcc
	v_pk_mul_f32 v[36:37], v[40:41], v[36:37] op_sel_hi:[0,1]
	v_pk_mul_f32 v[28:29], v[40:41], v[28:29] op_sel_hi:[0,1]
	s_nop 1
	v_pk_fma_f32 v[32:33], v[32:33], v[28:29], v[26:27]
	v_pk_fma_f32 v[30:31], v[30:31], v[36:37], v[34:35]
	v_cvt_pk_bf16_f32 v27, v32, v33
	v_cvt_pk_bf16_f32 v26, v30, v31
	global_store_dwordx2 v[38:39], v[26:27], off
	s_nop 1
	v_mov_b64_e32 v[26:27], v[204:205]
	v_mov_b64_e32 v[28:29], v[206:207]
	v_lshlrev_b32_e32 v36, 16, v24
	v_and_b32_e32 v37, 0xffff0000, v24
	v_lshlrev_b32_e32 v24, 16, v25
	v_and_b32_e32 v25, 0xffff0000, v25
	v_lshlrev_b32_e32 v34, 16, v22
	v_and_b32_e32 v35, 0xffff0000, v22
	v_lshlrev_b32_e32 v22, 16, v23
	v_and_b32_e32 v23, 0xffff0000, v23
	v_pk_mul_f32 v[36:37], v[40:41], v[36:37] op_sel_hi:[0,1]
	v_pk_mul_f32 v[24:25], v[40:41], v[24:25] op_sel_hi:[0,1]
	v_mul_f32_e32 v31, v31, v31
	v_mul_f32_e32 v33, v33, v33
	v_fmac_f32_e32 v31, v30, v30
	v_fmac_f32_e32 v33, v32, v32
	v_add_f32_e32 v30, v31, v33
	s_nop 1
	v_pk_fma_f32 v[28:29], v[28:29], v[24:25], v[22:23]
	v_pk_fma_f32 v[26:27], v[26:27], v[36:37], v[34:35]
	v_cvt_pk_bf16_f32 v23, v28, v29
	v_cvt_pk_bf16_f32 v22, v26, v27
	global_store_dwordx2 v[38:39], v[22:23], off offset:512
	s_nop 1
	v_mov_b64_e32 v[22:23], v[208:209]
	v_mov_b64_e32 v[24:25], v[210:211]
	v_lshlrev_b32_e32 v36, 16, v20
	v_and_b32_e32 v37, 0xffff0000, v20
	v_lshlrev_b32_e32 v20, 16, v21
	v_and_b32_e32 v21, 0xffff0000, v21
	v_lshlrev_b32_e32 v34, 16, v18
	v_and_b32_e32 v35, 0xffff0000, v18
	v_lshlrev_b32_e32 v18, 16, v19
	v_and_b32_e32 v19, 0xffff0000, v19
	v_pk_mul_f32 v[36:37], v[40:41], v[36:37] op_sel_hi:[0,1]
	v_pk_mul_f32 v[20:21], v[40:41], v[20:21] op_sel_hi:[0,1]
	v_mul_f32_e32 v27, v27, v27
	v_mul_f32_e32 v29, v29, v29
	v_fmac_f32_e32 v27, v26, v26
	v_fmac_f32_e32 v29, v28, v28
	v_add_f32_e32 v26, v27, v29
	v_add_f32_e32 v26, v30, v26
	s_nop 1
	v_pk_fma_f32 v[24:25], v[24:25], v[20:21], v[18:19]
	v_pk_fma_f32 v[22:23], v[22:23], v[36:37], v[34:35]
	v_cvt_pk_bf16_f32 v19, v24, v25
	v_cvt_pk_bf16_f32 v18, v22, v23
	global_store_dwordx2 v[38:39], v[18:19], off offset:1024
	s_nop 1
	v_mov_b64_e32 v[18:19], v[212:213]
	v_mov_b64_e32 v[20:21], v[214:215]
	v_lshlrev_b32_e32 v36, 16, v16
	v_and_b32_e32 v37, 0xffff0000, v16
	v_lshlrev_b32_e32 v16, 16, v17
	v_and_b32_e32 v17, 0xffff0000, v17
	v_lshlrev_b32_e32 v34, 16, v14
	v_and_b32_e32 v35, 0xffff0000, v14
	v_lshlrev_b32_e32 v14, 16, v15
	v_and_b32_e32 v15, 0xffff0000, v15
	v_pk_mul_f32 v[36:37], v[40:41], v[36:37] op_sel_hi:[0,1]
	v_pk_mul_f32 v[16:17], v[40:41], v[16:17] op_sel_hi:[0,1]
	v_mul_f32_e32 v23, v23, v23
	v_mul_f32_e32 v25, v25, v25
	v_fmac_f32_e32 v23, v22, v22
	v_fmac_f32_e32 v25, v24, v24
	v_add_f32_e32 v22, v23, v25
	v_add_f32_e32 v22, v22, v26
	s_nop 1
	v_pk_fma_f32 v[16:17], v[20:21], v[16:17], v[14:15]
	v_pk_fma_f32 v[18:19], v[18:19], v[36:37], v[34:35]
	v_mul_f32_e32 v15, v17, v17
	v_mul_f32_e32 v14, v19, v19
	v_fmac_f32_e32 v14, v18, v18
	v_fmac_f32_e32 v15, v16, v16
	v_add_f32_e32 v14, v14, v15
	v_add_f32_e32 v14, v14, v22
	ds_bpermute_b32 v15, v74, v14
	v_cvt_pk_bf16_f32 v18, v18, v19
	v_cvt_pk_bf16_f32 v19, v16, v17
	global_store_dwordx2 v[38:39], v[18:19], off offset:1536
	s_waitcnt lgkmcnt(0)
	v_add_f32_e32 v14, v14, v15
	ds_bpermute_b32 v15, v75, v14
	s_waitcnt lgkmcnt(0)
	v_add_f32_e32 v14, v14, v15
	ds_bpermute_b32 v15, v76, v14
	s_waitcnt lgkmcnt(0)
	v_add_f32_e32 v14, v14, v15
	ds_bpermute_b32 v15, v77, v14
	s_waitcnt lgkmcnt(0)
	v_add_f32_e32 v14, v14, v15
	ds_bpermute_b32 v15, v78, v14
	s_waitcnt lgkmcnt(0)
	v_add_f32_e32 v14, v14, v15
	ds_bpermute_b32 v15, v79, v14
	s_and_saveexec_b64 s[24:25], s[2:3]
	s_cbranch_execz .LBB0_1067
	s_waitcnt lgkmcnt(0)
	v_add_f32_e32 v14, v14, v15
	v_fmamk_f32 v14, v14, 0x3a800000, v80
	v_mul_f32_e32 v15, 0x4b800000, v14
	v_cmp_gt_f32_e32 vcc, s38, v14
	s_lshl_b64 s[22:23], s[22:23], 2
	s_add_u32 s22, s4, s22
	v_cndmask_b32_e32 v14, v14, v15, vcc
	v_rsq_f32_e32 v14, v14
	s_addc_u32 s23, s5, s23
	v_mul_f32_e32 v15, 0x45800000, v14
	v_cndmask_b32_e32 v14, v14, v15, vcc
	global_store_dword v1, v14, s[22:23]
	s_branch .LBB0_1067

; __device__ __forceinline__ unsigned cvt_pk_bf16(float lo, float hi) { unsigned r; asm volatile("v_cvt_pk_bf16_f32 %0, %1, %2" : "=v"(r) : "v"(lo), "v"(hi)); return r; }
;     __device__ __forceinline__ void operator()(const f32x4 (&acc)[2][2][4][2], const Unit& u, int wr, int wc, int fr, int fq) const {
;         const int row0 = u.pm * BM + wr * 64 + fr, col0 = u.pn * 128 + wc * 32 + 8 * fq;
; #pragma unroll
;         for (int ai = 0; ai < 2; ++ai)
; #pragma unroll
;             for (int m = 0; m < 4; ++m) {
;                 bf16_t* p = O + (size_t)(row0 + ai * HALF + m * 16) * ldc + col0;
;                 float h[8]; const float rsc = rs ? rs[row0 + ai * HALF + m * 16] : 1.0f;
; #pragma unroll
;                 for (int n = 0; n < 2; ++n)
; #pragma unroll
;                     for (int i = 0; i < 4; ++i) { const float g = acc[ai][0][m][n][i] * rsc, uu = acc[ai][1][m][n][i] * rsc; h[4 * n + i] = g * __builtin_amdgcn_rcpf(1.0f + __builtin_amdgcn_exp2f(g)) * uu; }
;                 u32x4 w; w.x = cvt_pk_bf16(h[0], h[1]); w.y = cvt_pk_bf16(h[2], h[3]); w.z = cvt_pk_bf16(h[4], h[5]); w.w = cvt_pk_bf16(h[6], h[7]);
;                 *(u32x4*)p = w;
;             }
.LBB0_1149:
	s_mov_b32 s98, 0x16000
	s_mov_b32 s99, 0
	s_mov_b32 s100, 0x6e000
	s_mov_b32 s101, 0
	v_lshl_add_u32 v146, s2, 8, v149
	v_ashrrev_i32_e32 v147, 31, v146
	v_lshl_add_u64 v[144:145], v[146:147], 2, s[4:5]
	global_load_dword v178, v[144:145], off
	global_load_dword v180, v[144:145], off offset:64
	global_load_dword v184, v[144:145], off offset:128
	global_load_dword v186, v[144:145], off offset:192
	global_load_dword v188, v[144:145], off offset:512
	global_load_dword v190, v[144:145], off offset:576
	global_load_dword v192, v[144:145], off offset:640
	global_load_dword v194, v[144:145], off offset:704
	v_mov_b64_e32 v[156:157], s[76:77]
	v_mov_b32_e32 v176, 1.0
	v_mad_i64_i32 v[198:199], s[26:27], v146, s46, v[156:157]
	v_lshl_or_b32 v144, s24, 7, v152
	v_ashrrev_i32_e32 v145, 31, v144
	v_lshl_add_u64 v[198:199], v[144:145], 1, v[198:199]
	v_lshl_add_u64 v[200:201], v[198:199], 0, s[98:99]
	v_lshl_add_u64 v[202:203], v[200:201], 0, s[98:99]
	v_lshl_add_u64 v[204:205], v[202:203], 0, s[98:99]
	v_lshl_add_u64 v[206:207], v[204:205], 0, s[100:101]
	v_lshl_add_u64 v[208:209], v[206:207], 0, s[98:99]
	v_lshl_add_u64 v[210:211], v[208:209], 0, s[98:99]
	v_lshl_add_u64 v[212:213], v[210:211], 0, s[98:99]
	s_waitcnt vmcnt(0)
	v_pk_mul_f32 v[124:125], v[124:125], v[178:179] op_sel_hi:[1,0]
	v_pk_mul_f32 v[126:127], v[126:127], v[178:179] op_sel_hi:[1,0]
	v_pk_mul_f32 v[116:117], v[116:117], v[178:179] op_sel_hi:[1,0]
	v_pk_mul_f32 v[118:119], v[118:119], v[178:179] op_sel_hi:[1,0]
	v_pk_mul_f32 v[120:121], v[120:121], v[178:179] op_sel_hi:[1,0]
	v_pk_mul_f32 v[122:123], v[122:123], v[178:179] op_sel_hi:[1,0]
	v_pk_mul_f32 v[112:113], v[112:113], v[178:179] op_sel_hi:[1,0]
	v_pk_mul_f32 v[114:115], v[114:115], v[178:179] op_sel_hi:[1,0]
	v_pk_mul_f32 v[108:109], v[108:109], v[180:181] op_sel_hi:[1,0]
	v_pk_mul_f32 v[110:111], v[110:111], v[180:181] op_sel_hi:[1,0]
	v_pk_mul_f32 v[100:101], v[100:101], v[180:181] op_sel_hi:[1,0]
	v_pk_mul_f32 v[102:103], v[102:103], v[180:181] op_sel_hi:[1,0]
	v_pk_mul_f32 v[104:105], v[104:105], v[180:181] op_sel_hi:[1,0]
	v_pk_mul_f32 v[106:107], v[106:107], v[180:181] op_sel_hi:[1,0]
	v_pk_mul_f32 v[96:97], v[96:97], v[180:181] op_sel_hi:[1,0]
	v_pk_mul_f32 v[98:99], v[98:99], v[180:181] op_sel_hi:[1,0]
	v_exp_f32_e32 v160, v124
	v_pk_mul_f32 v[92:93], v[92:93], v[184:185] op_sel_hi:[1,0]
	v_exp_f32_e32 v161, v125
	v_pk_mul_f32 v[94:95], v[94:95], v[184:185] op_sel_hi:[1,0]
	v_exp_f32_e32 v162, v126
	v_pk_mul_f32 v[84:85], v[84:85], v[184:185] op_sel_hi:[1,0]
	v_exp_f32_e32 v163, v127
	v_pk_mul_f32 v[86:87], v[86:87], v[184:185] op_sel_hi:[1,0]
	v_exp_f32_e32 v164, v116
	v_pk_mul_f32 v[88:89], v[88:89], v[184:185] op_sel_hi:[1,0]
	v_exp_f32_e32 v165, v117
	v_pk_mul_f32 v[90:91], v[90:91], v[184:185] op_sel_hi:[1,0]
	v_exp_f32_e32 v166, v118
	v_pk_mul_f32 v[80:81], v[80:81], v[184:185] op_sel_hi:[1,0]
	v_exp_f32_e32 v167, v119
	v_pk_mul_f32 v[82:83], v[82:83], v[184:185] op_sel_hi:[1,0]
	v_exp_f32_e32 v168, v108
	v_pk_mul_f32 v[76:77], v[76:77], v[186:187] op_sel_hi:[1,0]
	v_exp_f32_e32 v169, v109
	v_pk_mul_f32 v[78:79], v[78:79], v[186:187] op_sel_hi:[1,0]
	v_exp_f32_e32 v170, v110
	v_pk_mul_f32 v[68:69], v[68:69], v[186:187] op_sel_hi:[1,0]
	v_exp_f32_e32 v171, v111
	v_pk_mul_f32 v[70:71], v[70:71], v[186:187] op_sel_hi:[1,0]
	v_exp_f32_e32 v172, v100
	v_pk_mul_f32 v[72:73], v[72:73], v[186:187] op_sel_hi:[1,0]
	v_exp_f32_e32 v173, v101
	v_pk_mul_f32 v[74:75], v[74:75], v[186:187] op_sel_hi:[1,0]
	v_exp_f32_e32 v174, v102
	v_pk_mul_f32 v[64:65], v[64:65], v[186:187] op_sel_hi:[1,0]
	v_exp_f32_e32 v175, v103
	v_pk_mul_f32 v[66:67], v[66:67], v[186:187] op_sel_hi:[1,0]
	v_pk_add_f32 v[160:161], v[160:161], v[176:177] op_sel_hi:[1,0]
	v_pk_add_f32 v[162:163], v[162:163], v[176:177] op_sel_hi:[1,0]
	v_pk_add_f32 v[164:165], v[164:165], v[176:177] op_sel_hi:[1,0]
	v_pk_add_f32 v[166:167], v[166:167], v[176:177] op_sel_hi:[1,0]
	v_pk_add_f32 v[168:169], v[168:169], v[176:177] op_sel_hi:[1,0]
	v_pk_add_f32 v[170:171], v[170:171], v[176:177] op_sel_hi:[1,0]
	v_pk_add_f32 v[172:173], v[172:173], v[176:177] op_sel_hi:[1,0]
	v_pk_add_f32 v[174:175], v[174:175], v[176:177] op_sel_hi:[1,0]
	v_rcp_f32_e32 v160, v160
	v_rcp_f32_e32 v161, v161
	v_rcp_f32_e32 v162, v162
	v_rcp_f32_e32 v163, v163
	v_rcp_f32_e32 v164, v164
	v_rcp_f32_e32 v165, v165
	v_rcp_f32_e32 v166, v166
	v_rcp_f32_e32 v167, v167
	v_rcp_f32_e32 v168, v168
	v_rcp_f32_e32 v169, v169
	v_rcp_f32_e32 v170, v170
	v_rcp_f32_e32 v171, v171
	v_rcp_f32_e32 v172, v172
	v_rcp_f32_e32 v173, v173
	v_rcp_f32_e32 v174, v174
	v_rcp_f32_e32 v175, v175
	v_pk_mul_f32 v[124:125], v[124:125], v[160:161]
	v_exp_f32_e32 v160, v92
	v_pk_mul_f32 v[126:127], v[126:127], v[162:163]
	v_exp_f32_e32 v161, v93
	v_pk_mul_f32 v[116:117], v[116:117], v[164:165]
	v_exp_f32_e32 v162, v94
	v_pk_mul_f32 v[118:119], v[118:119], v[166:167]
	v_exp_f32_e32 v163, v95
	v_pk_mul_f32 v[108:109], v[108:109], v[168:169]
	v_exp_f32_e32 v164, v84
	v_pk_mul_f32 v[110:111], v[110:111], v[170:171]
	v_exp_f32_e32 v165, v85
	v_pk_mul_f32 v[100:101], v[100:101], v[172:173]
	v_exp_f32_e32 v166, v86
	v_pk_mul_f32 v[102:103], v[102:103], v[174:175]
	v_exp_f32_e32 v167, v87
	v_pk_mul_f32 v[120:121], v[124:125], v[120:121]
	v_exp_f32_e32 v168, v76
	v_pk_mul_f32 v[122:123], v[126:127], v[122:123]
	v_exp_f32_e32 v169, v77
	v_pk_mul_f32 v[112:113], v[116:117], v[112:113]
	v_exp_f32_e32 v170, v78
	v_pk_mul_f32 v[114:115], v[118:119], v[114:115]
	v_exp_f32_e32 v171, v79
	v_pk_mul_f32 v[104:105], v[108:109], v[104:105]
	v_exp_f32_e32 v172, v68
	v_pk_mul_f32 v[106:107], v[110:111], v[106:107]
	v_exp_f32_e32 v173, v69
; __device__ __forceinline__ unsigned cvt_pk_bf16(float lo, float hi) { unsigned r; asm volatile("v_cvt_pk_bf16_f32 %0, %1, %2" : "=v"(r) : "v"(lo), "v"(hi)); return r; }
;     __device__ __forceinline__ void operator()(const f32x4 (&acc)[2][2][4][2], const Unit& u, int wr, int wc, int fr, int fq) const {
;         const int row0 = u.pm * BM + wr * 64 + fr, col0 = u.pn * 128 + wc * 32 + 8 * fq;
; #pragma unroll
;         for (int ai = 0; ai < 2; ++ai)
; #pragma unroll
;             for (int m = 0; m < 4; ++m) {
;                 bf16_t* p = O + (size_t)(row0 + ai * HALF + m * 16) * ldc + col0;
;                 float h[8]; const float rsc = rs ? rs[row0 + ai * HALF + m * 16] : 1.0f;
; #pragma unroll
;                 for (int n = 0; n < 2; ++n)
; #pragma unroll
;                     for (int i = 0; i < 4; ++i) { const float g = acc[ai][0][m][n][i] * rsc, uu = acc[ai][1][m][n][i] * rsc; h[4 * n + i] = g * __builtin_amdgcn_rcpf(1.0f + __builtin_amdgcn_exp2f(g)) * uu; }
;                 u32x4 w; w.x = cvt_pk_bf16(h[0], h[1]); w.y = cvt_pk_bf16(h[2], h[3]); w.z = cvt_pk_bf16(h[4], h[5]); w.w = cvt_pk_bf16(h[6], h[7]);
;                 *(u32x4*)p = w;
;             }
	v_pk_mul_f32 v[96:97], v[100:101], v[96:97]
	v_exp_f32_e32 v174, v70
	v_pk_mul_f32 v[98:99], v[102:103], v[98:99]
	v_exp_f32_e32 v175, v71
	v_pk_add_f32 v[160:161], v[160:161], v[176:177] op_sel_hi:[1,0]
	v_pk_add_f32 v[162:163], v[162:163], v[176:177] op_sel_hi:[1,0]
	v_pk_add_f32 v[164:165], v[164:165], v[176:177] op_sel_hi:[1,0]
	v_pk_add_f32 v[166:167], v[166:167], v[176:177] op_sel_hi:[1,0]
	v_pk_add_f32 v[168:169], v[168:169], v[176:177] op_sel_hi:[1,0]
	v_pk_add_f32 v[170:171], v[170:171], v[176:177] op_sel_hi:[1,0]
	v_pk_add_f32 v[172:173], v[172:173], v[176:177] op_sel_hi:[1,0]
	v_pk_add_f32 v[174:175], v[174:175], v[176:177] op_sel_hi:[1,0]
	v_rcp_f32_e32 v160, v160
	v_cvt_pk_bf16_f32 v116, v120, v121
	v_rcp_f32_e32 v161, v161
	v_cvt_pk_bf16_f32 v117, v122, v123
	v_rcp_f32_e32 v162, v162
	v_cvt_pk_bf16_f32 v118, v112, v113
	v_rcp_f32_e32 v163, v163
	v_cvt_pk_bf16_f32 v119, v114, v115
	v_rcp_f32_e32 v164, v164
	v_cvt_pk_bf16_f32 v100, v104, v105
	v_rcp_f32_e32 v165, v165
	v_cvt_pk_bf16_f32 v101, v106, v107
	v_rcp_f32_e32 v166, v166
	v_cvt_pk_bf16_f32 v102, v96, v97
	v_rcp_f32_e32 v167, v167
	v_cvt_pk_bf16_f32 v103, v98, v99
	v_rcp_f32_e32 v168, v168
	global_store_dwordx4 v[198:199], v[116:119], off
	v_rcp_f32_e32 v169, v169
	global_store_dwordx4 v[200:201], v[100:103], off
	v_rcp_f32_e32 v170, v170
	v_pk_mul_f32 v[60:61], v[60:61], v[188:189] op_sel_hi:[1,0]
	v_rcp_f32_e32 v171, v171
	v_pk_mul_f32 v[62:63], v[62:63], v[188:189] op_sel_hi:[1,0]
	v_rcp_f32_e32 v172, v172
	v_pk_mul_f32 v[52:53], v[52:53], v[188:189] op_sel_hi:[1,0]
	v_rcp_f32_e32 v173, v173
	v_pk_mul_f32 v[54:55], v[54:55], v[188:189] op_sel_hi:[1,0]
	v_rcp_f32_e32 v174, v174
	v_pk_mul_f32 v[56:57], v[56:57], v[188:189] op_sel_hi:[1,0]
	v_rcp_f32_e32 v175, v175
	v_pk_mul_f32 v[58:59], v[58:59], v[188:189] op_sel_hi:[1,0]
	v_pk_mul_f32 v[48:49], v[48:49], v[188:189] op_sel_hi:[1,0]
	v_pk_mul_f32 v[50:51], v[50:51], v[188:189] op_sel_hi:[1,0]
	v_pk_mul_f32 v[44:45], v[44:45], v[190:191] op_sel_hi:[1,0]
	v_pk_mul_f32 v[46:47], v[46:47], v[190:191] op_sel_hi:[1,0]
	v_pk_mul_f32 v[36:37], v[36:37], v[190:191] op_sel_hi:[1,0]
	v_pk_mul_f32 v[38:39], v[38:39], v[190:191] op_sel_hi:[1,0]
	v_pk_mul_f32 v[40:41], v[40:41], v[190:191] op_sel_hi:[1,0]
	v_pk_mul_f32 v[42:43], v[42:43], v[190:191] op_sel_hi:[1,0]
	v_pk_mul_f32 v[32:33], v[32:33], v[190:191] op_sel_hi:[1,0]
	v_pk_mul_f32 v[34:35], v[34:35], v[190:191] op_sel_hi:[1,0]
	v_pk_mul_f32 v[92:93], v[92:93], v[160:161]
	v_exp_f32_e32 v160, v60
	v_pk_mul_f32 v[94:95], v[94:95], v[162:163]
	v_exp_f32_e32 v161, v61
	v_pk_mul_f32 v[84:85], v[84:85], v[164:165]
	v_exp_f32_e32 v162, v62
	v_pk_mul_f32 v[86:87], v[86:87], v[166:167]
	v_exp_f32_e32 v163, v63
	v_pk_mul_f32 v[76:77], v[76:77], v[168:169]
	v_exp_f32_e32 v164, v52
	v_pk_mul_f32 v[78:79], v[78:79], v[170:171]
	v_exp_f32_e32 v165, v53
	v_pk_mul_f32 v[68:69], v[68:69], v[172:173]
	v_exp_f32_e32 v166, v54
	v_pk_mul_f32 v[70:71], v[70:71], v[174:175]
	v_exp_f32_e32 v167, v55
	v_pk_mul_f32 v[88:89], v[92:93], v[88:89]
	v_exp_f32_e32 v168, v44
	v_pk_mul_f32 v[90:91], v[94:95], v[90:91]
	v_exp_f32_e32 v169, v45
	v_pk_mul_f32 v[80:81], v[84:85], v[80:81]
	v_exp_f32_e32 v170, v46
	v_pk_mul_f32 v[82:83], v[86:87], v[82:83]
	v_exp_f32_e32 v171, v47
	v_pk_mul_f32 v[72:73], v[76:77], v[72:73]
	v_exp_f32_e32 v172, v36
	v_pk_mul_f32 v[74:75], v[78:79], v[74:75]
	v_exp_f32_e32 v173, v37
	v_pk_mul_f32 v[64:65], v[68:69], v[64:65]
	v_exp_f32_e32 v174, v38
	v_pk_mul_f32 v[66:67], v[70:71], v[66:67]
	v_exp_f32_e32 v175, v39
	v_pk_add_f32 v[160:161], v[160:161], v[176:177] op_sel_hi:[1,0]
	v_pk_add_f32 v[162:163], v[162:163], v[176:177] op_sel_hi:[1,0]
	v_pk_add_f32 v[164:165], v[164:165], v[176:177] op_sel_hi:[1,0]
	v_pk_add_f32 v[166:167], v[166:167], v[176:177] op_sel_hi:[1,0]
	v_pk_add_f32 v[168:169], v[168:169], v[176:177] op_sel_hi:[1,0]
	v_pk_add_f32 v[170:171], v[170:171], v[176:177] op_sel_hi:[1,0]
	v_pk_add_f32 v[172:173], v[172:173], v[176:177] op_sel_hi:[1,0]
	v_pk_add_f32 v[174:175], v[174:175], v[176:177] op_sel_hi:[1,0]
	v_rcp_f32_e32 v160, v160
	v_cvt_pk_bf16_f32 v84, v88, v89
	v_rcp_f32_e32 v161, v161
	v_cvt_pk_bf16_f32 v85, v90, v91
	v_rcp_f32_e32 v162, v162
	v_cvt_pk_bf16_f32 v86, v80, v81
	v_rcp_f32_e32 v163, v163
	v_cvt_pk_bf16_f32 v87, v82, v83
	v_rcp_f32_e32 v164, v164
	v_cvt_pk_bf16_f32 v68, v72, v73
	v_rcp_f32_e32 v165, v165
	v_cvt_pk_bf16_f32 v69, v74, v75
	v_rcp_f32_e32 v166, v166
	v_cvt_pk_bf16_f32 v70, v64, v65
	v_rcp_f32_e32 v167, v167
	v_cvt_pk_bf16_f32 v71, v66, v67
	v_rcp_f32_e32 v168, v168
	global_store_dwordx4 v[202:203], v[84:87], off
	v_rcp_f32_e32 v169, v169
	global_store_dwordx4 v[204:205], v[68:71], off
	v_rcp_f32_e32 v170, v170
; __device__ __forceinline__ unsigned cvt_pk_bf16(float lo, float hi) { unsigned r; asm volatile("v_cvt_pk_bf16_f32 %0, %1, %2" : "=v"(r) : "v"(lo), "v"(hi)); return r; }
;     __device__ __forceinline__ void operator()(const f32x4 (&acc)[2][2][4][2], const Unit& u, int wr, int wc, int fr, int fq) const {
;         const int row0 = u.pm * BM + wr * 64 + fr, col0 = u.pn * 128 + wc * 32 + 8 * fq;
; #pragma unroll
;         for (int ai = 0; ai < 2; ++ai)
; #pragma unroll
;             for (int m = 0; m < 4; ++m) {
;                 bf16_t* p = O + (size_t)(row0 + ai * HALF + m * 16) * ldc + col0;
;                 float h[8]; const float rsc = rs ? rs[row0 + ai * HALF + m * 16] : 1.0f;
; #pragma unroll
;                 for (int n = 0; n < 2; ++n)
; #pragma unroll
;                     for (int i = 0; i < 4; ++i) { const float g = acc[ai][0][m][n][i] * rsc, uu = acc[ai][1][m][n][i] * rsc; h[4 * n + i] = g * __builtin_amdgcn_rcpf(1.0f + __builtin_amdgcn_exp2f(g)) * uu; }
;                 u32x4 w; w.x = cvt_pk_bf16(h[0], h[1]); w.y = cvt_pk_bf16(h[2], h[3]); w.z = cvt_pk_bf16(h[4], h[5]); w.w = cvt_pk_bf16(h[6], h[7]);
;                 *(u32x4*)p = w;
;             }
	v_pk_mul_f32 v[28:29], v[28:29], v[192:193] op_sel_hi:[1,0]
	v_rcp_f32_e32 v171, v171
	v_pk_mul_f32 v[30:31], v[30:31], v[192:193] op_sel_hi:[1,0]
	v_rcp_f32_e32 v172, v172
	v_pk_mul_f32 v[20:21], v[20:21], v[192:193] op_sel_hi:[1,0]
	v_rcp_f32_e32 v173, v173
	v_pk_mul_f32 v[22:23], v[22:23], v[192:193] op_sel_hi:[1,0]
	v_rcp_f32_e32 v174, v174
	v_pk_mul_f32 v[24:25], v[24:25], v[192:193] op_sel_hi:[1,0]
	v_rcp_f32_e32 v175, v175
	v_pk_mul_f32 v[26:27], v[26:27], v[192:193] op_sel_hi:[1,0]
	v_pk_mul_f32 v[16:17], v[16:17], v[192:193] op_sel_hi:[1,0]
	v_pk_mul_f32 v[18:19], v[18:19], v[192:193] op_sel_hi:[1,0]
	v_pk_mul_f32 v[12:13], v[12:13], v[194:195] op_sel_hi:[1,0]
	v_pk_mul_f32 v[14:15], v[14:15], v[194:195] op_sel_hi:[1,0]
	v_pk_mul_f32 v[4:5], v[4:5], v[194:195] op_sel_hi:[1,0]
	v_pk_mul_f32 v[6:7], v[6:7], v[194:195] op_sel_hi:[1,0]
	v_pk_mul_f32 v[8:9], v[8:9], v[194:195] op_sel_hi:[1,0]
	v_pk_mul_f32 v[10:11], v[10:11], v[194:195] op_sel_hi:[1,0]
	v_pk_mul_f32 v[0:1], v[0:1], v[194:195] op_sel_hi:[1,0]
	v_pk_mul_f32 v[2:3], v[2:3], v[194:195] op_sel_hi:[1,0]
	v_pk_mul_f32 v[60:61], v[60:61], v[160:161]
	v_exp_f32_e32 v160, v28
	v_pk_mul_f32 v[62:63], v[62:63], v[162:163]
	v_exp_f32_e32 v161, v29
	v_pk_mul_f32 v[52:53], v[52:53], v[164:165]
	v_exp_f32_e32 v162, v30
	v_pk_mul_f32 v[54:55], v[54:55], v[166:167]
	v_exp_f32_e32 v163, v31
	v_pk_mul_f32 v[44:45], v[44:45], v[168:169]
	v_exp_f32_e32 v164, v20
	v_pk_mul_f32 v[46:47], v[46:47], v[170:171]
	v_exp_f32_e32 v165, v21
	v_pk_mul_f32 v[36:37], v[36:37], v[172:173]
	v_exp_f32_e32 v166, v22
	v_pk_mul_f32 v[38:39], v[38:39], v[174:175]
	v_exp_f32_e32 v167, v23
	v_pk_mul_f32 v[56:57], v[60:61], v[56:57]
	v_exp_f32_e32 v168, v12
	v_pk_mul_f32 v[58:59], v[62:63], v[58:59]
	v_exp_f32_e32 v169, v13
	v_pk_mul_f32 v[48:49], v[52:53], v[48:49]
	v_exp_f32_e32 v170, v14
	v_pk_mul_f32 v[50:51], v[54:55], v[50:51]
	v_exp_f32_e32 v171, v15
	v_pk_mul_f32 v[40:41], v[44:45], v[40:41]
	v_exp_f32_e32 v172, v4
	v_pk_mul_f32 v[42:43], v[46:47], v[42:43]
	v_exp_f32_e32 v173, v5
	v_pk_mul_f32 v[32:33], v[36:37], v[32:33]
	v_exp_f32_e32 v174, v6
	v_pk_mul_f32 v[34:35], v[38:39], v[34:35]
	v_exp_f32_e32 v175, v7
	v_pk_add_f32 v[160:161], v[160:161], v[176:177] op_sel_hi:[1,0]
	v_pk_add_f32 v[162:163], v[162:163], v[176:177] op_sel_hi:[1,0]
	v_pk_add_f32 v[164:165], v[164:165], v[176:177] op_sel_hi:[1,0]
	v_pk_add_f32 v[166:167], v[166:167], v[176:177] op_sel_hi:[1,0]
	v_pk_add_f32 v[168:169], v[168:169], v[176:177] op_sel_hi:[1,0]
	v_pk_add_f32 v[170:171], v[170:171], v[176:177] op_sel_hi:[1,0]
	v_pk_add_f32 v[172:173], v[172:173], v[176:177] op_sel_hi:[1,0]
	v_pk_add_f32 v[174:175], v[174:175], v[176:177] op_sel_hi:[1,0]
	v_rcp_f32_e32 v160, v160
	v_cvt_pk_bf16_f32 v52, v56, v57
	v_rcp_f32_e32 v161, v161
	v_cvt_pk_bf16_f32 v53, v58, v59
	v_rcp_f32_e32 v162, v162
	v_cvt_pk_bf16_f32 v54, v48, v49
	v_rcp_f32_e32 v163, v163
	v_cvt_pk_bf16_f32 v55, v50, v51
	v_rcp_f32_e32 v164, v164
	v_cvt_pk_bf16_f32 v36, v40, v41
	v_rcp_f32_e32 v165, v165
	v_cvt_pk_bf16_f32 v37, v42, v43
	v_rcp_f32_e32 v166, v166
	v_cvt_pk_bf16_f32 v38, v32, v33
	v_rcp_f32_e32 v167, v167
	v_cvt_pk_bf16_f32 v39, v34, v35
	v_rcp_f32_e32 v168, v168
	global_store_dwordx4 v[206:207], v[52:55], off
	v_rcp_f32_e32 v169, v169
	global_store_dwordx4 v[208:209], v[36:39], off
	v_rcp_f32_e32 v170, v170
	v_rcp_f32_e32 v171, v171
	v_rcp_f32_e32 v172, v172
	v_rcp_f32_e32 v173, v173
	v_rcp_f32_e32 v174, v174
	v_rcp_f32_e32 v175, v175
	v_pk_mul_f32 v[28:29], v[28:29], v[160:161]
	v_pk_mul_f32 v[30:31], v[30:31], v[162:163]
	v_pk_mul_f32 v[20:21], v[20:21], v[164:165]
	v_pk_mul_f32 v[22:23], v[22:23], v[166:167]
	v_pk_mul_f32 v[12:13], v[12:13], v[168:169]
	v_pk_mul_f32 v[14:15], v[14:15], v[170:171]
	v_pk_mul_f32 v[4:5], v[4:5], v[172:173]
	v_pk_mul_f32 v[6:7], v[6:7], v[174:175]
	v_pk_mul_f32 v[24:25], v[28:29], v[24:25]
	v_pk_mul_f32 v[26:27], v[30:31], v[26:27]
	v_pk_mul_f32 v[16:17], v[20:21], v[16:17]
	v_pk_mul_f32 v[18:19], v[22:23], v[18:19]
	v_pk_mul_f32 v[8:9], v[12:13], v[8:9]
	v_pk_mul_f32 v[10:11], v[14:15], v[10:11]
	v_pk_mul_f32 v[0:1], v[4:5], v[0:1]
	v_pk_mul_f32 v[2:3], v[6:7], v[2:3]
	v_cvt_pk_bf16_f32 v20, v24, v25
	v_cvt_pk_bf16_f32 v21, v26, v27
	v_cvt_pk_bf16_f32 v22, v16, v17
	v_cvt_pk_bf16_f32 v23, v18, v19
	v_cvt_pk_bf16_f32 v4, v8, v9
	v_cvt_pk_bf16_f32 v5, v10, v11
	v_cvt_pk_bf16_f32 v6, v0, v1
	v_cvt_pk_bf16_f32 v7, v2, v3
	global_store_dwordx4 v[210:211], v[20:23], off
	global_store_dwordx4 v[212:213], v[4:7], off
	s_andn2_b64 vcc, exec, s[0:1]
	s_mov_b64 s[0:1], -1
	s_cbranch_vccnz .LBB0_1142
	s_andn2_b64 vcc, exec, s[8:9]
	s_cbranch_vccnz .LBB0_1141
	s_barrier
	s_branch .LBB0_1141

; DI unsigned pk2(float lo, float hi) { f32x2_t v = {lo, hi}; bf16x2_t b = __builtin_convertvector(v, bf16x2_t); return __builtin_bit_cast(unsigned, b); }
; DI float bflo(unsigned u) { return __uint_as_float(u << 16); }
; template <int NR, bool XIN_BF, bool XOUT_BF> DI void resid_rows(const void* xin_, void* xout_, const bf16* d, const float* rsq, float coef, const float* pg, const float* ng, bf16* xn, int m0, int mstride, int lane, float* rs_out = nullptr) {
;     f32x4 xv[NR][4]; u32x2 dv[NR][4]; float ss[NR];
; #pragma unroll
;     for (int r = 0; r < NR; ++r) { const size_t m = (size_t)(m0 + r * mstride);
;         ss[r] = lane < 16 ? rsq[m * 16 + lane] : 0.f;
; #pragma unroll
;         for (int j = 0; j < 4; ++j) { const int c = 4 * lane + 256 * j;
;             if (XIN_BF) { const u32x2 t = __builtin_nontemporal_load((const u32x2*)((const bf16*)xin_ + m * DM + c)); xv[r][j] = (f32x4){bflo(t.x), bfhi(t.x), bflo(t.y), bfhi(t.y)}; }
;             else xv[r][j] = __builtin_nontemporal_load((const f32x4*)((const float*)xin_ + m * DM + c));
;             dv[r][j] = __builtin_nontemporal_load((const u32x2*)(d + m * DM + c)); } }
; #pragma unroll
;     for (int r = 0; r < NR; ++r) { const size_t m = (size_t)(m0 + r * mstride);
;         const float rr = rsqrtf(wave_sum(ss[r]) * (1.f / 1024.f) + EPS) * coef; float s2 = 0.f;
; #pragma unroll
;         for (int j = 0; j < 4; ++j) { const int c = 4 * lane + 256 * j; const f32x4 gg = *(const f32x4*)(pg + c);
;             const f32x4 df = {bflo(dv[r][j].x), bfhi(dv[r][j].x), bflo(dv[r][j].y), bfhi(dv[r][j].y)};
;             xv[r][j] = xv[r][j] + df * rr * gg;
;             if (XOUT_BF) { u32x2 w; w.x = pk2(xv[r][j][0], xv[r][j][1]); w.y = pk2(xv[r][j][2], xv[r][j][3]); *(u32x2*)((bf16*)xout_ + m * DM + c) = w; }
;             else __builtin_nontemporal_store(xv[r][j], (f32x4*)((float*)xout_ + m * DM + c));
;             s2 += (xv[r][j][0] * xv[r][j][0] + xv[r][j][1] * xv[r][j][1]) + (xv[r][j][2] * xv[r][j][2] + xv[r][j][3] * xv[r][j][3]); }
;         if (rs_out) { const float r2 = rsqrtf(wave_sum(s2) * (1.f / 1024.f) + EPS); if (lane == 0) rs_out[m] = r2; }
; __global__ void __launch_bounds__(512, 2) mk_fwd(Args a) {
;     ...
;         for (int m = gw; m < M; m += 4 * NGW) resid_rows<4, true, false>(GB, a.out, Q, ROWSQ, 0.5f, (const float*)a.in[24], nullptr, nullptr, m, NGW, lane);
.LBB0_1312:
	s_cmp_lt_i32 s66, 14
	s_cselect_b64 s[2:3], -1, 0
	s_and_b64 s[0:1], s[2:3], s[0:1]
	s_andn2_b64 vcc, exec, s[0:1]
	s_cbranch_vccnz .LBB0_1324
	s_cmpk_gt_i32 s58, 0x7fff
	s_cbranch_scc1 .LBB0_1324
	v_mbcnt_lo_u32_b32 v4, -1, 0
	v_mbcnt_hi_u32_b32 v4, -1, v4
	s_waitcnt lgkmcnt(0)
	v_and_b32_e32 v5, 64, v4
	v_add_u32_e32 v5, 64, v5
	v_xor_b32_e32 v6, 1, v4
	v_cmp_lt_i32_e32 vcc, v6, v5
	s_ashr_i32 s59, s58, 31
	v_lshlrev_b32_e32 v10, 2, v196
	v_cndmask_b32_e32 v6, v4, v6, vcc
	v_lshlrev_b32_e32 v80, 2, v6
	v_xor_b32_e32 v6, 2, v4
	v_cmp_lt_i32_e32 vcc, v6, v5
	v_mov_b32_e32 v11, 0
	s_lshl_b32 s2, s70, 5
	v_cndmask_b32_e32 v6, v4, v6, vcc
	v_lshlrev_b32_e32 v81, 2, v6
	v_xor_b32_e32 v6, 4, v4
	v_cmp_lt_i32_e32 vcc, v6, v5
	s_lshl_b64 s[4:5], s[58:59], 6
	v_lshl_add_u64 v[0:1], s[78:79], 0, v[10:11]
	v_cndmask_b32_e32 v6, v4, v6, vcc
	v_lshlrev_b32_e32 v82, 2, v6
	v_xor_b32_e32 v6, 8, v4
	v_cmp_lt_i32_e32 vcc, v6, v5
	v_mov_b32_e32 v13, v11
	v_mov_b32_e32 v15, v11
	v_cndmask_b32_e32 v6, v4, v6, vcc
	v_lshlrev_b32_e32 v83, 2, v6
	v_xor_b32_e32 v6, 16, v4
	v_cmp_lt_i32_e32 vcc, v6, v5
	v_lshl_add_u64 v[10:11], s[4:5], 0, v[10:11]
	s_mov_b64 s[4:5], 0x28a0000
	s_ashr_i32 s3, s2, 31
	v_cndmask_b32_e32 v6, v4, v6, vcc
	v_lshl_add_u64 v[10:11], v[10:11], 0, s[4:5]
	s_lshl_b64 s[4:5], s[2:3], 6
	s_lshl_b64 s[6:7], s[58:59], 12
	v_lshlrev_b32_e32 v84, 2, v6
	v_xor_b32_e32 v6, 32, v4
	s_add_u32 s6, s62, s6
	v_lshlrev_b32_e32 v12, 4, v196
	v_cmp_lt_i32_e32 vcc, v6, v5
	s_addc_u32 s7, s63, s7
	v_lshl_add_u64 v[2:3], s[60:61], 0, v[12:13]
	v_cndmask_b32_e32 v4, v4, v6, vcc
	v_lshlrev_b32_e32 v14, 3, v196
	v_lshl_add_u64 v[8:9], s[62:63], 0, v[12:13]
	v_lshl_add_u64 v[12:13], s[6:7], 0, v[12:13]
	s_mov_b64 s[6:7], 0xc00
	s_lshl_b64 s[8:9], s[58:59], 11
	v_cmp_gt_u32_e64 s[0:1], 16, v196
	v_lshlrev_b32_e32 v85, 2, v4
	v_lshl_add_u64 v[4:5], s[80:81], 0, v[14:15]
	v_lshl_add_u64 v[6:7], s[84:85], 0, v[14:15]
	v_lshl_add_u64 v[12:13], v[12:13], 0, s[6:7]
	s_lshl_b64 s[6:7], s[2:3], 12
	v_or_b32_e32 v14, s8, v14
	v_mov_b32_e32 v15, s9
	s_lshl_b64 s[8:9], s[2:3], 11
	s_lshl_b32 s3, s70, 4
	s_mul_i32 s11, s70, 24
	s_mov_b32 s10, 0x3a800000
	s_mov_b32 s12, 0x358637bd
	s_mov_b32 s13, 0x800000
	global_load_dwordx4 v[200:203], v[2:3], off
	global_load_dwordx4 v[204:207], v[2:3], off offset:1024
	global_load_dwordx4 v[208:211], v[2:3], off offset:2048
	global_load_dwordx4 v[212:215], v[2:3], off offset:3072
	s_waitcnt vmcnt(0)
	s_branch .LBB0_1316
.LBB0_1315:
	s_or_b64 exec, exec, s[20:21]
	s_nop 1
	v_mov_b64_e32 v[86:87], v[200:201]
	v_mov_b64_e32 v[88:89], v[202:203]
	s_waitcnt vmcnt(0)
	ds_bpermute_b32 v35, v80, v21
	ds_bpermute_b32 v34, v80, v20
	v_lshlrev_b32_e32 v90, 16, v32
	v_and_b32_e32 v91, 0xffff0000, v32
	v_lshlrev_b32_e32 v92, 16, v33
	v_and_b32_e32 v93, 0xffff0000, v33
	s_waitcnt lgkmcnt(0)
	v_pk_add_f32 v[20:21], v[20:21], v[34:35]
	ds_bpermute_b32 v35, v81, v21
	ds_bpermute_b32 v34, v81, v20
	s_lshl_b64 s[20:21], s[14:15], 11
	v_lshlrev_b32_e32 v94, 16, v22
	v_and_b32_e32 v95, 0xffff0000, v22
	v_lshlrev_b32_e32 v96, 16, v23
	s_waitcnt lgkmcnt(0)
	v_pk_add_f32 v[20:21], v[20:21], v[34:35]
	ds_bpermute_b32 v35, v82, v21
	ds_bpermute_b32 v34, v82, v20
	v_and_b32_e32 v97, 0xffff0000, v23
	v_lshl_add_u64 v[22:23], v[4:5], 0, s[20:21]
	v_mov_b64_e32 v[70:71], s[12:13]
	v_lshl_add_u64 v[98:99], v[6:7], 0, s[20:21]
	s_waitcnt lgkmcnt(0)
	v_pk_add_f32 v[20:21], v[20:21], v[34:35]
	ds_bpermute_b32 v33, v83, v21
	ds_bpermute_b32 v32, v83, v20
	s_lshl_b64 s[18:19], s[18:19], 12
	s_lshl_b64 s[16:17], s[16:17], 12
	s_lshl_b64 s[14:15], s[14:15], 12
	s_add_i32 s58, s58, s2
	s_waitcnt lgkmcnt(0)
	v_pk_add_f32 v[20:21], v[20:21], v[32:33]
	ds_bpermute_b32 v33, v84, v21
	ds_bpermute_b32 v32, v84, v20
	v_lshl_add_u64 v[10:11], v[10:11], 0, s[4:5]
	s_cmp_lt_i32 s58, 0x8000
	v_lshl_add_u64 v[14:15], v[14:15], 0, s[8:9]
	s_waitcnt lgkmcnt(0)
	v_pk_add_f32 v[34:35], v[20:21], v[32:33]
	ds_bpermute_b32 v45, v85, v35
	ds_bpermute_b32 v44, v85, v34
	global_load_dwordx2 v[46:47], v[22:23], off nt
	global_load_dwordx2 v[40:41], v[22:23], off offset:512 nt
	global_load_dwordx2 v[32:33], v[22:23], off offset:1024 nt
	global_load_dwordx2 v[20:21], v[22:23], off offset:1536 nt
	s_waitcnt lgkmcnt(0)
; DI float bflo(unsigned u) { return __uint_as_float(u << 16); }
; template <int NR, bool XIN_BF, bool XOUT_BF> DI void resid_rows(const void* xin_, void* xout_, const bf16* d, const float* rsq, float coef, const float* pg, const float* ng, bf16* xn, int m0, int mstride, int lane, float* rs_out = nullptr) {
;     f32x4 xv[NR][4]; u32x2 dv[NR][4]; float ss[NR];
; #pragma unroll
;     for (int r = 0; r < NR; ++r) { const size_t m = (size_t)(m0 + r * mstride);
;         ss[r] = lane < 16 ? rsq[m * 16 + lane] : 0.f;
; #pragma unroll
;         for (int j = 0; j < 4; ++j) { const int c = 4 * lane + 256 * j;
;             if (XIN_BF) { const u32x2 t = __builtin_nontemporal_load((const u32x2*)((const bf16*)xin_ + m * DM + c)); xv[r][j] = (f32x4){bflo(t.x), bfhi(t.x), bflo(t.y), bfhi(t.y)}; }
;             else xv[r][j] = __builtin_nontemporal_load((const f32x4*)((const float*)xin_ + m * DM + c));
;             dv[r][j] = __builtin_nontemporal_load((const u32x2*)(d + m * DM + c)); } }
; #pragma unroll
;     for (int r = 0; r < NR; ++r) { const size_t m = (size_t)(m0 + r * mstride);
;         const float rr = rsqrtf(wave_sum(ss[r]) * (1.f / 1024.f) + EPS) * coef; float s2 = 0.f;
; #pragma unroll
;         for (int j = 0; j < 4; ++j) { const int c = 4 * lane + 256 * j; const f32x4 gg = *(const f32x4*)(pg + c);
;             const f32x4 df = {bflo(dv[r][j].x), bfhi(dv[r][j].x), bflo(dv[r][j].y), bfhi(dv[r][j].y)};
;             xv[r][j] = xv[r][j] + df * rr * gg;
;             if (XOUT_BF) { u32x2 w; w.x = pk2(xv[r][j][0], xv[r][j][1]); w.y = pk2(xv[r][j][2], xv[r][j][3]); *(u32x2*)((bf16*)xout_ + m * DM + c) = w; }
;             else __builtin_nontemporal_store(xv[r][j], (f32x4*)((float*)xout_ + m * DM + c));
;             s2 += (xv[r][j][0] * xv[r][j][0] + xv[r][j][1] * xv[r][j][1]) + (xv[r][j][2] * xv[r][j][2] + xv[r][j][3] * xv[r][j][3]); }
;         if (rs_out) { const float r2 = rsqrtf(wave_sum(s2) * (1.f / 1024.f) + EPS); if (lane == 0) rs_out[m] = r2; }
;         if (xn) {
;             const float r2 = rsqrtf(wave_sum(s2) * (1.f / 1024.f) + EPS);
; #pragma unroll
;             for (int j = 0; j < 4; ++j) { const int c = 4 * lane + 256 * j; const f32x4 gg = *(const f32x4*)(ng + c); const f32x4 o = xv[r][j] * r2 * gg;
;                 u32x2 w; w.x = pk2(o[0], o[1]); w.y = pk2(o[2], o[3]); *(u32x2*)(xn + m * DM + c) = w; }
;         }
;     }
	v_pk_add_f32 v[22:23], v[34:35], v[44:45]
	s_nop 0
	v_pk_fma_f32 v[100:101], v[22:23], s[10:11], v[70:71] op_sel_hi:[1,0,0]
	s_nop 0
	v_mul_f32_e32 v22, 0x4b800000, v101
	v_cmp_gt_f32_e32 vcc, s13, v101
	s_nop 1
	v_cndmask_b32_e32 v22, v101, v22, vcc
	v_rsq_f32_e32 v101, v22
	global_load_dwordx2 v[48:49], v[98:99], off nt
	global_load_dwordx2 v[44:45], v[98:99], off offset:512 nt
	global_load_dwordx2 v[34:35], v[98:99], off offset:1024 nt
	global_load_dwordx2 v[22:23], v[98:99], off offset:1536 nt
	v_mul_f32_e32 v98, 0x45800000, v101
	v_cndmask_b32_e32 v98, v101, v98, vcc
	v_mul_f32_e32 v98, 0.5, v98
	v_pk_mul_f32 v[94:95], v[98:99], v[94:95] op_sel_hi:[0,1]
	v_pk_mul_f32 v[96:97], v[98:99], v[96:97] op_sel_hi:[0,1]
	v_cmp_gt_f32_e32 vcc, s13, v100
	v_pk_fma_f32 v[88:89], v[88:89], v[96:97], v[92:93]
	v_pk_fma_f32 v[86:87], v[86:87], v[94:95], v[90:91]
	global_store_dwordx4 v[12:13], v[86:89], off offset:-3072 nt
	s_nop 1
	v_mov_b64_e32 v[86:87], v[204:205]
	v_mov_b64_e32 v[88:89], v[206:207]
	v_lshlrev_b32_e32 v90, 16, v76
	v_and_b32_e32 v91, 0xffff0000, v76
	v_lshlrev_b32_e32 v92, 16, v77
	v_and_b32_e32 v93, 0xffff0000, v77
	v_lshlrev_b32_e32 v76, 16, v78
	v_and_b32_e32 v77, 0xffff0000, v78
	v_lshlrev_b32_e32 v78, 16, v79
	v_and_b32_e32 v79, 0xffff0000, v79
	v_pk_mul_f32 v[78:79], v[98:99], v[78:79] op_sel_hi:[0,1]
	v_pk_mul_f32 v[76:77], v[98:99], v[76:77] op_sel_hi:[0,1]
	s_nop 1
	v_pk_fma_f32 v[76:77], v[86:87], v[76:77], v[90:91]
	v_pk_fma_f32 v[78:79], v[88:89], v[78:79], v[92:93]
	global_store_dwordx4 v[12:13], v[76:79], off offset:-2048 nt
	s_nop 1
	v_mov_b64_e32 v[76:77], v[208:209]
	v_mov_b64_e32 v[78:79], v[210:211]
	v_lshlrev_b32_e32 v86, 16, v72
	v_and_b32_e32 v87, 0xffff0000, v72
	v_lshlrev_b32_e32 v88, 16, v73
	v_and_b32_e32 v89, 0xffff0000, v73
	v_lshlrev_b32_e32 v72, 16, v74
	v_and_b32_e32 v73, 0xffff0000, v74
	v_lshlrev_b32_e32 v74, 16, v75
	v_and_b32_e32 v75, 0xffff0000, v75
	v_pk_mul_f32 v[74:75], v[98:99], v[74:75] op_sel_hi:[0,1]
	v_pk_mul_f32 v[72:73], v[98:99], v[72:73] op_sel_hi:[0,1]
	s_nop 1
	v_pk_fma_f32 v[72:73], v[76:77], v[72:73], v[86:87]
	v_pk_fma_f32 v[74:75], v[78:79], v[74:75], v[88:89]
	global_store_dwordx4 v[12:13], v[72:75], off offset:-1024 nt
	s_nop 1
	v_mov_b64_e32 v[72:73], v[212:213]
	v_mov_b64_e32 v[74:75], v[214:215]
	v_lshlrev_b32_e32 v76, 16, v66
	v_and_b32_e32 v77, 0xffff0000, v66
	v_lshlrev_b32_e32 v78, 16, v67
	v_and_b32_e32 v79, 0xffff0000, v67
	v_lshlrev_b32_e32 v66, 16, v68
	v_and_b32_e32 v67, 0xffff0000, v68
	v_lshlrev_b32_e32 v68, 16, v69
	v_and_b32_e32 v69, 0xffff0000, v69
	v_pk_mul_f32 v[68:69], v[98:99], v[68:69] op_sel_hi:[0,1]
	v_pk_mul_f32 v[66:67], v[98:99], v[66:67] op_sel_hi:[0,1]
	s_nop 1
	v_pk_fma_f32 v[66:67], v[72:73], v[66:67], v[76:77]
	v_pk_fma_f32 v[68:69], v[74:75], v[68:69], v[78:79]
	global_store_dwordx4 v[12:13], v[66:69], off nt
	s_nop 1
	v_mov_b64_e32 v[66:67], v[200:201]
	v_mov_b64_e32 v[68:69], v[202:203]
	v_lshlrev_b32_e32 v74, 16, v62
	v_and_b32_e32 v75, 0xffff0000, v62
	v_mul_f32_e32 v62, 0x4b800000, v100
	v_cndmask_b32_e32 v62, v100, v62, vcc
	v_rsq_f32_e32 v78, v62
	v_lshlrev_b32_e32 v62, 16, v63
	v_and_b32_e32 v63, 0xffff0000, v63
	v_lshlrev_b32_e32 v72, 16, v64
	v_mul_f32_e32 v79, 0x45800000, v78
	v_cndmask_b32_e32 v78, v78, v79, vcc
	v_mul_f32_e32 v78, 0.5, v78
	v_and_b32_e32 v73, 0xffff0000, v64
	v_lshlrev_b32_e32 v64, 16, v65
	v_and_b32_e32 v65, 0xffff0000, v65
	v_pk_mul_f32 v[86:87], v[78:79], v[62:63] op_sel_hi:[0,1]
	v_pk_mul_f32 v[62:63], v[78:79], v[74:75] op_sel_hi:[0,1]
	v_lshl_add_u64 v[76:77], v[8:9], 0, s[18:19]
	v_lshl_add_u64 v[12:13], v[12:13], 0, s[6:7]
	s_nop 1
	v_pk_fma_f32 v[62:63], v[66:67], v[62:63], v[72:73]
	v_pk_fma_f32 v[64:65], v[68:69], v[86:87], v[64:65]
	global_store_dwordx4 v[76:77], v[62:65], off nt
	s_nop 1
	v_mov_b64_e32 v[62:63], v[204:205]
	v_mov_b64_e32 v[64:65], v[206:207]
	v_lshlrev_b32_e32 v66, 16, v58
	v_and_b32_e32 v67, 0xffff0000, v58
	v_lshlrev_b32_e32 v68, 16, v59
	v_and_b32_e32 v69, 0xffff0000, v59
	v_lshlrev_b32_e32 v58, 16, v60
	v_and_b32_e32 v59, 0xffff0000, v60
	v_lshlrev_b32_e32 v60, 16, v61
	v_and_b32_e32 v61, 0xffff0000, v61
	v_pk_mul_f32 v[60:61], v[78:79], v[60:61] op_sel_hi:[0,1]
	v_pk_mul_f32 v[58:59], v[78:79], v[58:59] op_sel_hi:[0,1]
	s_nop 1
	v_pk_fma_f32 v[58:59], v[62:63], v[58:59], v[66:67]
	v_pk_fma_f32 v[60:61], v[64:65], v[60:61], v[68:69]
	global_store_dwordx4 v[76:77], v[58:61], off offset:1024 nt
	s_nop 1
	v_mov_b64_e32 v[58:59], v[208:209]
	v_mov_b64_e32 v[60:61], v[210:211]
	v_lshlrev_b32_e32 v62, 16, v54
	v_and_b32_e32 v63, 0xffff0000, v54
	v_lshlrev_b32_e32 v64, 16, v55
	v_and_b32_e32 v65, 0xffff0000, v55
	v_lshlrev_b32_e32 v54, 16, v56
	v_and_b32_e32 v55, 0xffff0000, v56
	v_lshlrev_b32_e32 v56, 16, v57
	v_and_b32_e32 v57, 0xffff0000, v57
	v_pk_mul_f32 v[56:57], v[78:79], v[56:57] op_sel_hi:[0,1]
	v_pk_mul_f32 v[54:55], v[78:79], v[54:55] op_sel_hi:[0,1]
	s_nop 1
	v_pk_fma_f32 v[54:55], v[58:59], v[54:55], v[62:63]
	v_pk_fma_f32 v[56:57], v[60:61], v[56:57], v[64:65]
	global_store_dwordx4 v[76:77], v[54:57], off offset:2048 nt
	s_nop 1
	v_mov_b64_e32 v[54:55], v[212:213]
	v_mov_b64_e32 v[56:57], v[214:215]
	v_lshlrev_b32_e32 v58, 16, v50
	v_and_b32_e32 v59, 0xffff0000, v50
	v_lshlrev_b32_e32 v60, 16, v51
	v_and_b32_e32 v61, 0xffff0000, v51
	v_lshlrev_b32_e32 v50, 16, v52
	v_and_b32_e32 v51, 0xffff0000, v52
	v_lshlrev_b32_e32 v52, 16, v53
	v_and_b32_e32 v53, 0xffff0000, v53
	v_pk_mul_f32 v[52:53], v[78:79], v[52:53] op_sel_hi:[0,1]
	v_pk_mul_f32 v[50:51], v[78:79], v[50:51] op_sel_hi:[0,1]
	s_nop 1
	v_pk_fma_f32 v[50:51], v[54:55], v[50:51], v[58:59]
	v_pk_fma_f32 v[52:53], v[56:57], v[52:53], v[60:61]
	global_store_dwordx4 v[76:77], v[50:53], off offset:3072 nt
	s_nop 1
	v_mov_b64_e32 v[50:51], v[200:201]
	v_mov_b64_e32 v[52:53], v[202:203]
	ds_bpermute_b32 v55, v80, v37
	ds_bpermute_b32 v54, v80, v36
	v_lshlrev_b32_e32 v58, 16, v38
	v_and_b32_e32 v59, 0xffff0000, v38
	v_lshlrev_b32_e32 v56, 16, v42
	v_and_b32_e32 v57, 0xffff0000, v42
	s_waitcnt lgkmcnt(0)
; DI float bflo(unsigned u) { return __uint_as_float(u << 16); }
; template <int NR, bool XIN_BF, bool XOUT_BF> DI void resid_rows(const void* xin_, void* xout_, const bf16* d, const float* rsq, float coef, const float* pg, const float* ng, bf16* xn, int m0, int mstride, int lane, float* rs_out = nullptr) {
;     f32x4 xv[NR][4]; u32x2 dv[NR][4]; float ss[NR];
; #pragma unroll
;     for (int r = 0; r < NR; ++r) { const size_t m = (size_t)(m0 + r * mstride);
;         ss[r] = lane < 16 ? rsq[m * 16 + lane] : 0.f;
; #pragma unroll
;         for (int j = 0; j < 4; ++j) { const int c = 4 * lane + 256 * j;
;             if (XIN_BF) { const u32x2 t = __builtin_nontemporal_load((const u32x2*)((const bf16*)xin_ + m * DM + c)); xv[r][j] = (f32x4){bflo(t.x), bfhi(t.x), bflo(t.y), bfhi(t.y)}; }
;             else xv[r][j] = __builtin_nontemporal_load((const f32x4*)((const float*)xin_ + m * DM + c));
;             dv[r][j] = __builtin_nontemporal_load((const u32x2*)(d + m * DM + c)); } }
; #pragma unroll
;     for (int r = 0; r < NR; ++r) { const size_t m = (size_t)(m0 + r * mstride);
;         const float rr = rsqrtf(wave_sum(ss[r]) * (1.f / 1024.f) + EPS) * coef; float s2 = 0.f;
; #pragma unroll
;         for (int j = 0; j < 4; ++j) { const int c = 4 * lane + 256 * j; const f32x4 gg = *(const f32x4*)(pg + c);
;             const f32x4 df = {bflo(dv[r][j].x), bfhi(dv[r][j].x), bflo(dv[r][j].y), bfhi(dv[r][j].y)};
;             xv[r][j] = xv[r][j] + df * rr * gg;
;             if (XOUT_BF) { u32x2 w; w.x = pk2(xv[r][j][0], xv[r][j][1]); w.y = pk2(xv[r][j][2], xv[r][j][3]); *(u32x2*)((bf16*)xout_ + m * DM + c) = w; }
;             else __builtin_nontemporal_store(xv[r][j], (f32x4*)((float*)xout_ + m * DM + c));
;             s2 += (xv[r][j][0] * xv[r][j][0] + xv[r][j][1] * xv[r][j][1]) + (xv[r][j][2] * xv[r][j][2] + xv[r][j][3] * xv[r][j][3]); }
;         if (rs_out) { const float r2 = rsqrtf(wave_sum(s2) * (1.f / 1024.f) + EPS); if (lane == 0) rs_out[m] = r2; }
;         if (xn) {
;             const float r2 = rsqrtf(wave_sum(s2) * (1.f / 1024.f) + EPS);
; #pragma unroll
;             for (int j = 0; j < 4; ++j) { const int c = 4 * lane + 256 * j; const f32x4 gg = *(const f32x4*)(ng + c); const f32x4 o = xv[r][j] * r2 * gg;
;                 u32x2 w; w.x = pk2(o[0], o[1]); w.y = pk2(o[2], o[3]); *(u32x2*)(xn + m * DM + c) = w; }
;         }
;     }
	v_pk_add_f32 v[36:37], v[36:37], v[54:55]
	ds_bpermute_b32 v55, v81, v37
	ds_bpermute_b32 v54, v81, v36
	v_lshlrev_b32_e32 v42, 16, v43
	v_and_b32_e32 v43, 0xffff0000, v43
	v_lshl_add_u64 v[60:61], v[8:9], 0, s[16:17]
	s_waitcnt lgkmcnt(0)
	v_pk_add_f32 v[36:37], v[36:37], v[54:55]
	ds_bpermute_b32 v55, v82, v37
	ds_bpermute_b32 v54, v82, v36
	s_waitcnt lgkmcnt(0)
	v_pk_add_f32 v[36:37], v[36:37], v[54:55]
	ds_bpermute_b32 v55, v83, v37
	ds_bpermute_b32 v54, v83, v36
	s_waitcnt lgkmcnt(0)
	v_pk_add_f32 v[36:37], v[36:37], v[54:55]
	ds_bpermute_b32 v55, v84, v37
	ds_bpermute_b32 v54, v84, v36
	s_waitcnt lgkmcnt(0)
	v_pk_add_f32 v[36:37], v[36:37], v[54:55]
	ds_bpermute_b32 v55, v85, v37
	ds_bpermute_b32 v54, v85, v36
	s_waitcnt lgkmcnt(0)
	v_pk_add_f32 v[36:37], v[36:37], v[54:55]
	s_nop 0
	v_pk_fma_f32 v[54:55], v[36:37], s[10:11], v[70:71] op_sel_hi:[1,0,0]
	v_and_b32_e32 v37, 0xffff0000, v39
	v_mul_f32_e32 v36, 0x4b800000, v55
	v_cmp_gt_f32_e32 vcc, s13, v55
	s_nop 1
	v_cndmask_b32_e32 v36, v55, v36, vcc
	v_rsq_f32_e32 v38, v36
	v_lshlrev_b32_e32 v36, 16, v39
	v_mul_f32_e32 v39, 0x45800000, v38
	v_cndmask_b32_e32 v38, v38, v39, vcc
	v_mul_f32_e32 v62, 0.5, v38
	v_pk_mul_f32 v[38:39], v[62:63], v[36:37] op_sel_hi:[0,1]
	v_pk_mul_f32 v[36:37], v[62:63], v[58:59] op_sel_hi:[0,1]
	v_cmp_gt_f32_e32 vcc, s13, v54
	s_nop 1
	v_pk_fma_f32 v[36:37], v[50:51], v[36:37], v[56:57]
	v_pk_fma_f32 v[38:39], v[52:53], v[38:39], v[42:43]
	global_store_dwordx4 v[60:61], v[36:39], off nt
	s_nop 1
	v_mov_b64_e32 v[36:37], v[204:205]
	v_mov_b64_e32 v[38:39], v[206:207]
	v_lshlrev_b32_e32 v42, 16, v28
	v_and_b32_e32 v43, 0xffff0000, v28
	v_lshlrev_b32_e32 v50, 16, v29
	v_and_b32_e32 v51, 0xffff0000, v29
	v_lshlrev_b32_e32 v28, 16, v30
	v_and_b32_e32 v29, 0xffff0000, v30
	v_lshlrev_b32_e32 v30, 16, v31
	v_and_b32_e32 v31, 0xffff0000, v31
	v_pk_mul_f32 v[30:31], v[62:63], v[30:31] op_sel_hi:[0,1]
	v_pk_mul_f32 v[28:29], v[62:63], v[28:29] op_sel_hi:[0,1]
	s_nop 1
	v_pk_fma_f32 v[28:29], v[36:37], v[28:29], v[42:43]
	v_pk_fma_f32 v[30:31], v[38:39], v[30:31], v[50:51]
	global_store_dwordx4 v[60:61], v[28:31], off offset:1024 nt
	s_nop 1
	v_mov_b64_e32 v[28:29], v[208:209]
	v_mov_b64_e32 v[30:31], v[210:211]
	v_lshlrev_b32_e32 v36, 16, v24
	v_and_b32_e32 v37, 0xffff0000, v24
	v_lshlrev_b32_e32 v38, 16, v25
	v_and_b32_e32 v39, 0xffff0000, v25
	v_lshlrev_b32_e32 v24, 16, v26
	v_and_b32_e32 v25, 0xffff0000, v26
	v_lshlrev_b32_e32 v26, 16, v27
	v_and_b32_e32 v27, 0xffff0000, v27
	v_pk_mul_f32 v[26:27], v[62:63], v[26:27] op_sel_hi:[0,1]
	v_pk_mul_f32 v[24:25], v[62:63], v[24:25] op_sel_hi:[0,1]
	s_waitcnt vmcnt(0)
	v_pk_fma_f32 v[24:25], v[28:29], v[24:25], v[36:37]
	v_pk_fma_f32 v[26:27], v[30:31], v[26:27], v[38:39]
	global_store_dwordx4 v[60:61], v[24:27], off offset:2048 nt
	s_nop 1
	v_mov_b64_e32 v[24:25], v[212:213]
	v_mov_b64_e32 v[26:27], v[214:215]
	v_lshlrev_b32_e32 v28, 16, v16
	v_and_b32_e32 v29, 0xffff0000, v16
	v_lshlrev_b32_e32 v30, 16, v17
	v_and_b32_e32 v31, 0xffff0000, v17
	v_lshlrev_b32_e32 v16, 16, v18
	v_and_b32_e32 v17, 0xffff0000, v18
	v_lshlrev_b32_e32 v18, 16, v19
	v_and_b32_e32 v19, 0xffff0000, v19
	v_pk_mul_f32 v[18:19], v[62:63], v[18:19] op_sel_hi:[0,1]
	v_pk_mul_f32 v[16:17], v[62:63], v[16:17] op_sel_hi:[0,1]
	v_lshlrev_b32_e32 v36, 16, v48
	v_and_b32_e32 v37, 0xffff0000, v48
	v_lshlrev_b32_e32 v38, 16, v49
	v_and_b32_e32 v39, 0xffff0000, v49
	s_nop 1
	v_pk_fma_f32 v[16:17], v[24:25], v[16:17], v[28:29]
	v_pk_fma_f32 v[18:19], v[26:27], v[18:19], v[30:31]
	global_store_dwordx4 v[60:61], v[16:19], off offset:3072 nt
	s_nop 1
	v_mov_b64_e32 v[16:17], v[200:201]
	v_mov_b64_e32 v[18:19], v[202:203]
	v_mul_f32_e32 v24, 0x4b800000, v54
	v_cndmask_b32_e32 v24, v54, v24, vcc
	v_rsq_f32_e32 v26, v24
	v_lshlrev_b32_e32 v28, 16, v46
	v_and_b32_e32 v29, 0xffff0000, v46
	v_lshlrev_b32_e32 v30, 16, v47
	v_mul_f32_e32 v27, 0x45800000, v26
	v_cndmask_b32_e32 v26, v26, v27, vcc
	v_mul_f32_e32 v26, 0.5, v26
	v_and_b32_e32 v31, 0xffff0000, v47
	v_pk_mul_f32 v[38:39], v[26:27], v[38:39] op_sel_hi:[0,1]
	v_pk_mul_f32 v[36:37], v[26:27], v[36:37] op_sel_hi:[0,1]
	v_lshl_add_u64 v[24:25], v[8:9], 0, s[14:15]
	s_nop 1
	v_pk_fma_f32 v[16:17], v[16:17], v[36:37], v[28:29]
	v_pk_fma_f32 v[18:19], v[18:19], v[38:39], v[30:31]
	global_store_dwordx4 v[24:25], v[16:19], off nt
	s_nop 1
	v_mov_b64_e32 v[16:17], v[204:205]
	v_mov_b64_e32 v[18:19], v[206:207]
	v_lshlrev_b32_e32 v36, 16, v44
	v_and_b32_e32 v37, 0xffff0000, v44
	v_lshlrev_b32_e32 v38, 16, v45
	v_and_b32_e32 v39, 0xffff0000, v45
	v_lshlrev_b32_e32 v28, 16, v40
	v_and_b32_e32 v29, 0xffff0000, v40
	v_lshlrev_b32_e32 v30, 16, v41
	v_and_b32_e32 v31, 0xffff0000, v41
	v_pk_mul_f32 v[38:39], v[26:27], v[38:39] op_sel_hi:[0,1]
	v_pk_mul_f32 v[36:37], v[26:27], v[36:37] op_sel_hi:[0,1]
	s_nop 1
	v_pk_fma_f32 v[16:17], v[16:17], v[36:37], v[28:29]
	v_pk_fma_f32 v[18:19], v[18:19], v[38:39], v[30:31]
	global_store_dwordx4 v[24:25], v[16:19], off offset:1024 nt
	s_nop 1
	v_mov_b64_e32 v[16:17], v[208:209]
	v_mov_b64_e32 v[18:19], v[210:211]
	v_lshlrev_b32_e32 v28, 16, v32
	v_and_b32_e32 v29, 0xffff0000, v32
	v_lshlrev_b32_e32 v30, 16, v33
	v_and_b32_e32 v31, 0xffff0000, v33
	v_lshlrev_b32_e32 v32, 16, v34
	v_and_b32_e32 v33, 0xffff0000, v34
	v_lshlrev_b32_e32 v34, 16, v35
	v_and_b32_e32 v35, 0xffff0000, v35
	v_pk_mul_f32 v[34:35], v[26:27], v[34:35] op_sel_hi:[0,1]
	v_pk_mul_f32 v[32:33], v[26:27], v[32:33] op_sel_hi:[0,1]
	s_nop 1
	v_pk_fma_f32 v[16:17], v[16:17], v[32:33], v[28:29]
	v_pk_fma_f32 v[18:19], v[18:19], v[34:35], v[30:31]
	global_store_dwordx4 v[24:25], v[16:19], off offset:2048 nt
	s_nop 1
	v_mov_b64_e32 v[16:17], v[212:213]
	v_mov_b64_e32 v[18:19], v[214:215]
	v_lshlrev_b32_e32 v30, 16, v22
	v_and_b32_e32 v31, 0xffff0000, v22
	v_lshlrev_b32_e32 v22, 16, v23
	v_and_b32_e32 v23, 0xffff0000, v23
	v_lshlrev_b32_e32 v28, 16, v20
	v_and_b32_e32 v29, 0xffff0000, v20
	v_lshlrev_b32_e32 v20, 16, v21
	v_and_b32_e32 v21, 0xffff0000, v21
	v_pk_mul_f32 v[22:23], v[26:27], v[22:23] op_sel_hi:[0,1]
	v_pk_mul_f32 v[26:27], v[26:27], v[30:31] op_sel_hi:[0,1]
	s_nop 1
	v_pk_fma_f32 v[16:17], v[16:17], v[26:27], v[28:29]
	v_pk_fma_f32 v[18:19], v[18:19], v[22:23], v[20:21]
	global_store_dwordx4 v[24:25], v[16:19], off offset:3072 nt
	s_cbranch_scc0 .LBB0_1324

; __global__ void __launch_bounds__(512, 2) mk_fwd(Args a) {
	.amdhsa_kernel _Z6mk_fwd4Args
		.amdhsa_group_segment_fixed_size 0
		.amdhsa_private_segment_fixed_size 0
		.amdhsa_kernarg_size 480
		.amdhsa_user_sgpr_count 2
		.amdhsa_user_sgpr_dispatch_ptr 0
		.amdhsa_user_sgpr_queue_ptr 0
		.amdhsa_user_sgpr_kernarg_segment_ptr 1
		.amdhsa_user_sgpr_dispatch_id 0
		.amdhsa_user_sgpr_kernarg_preload_length 0
		.amdhsa_user_sgpr_kernarg_preload_offset 0
		.amdhsa_user_sgpr_private_segment_size 0
		.amdhsa_uses_dynamic_stack 0
		.amdhsa_enable_private_segment 0
		.amdhsa_system_sgpr_workgroup_id_x 1
		.amdhsa_system_sgpr_workgroup_id_y 0
		.amdhsa_system_sgpr_workgroup_id_z 0
		.amdhsa_system_sgpr_workgroup_info 0
		.amdhsa_system_vgpr_workitem_id 2
		.amdhsa_next_free_vgpr 254
		.amdhsa_next_free_sgpr 102
		.amdhsa_accum_offset 256
		.amdhsa_reserve_vcc 1
		.amdhsa_float_round_mode_32 0
		.amdhsa_float_round_mode_16_64 0
		.amdhsa_float_denorm_mode_32 3
		.amdhsa_float_denorm_mode_16_64 3
		.amdhsa_dx10_clamp 1
		.amdhsa_ieee_mode 1
		.amdhsa_fp16_overflow 0
		.amdhsa_tg_split 0
		.amdhsa_exception_fp_ieee_invalid_op 0
		.amdhsa_exception_fp_denorm_src 0
		.amdhsa_exception_fp_ieee_div_zero 0
		.amdhsa_exception_fp_ieee_overflow 0
		.amdhsa_exception_fp_ieee_underflow 0
		.amdhsa_exception_fp_ieee_inexact 0
		.amdhsa_exception_int_div_zero 0
	.end_amdhsa_kernel

; __global__ void __launch_bounds__(512, 2) mk_fwd(Args a) {
amdhsa.kernels:
  - .agpr_count:     0
    .args:
      - .offset:         0
        .size:           224
        .value_kind:     by_value
      - .offset:         224
        .size:           4
        .value_kind:     hidden_block_count_x
      - .offset:         228
        .size:           4
        .value_kind:     hidden_block_count_y
      - .offset:         232
        .size:           4
        .value_kind:     hidden_block_count_z
      - .offset:         236
        .size:           2
        .value_kind:     hidden_group_size_x
      - .offset:         238
        .size:           2
        .value_kind:     hidden_group_size_y
      - .offset:         240
        .size:           2
        .value_kind:     hidden_group_size_z
      - .offset:         242
        .size:           2
        .value_kind:     hidden_remainder_x
      - .offset:         244
        .size:           2
        .value_kind:     hidden_remainder_y
      - .offset:         246
        .size:           2
        .value_kind:     hidden_remainder_z
      - .offset:         264
        .size:           8
        .value_kind:     hidden_global_offset_x
      - .offset:         272
        .size:           8
        .value_kind:     hidden_global_offset_y
      - .offset:         280
        .size:           8
        .value_kind:     hidden_global_offset_z
      - .offset:         288
        .size:           2
        .value_kind:     hidden_grid_dims
      - .offset:         312
        .size:           8
        .value_kind:     hidden_multigrid_sync_arg
      - .offset:         344
        .size:           4
        .value_kind:     hidden_dynamic_lds_size
    .group_segment_fixed_size: 0
    .kernarg_segment_align: 8
    .kernarg_segment_size: 480
    .language:       OpenCL C
    .language_version:
      - 2
      - 0
    .max_flat_workgroup_size: 512
    .name:           _Z6mk_fwd4Args
    .private_segment_fixed_size: 0
    .sgpr_count:     108
    .sgpr_spill_count: 75
    .symbol:         _Z6mk_fwd4Args.kd
    .uniform_work_group_size: 1
    .uses_dynamic_stack: false
    .vgpr_count:     254
    .vgpr_spill_count: 0
    .wavefront_size: 64
